# Hyena FFT loop: v_perm bf16 unpack in plane staging, packed short-conv FMAs, first pass reads gate registers directly
# speedup vs baseline: 1.0028x; 1.0012x over previous
; #define WG_SYNC() do { asm volatile("s_waitcnt lgkmcnt(0)" ::: "memory"); __builtin_amdgcn_s_barrier(); asm volatile("" ::: "memory"); } while (0)
; template <bool INV> __device__ __forceinline__ void dft16(f32x2 (&x)[16]) {
;     constexpr float C1 = 0.92387953251128674f, S1 = 0.38268343236508977f, C2 = 0.70710678118654752f;
; #pragma unroll
;     for (int b = 0; b < 4; ++b) dft4<INV>(x[b], x[4 + b], x[8 + b], x[12 + b]);
; __device__ __forceinline__ void hyena_fft(LAS unsigned char* lds, int layer, int G, const int wave_s) {
;     ...
;         for (int c = c_lo; c < c_hi; ++c) { const int unit = c >> 2, jc = c & 3;
;             WG_SYNC();
;             { f32x2 x[16]; const unsigned* tf = TF + (size_t)c * SEQ; const unsigned* tb = TB + (size_t)c * SEQ;
; #pragma unroll
;               for (int r = 0; r < 8; ++r) { const unsigned w = tf[n2 + 512 * r]; x[r] = (f32x2){bf_lo(w), bf_hi(w)}; }
; #pragma unroll
;               for (int r = 8; r < 16; ++r) { const int l = FN - 512 * r - n2; const unsigned w = l < SEQ ? tb[l] : 0u; x[r] = (f32x2){bf_lo(w), bf_hi(w)}; }
;               __builtin_amdgcn_sched_barrier(0); fft_fwd1<false>(x, Fb, n2, w1p); __builtin_amdgcn_sched_barrier(0); }
.Lhfft_loop:
	s_lshr_b32 s43, s80, 2
	s_mul_i32 s73, s43, 0x11000
	s_and_b32 s43, s80, 2
	s_lshl_b32 s43, s43, 1
	s_add_u32 s73, s73, s43
	s_and_b32 s43, s80, 1
	s_mov_b32 s15, 0x1000c0c
	s_cmp_eq_u32 s43, 0
	s_cselect_b32 s15, s15, 0x3020c0c
	s_lshl_b32 s43, s80, 14
	s_add_u32 s46, s36, s43
	s_addc_u32 s47, s37, 0
	s_add_u32 s50, s46, 0x4000000
	s_addc_u32 s51, s47, 0
	s_waitcnt lgkmcnt(0)
	s_barrier
	s_add_u32 s60, s46, 0
	s_addc_u32 s61, s47, 0
	global_load_dword v176, v212, s[60:61]
	global_load_dword v178, v212, s[60:61] offset:2048
	s_add_u32 s60, s46, 0x1000
	s_addc_u32 s61, s47, 0
	global_load_dword v180, v212, s[60:61]
	global_load_dword v182, v212, s[60:61] offset:2048
	s_add_u32 s60, s46, 0x2000
	s_addc_u32 s61, s47, 0
	global_load_dword v184, v212, s[60:61]
	global_load_dword v186, v212, s[60:61] offset:2048
	s_add_u32 s60, s46, 0x3000
	s_addc_u32 s61, s47, 0
	global_load_dword v188, v212, s[60:61]
	global_load_dword v166, v212, s[60:61] offset:2048
	s_add_u32 s62, s50, 0x3000
	s_addc_u32 s63, s51, 0
	global_load_dword v177, v214, s[62:63] offset:2048
	global_load_dword v179, v214, s[62:63]
	s_add_u32 s62, s50, 0x2000
	s_addc_u32 s63, s51, 0
	global_load_dword v181, v214, s[62:63] offset:2048
	global_load_dword v183, v214, s[62:63]
	s_add_u32 s62, s50, 0x1000
	s_addc_u32 s63, s51, 0
	global_load_dword v185, v214, s[62:63] offset:2048
	global_load_dword v187, v214, s[62:63]
	s_add_u32 s62, s50, 0
	s_addc_u32 s63, s51, 0
	global_load_dword v189, v214, s[62:63] offset:2048
	global_load_dword v167, v214, s[62:63]
	s_add_u32 s56, s38, s73
	s_addc_u32 s57, s39, 0
	s_add_u32 s56, s56, 0x2200000
	s_addc_u32 s57, s57, 0
	global_load_dwordx3 v[58:60], v216, s[56:57]
	global_load_dwordx3 v[62:64], v218, s[56:57]
	global_load_dwordx3 v[66:68], v220, s[56:57]
	global_load_dwordx3 v[70:72], v222, s[56:57]
	global_load_dwordx3 v[74:76], v240, s[56:57]
	global_load_dwordx3 v[78:80], v242, s[56:57]
	global_load_dwordx3 v[82:84], v244, s[56:57]
	global_load_dwordx3 v[86:88], v61, s[56:57]
	s_waitcnt vmcnt(23)
	v_and_b32_e32 v101, 0xffff0000, v176
	v_lshlrev_b32_e32 v100, 16, v176
	s_waitcnt vmcnt(22)
	v_and_b32_e32 v103, 0xffff0000, v178
	v_lshlrev_b32_e32 v102, 16, v178
	s_waitcnt vmcnt(21)
	v_and_b32_e32 v105, 0xffff0000, v180
	v_lshlrev_b32_e32 v104, 16, v180
	s_waitcnt vmcnt(20)
	v_and_b32_e32 v107, 0xffff0000, v182
	v_lshlrev_b32_e32 v106, 16, v182
	s_waitcnt vmcnt(19)
	v_and_b32_e32 v109, 0xffff0000, v184
	v_lshlrev_b32_e32 v108, 16, v184
	s_waitcnt vmcnt(18)
	v_and_b32_e32 v111, 0xffff0000, v186
	v_lshlrev_b32_e32 v110, 16, v186
	s_waitcnt vmcnt(17)
	v_and_b32_e32 v113, 0xffff0000, v188
	v_lshlrev_b32_e32 v112, 16, v188
	s_waitcnt vmcnt(16)
	v_and_b32_e32 v115, 0xffff0000, v166
	v_lshlrev_b32_e32 v114, 16, v166
	s_waitcnt vmcnt(15)
	v_cndmask_b32_e64 v177, v177, 0, s[10:11]
	v_and_b32_e32 v117, 0xffff0000, v177
	v_lshlrev_b32_e32 v116, 16, v177
	s_waitcnt vmcnt(14)
	v_and_b32_e32 v119, 0xffff0000, v179
	v_lshlrev_b32_e32 v118, 16, v179
	s_waitcnt vmcnt(13)
	v_and_b32_e32 v121, 0xffff0000, v181
	v_lshlrev_b32_e32 v120, 16, v181
	s_waitcnt vmcnt(12)
	v_and_b32_e32 v123, 0xffff0000, v183
	v_lshlrev_b32_e32 v122, 16, v183
	s_waitcnt vmcnt(11)
	v_and_b32_e32 v125, 0xffff0000, v185
	v_lshlrev_b32_e32 v124, 16, v185
	s_waitcnt vmcnt(10)
	v_and_b32_e32 v127, 0xffff0000, v187
	v_lshlrev_b32_e32 v126, 16, v187
	s_waitcnt vmcnt(9)
	v_and_b32_e32 v129, 0xffff0000, v189
	v_lshlrev_b32_e32 v128, 16, v189
	s_waitcnt vmcnt(8)
	v_and_b32_e32 v131, 0xffff0000, v167
	v_lshlrev_b32_e32 v130, 16, v167
	v_pk_add_f32 v[168:169], v[100:101], v[116:117]
	v_pk_add_f32 v[174:175], v[100:101], v[116:117] neg_lo:[0,1] neg_hi:[0,1]
	v_pk_add_f32 v[176:177], v[108:109], v[124:125]
	v_pk_add_f32 v[178:179], v[108:109], v[124:125] neg_lo:[0,1] neg_hi:[0,1]
	v_pk_add_f32 v[100:101], v[168:169], v[176:177]
	v_pk_add_f32 v[116:117], v[168:169], v[176:177] neg_lo:[0,1] neg_hi:[0,1]
	v_pk_add_f32 v[108:109], v[174:175], v[178:179] op_sel:[0,1] op_sel_hi:[1,0] neg_hi:[0,1]
	v_pk_add_f32 v[124:125], v[174:175], v[178:179] op_sel:[0,1] op_sel_hi:[1,0] neg_lo:[0,1]
	v_pk_add_f32 v[180:181], v[102:103], v[118:119]
	v_pk_add_f32 v[182:183], v[102:103], v[118:119] neg_lo:[0,1] neg_hi:[0,1]
	v_pk_add_f32 v[184:185], v[110:111], v[126:127]
	v_pk_add_f32 v[186:187], v[110:111], v[126:127] neg_lo:[0,1] neg_hi:[0,1]
	v_pk_add_f32 v[102:103], v[180:181], v[184:185]
	v_pk_add_f32 v[118:119], v[180:181], v[184:185] neg_lo:[0,1] neg_hi:[0,1]
	v_pk_add_f32 v[110:111], v[182:183], v[186:187] op_sel:[0,1] op_sel_hi:[1,0] neg_hi:[0,1]
	v_pk_add_f32 v[126:127], v[182:183], v[186:187] op_sel:[0,1] op_sel_hi:[1,0] neg_lo:[0,1]
	v_pk_add_f32 v[188:189], v[104:105], v[120:121]
	v_pk_add_f32 v[166:167], v[104:105], v[120:121] neg_lo:[0,1] neg_hi:[0,1]
	v_pk_add_f32 v[168:169], v[112:113], v[128:129]
	v_pk_add_f32 v[174:175], v[112:113], v[128:129] neg_lo:[0,1] neg_hi:[0,1]
	v_pk_add_f32 v[104:105], v[188:189], v[168:169]
	v_pk_add_f32 v[120:121], v[188:189], v[168:169] neg_lo:[0,1] neg_hi:[0,1]
	v_pk_add_f32 v[112:113], v[166:167], v[174:175] op_sel:[0,1] op_sel_hi:[1,0] neg_hi:[0,1]
	v_pk_add_f32 v[128:129], v[166:167], v[174:175] op_sel:[0,1] op_sel_hi:[1,0] neg_lo:[0,1]
	v_pk_add_f32 v[176:177], v[106:107], v[122:123]
	v_pk_add_f32 v[178:179], v[106:107], v[122:123] neg_lo:[0,1] neg_hi:[0,1]
	v_pk_add_f32 v[180:181], v[114:115], v[130:131]
	v_pk_add_f32 v[182:183], v[114:115], v[130:131] neg_lo:[0,1] neg_hi:[0,1]
	v_pk_add_f32 v[106:107], v[176:177], v[180:181]
	v_pk_add_f32 v[122:123], v[176:177], v[180:181] neg_lo:[0,1] neg_hi:[0,1]
	v_pk_add_f32 v[114:115], v[178:179], v[182:183] op_sel:[0,1] op_sel_hi:[1,0] neg_hi:[0,1]
; #define LAS __attribute__((address_space(3)))
; __device__ __forceinline__ f32x2 cmul(f32x2 a, f32x2 b) { return (f32x2){a.x * b.x - a.y * b.y, a.x * b.y + a.y * b.x}; }
; template <bool INV> __device__ __forceinline__ f32x2 cmul_tw(f32x2 a, f32x2 w) { return INV ? cmulc(a, w) : cmul(a, w); }
; template <bool INV> __device__ __forceinline__ void dft16(f32x2 (&x)[16]) {
;     ...
;     const f32x2 w1 = {C1, -S1}, w2 = {C2, -C2}, w3 = {S1, -C1}, w4 = {0.f, -1.f}, w6 = {-C2, -C2}, w9 = {-C1, S1};
;     x[4 * 1 + 1] = cmul_tw<INV>(x[5], w1); x[4 * 1 + 2] = cmul_tw<INV>(x[6], w2); x[4 * 1 + 3] = cmul_tw<INV>(x[7], w3);
;     x[4 * 2 + 1] = cmul_tw<INV>(x[9], w2); x[4 * 2 + 2] = cmul_tw<INV>(x[10], w4); x[4 * 2 + 3] = cmul_tw<INV>(x[11], w6);
;     x[4 * 3 + 1] = cmul_tw<INV>(x[13], w3); x[4 * 3 + 2] = cmul_tw<INV>(x[14], w6); x[4 * 3 + 3] = cmul_tw<INV>(x[15], w9);
; #pragma unroll
;     for (int c = 0; c < 4; ++c) dft4<INV>(x[4 * c], x[4 * c + 1], x[4 * c + 2], x[4 * c + 3]);
;     f32x2 y[16];
; #pragma unroll
;     for (int k = 0; k < 16; ++k) y[k] = x[4 * (k & 3) + (k >> 2)];
; #pragma unroll
;     for (int k = 0; k < 16; ++k) x[k] = y[k];
; template <bool LO> __device__ __forceinline__ void fft_fwd1(f32x2 (&x)[16], LAS f32x2* B, int n2, const f32x2 (&w)[16]) {
;     asm volatile("" : "+v"(n2));
;     if (LO) dft16_fwd_lo(x); else dft16<false>(x);
;     B[fpad(n2)] = x[0];
; #pragma unroll
;     for (int k = 1; k < 16; ++k) B[fpad(512 * k + n2)] = cmul(x[k], w[k]);
; }
	v_pk_add_f32 v[130:131], v[178:179], v[182:183] op_sel:[0,1] op_sel_hi:[1,0] neg_lo:[0,1]
	v_pk_mul_f32 v[184:185], v[110:111], s[68:69] op_sel:[1,1] op_sel_hi:[0,1]
	v_pk_fma_f32 v[110:111], v[110:111], s[68:69], v[184:185] op_sel_hi:[1,0,1] neg_lo:[0,0,1]
	v_pk_mul_f32 v[186:187], v[112:113], s[84:85] op_sel:[1,1] op_sel_hi:[0,1]
	v_pk_fma_f32 v[112:113], v[112:113], s[84:85], v[186:187] op_sel_hi:[1,0,1] neg_lo:[0,0,1]
	v_pk_mul_f32 v[188:189], v[114:115], s[88:89] op_sel:[1,1] op_sel_hi:[0,1]
	v_pk_fma_f32 v[114:115], v[114:115], s[88:89], v[188:189] op_sel_hi:[1,0,1] neg_lo:[0,0,1]
	v_pk_mul_f32 v[166:167], v[118:119], s[84:85] op_sel:[1,1] op_sel_hi:[0,1]
	v_pk_fma_f32 v[118:119], v[118:119], s[84:85], v[166:167] op_sel_hi:[1,0,1] neg_lo:[0,0,1]
	v_pk_mul_f32 v[168:169], v[122:123], s[90:91] op_sel:[1,1] op_sel_hi:[0,1]
	v_pk_fma_f32 v[122:123], v[122:123], s[90:91], v[168:169] op_sel_hi:[1,0,1] neg_lo:[0,0,1]
	v_pk_mul_f32 v[174:175], v[126:127], s[88:89] op_sel:[1,1] op_sel_hi:[0,1]
	v_pk_fma_f32 v[126:127], v[126:127], s[88:89], v[174:175] op_sel_hi:[1,0,1] neg_lo:[0,0,1]
	v_pk_mul_f32 v[176:177], v[128:129], s[90:91] op_sel:[1,1] op_sel_hi:[0,1]
	v_pk_fma_f32 v[128:129], v[128:129], s[90:91], v[176:177] op_sel_hi:[1,0,1] neg_lo:[0,0,1]
	v_pk_mul_f32 v[178:179], v[130:131], s[98:99] op_sel:[1,1] op_sel_hi:[0,1]
	v_pk_fma_f32 v[130:131], v[130:131], s[98:99], v[178:179] op_sel_hi:[1,0,1] neg_lo:[0,0,1]
	v_pk_add_f32 v[180:181], v[100:101], v[104:105]
	v_pk_add_f32 v[182:183], v[100:101], v[104:105] neg_lo:[0,1] neg_hi:[0,1]
	v_pk_add_f32 v[184:185], v[102:103], v[106:107]
	v_pk_add_f32 v[186:187], v[102:103], v[106:107] neg_lo:[0,1] neg_hi:[0,1]
	v_pk_add_f32 v[100:101], v[180:181], v[184:185]
	v_pk_add_f32 v[104:105], v[180:181], v[184:185] neg_lo:[0,1] neg_hi:[0,1]
	v_pk_add_f32 v[102:103], v[182:183], v[186:187] op_sel:[0,1] op_sel_hi:[1,0] neg_hi:[0,1]
	v_pk_add_f32 v[106:107], v[182:183], v[186:187] op_sel:[0,1] op_sel_hi:[1,0] neg_lo:[0,1]
	v_pk_add_f32 v[188:189], v[108:109], v[112:113]
	v_pk_add_f32 v[166:167], v[108:109], v[112:113] neg_lo:[0,1] neg_hi:[0,1]
	v_pk_add_f32 v[168:169], v[110:111], v[114:115]
	v_pk_add_f32 v[174:175], v[110:111], v[114:115] neg_lo:[0,1] neg_hi:[0,1]
	v_pk_add_f32 v[108:109], v[188:189], v[168:169]
	v_pk_add_f32 v[112:113], v[188:189], v[168:169] neg_lo:[0,1] neg_hi:[0,1]
	v_pk_add_f32 v[110:111], v[166:167], v[174:175] op_sel:[0,1] op_sel_hi:[1,0] neg_hi:[0,1]
	v_pk_add_f32 v[114:115], v[166:167], v[174:175] op_sel:[0,1] op_sel_hi:[1,0] neg_lo:[0,1]
	v_pk_add_f32 v[176:177], v[116:117], v[120:121] op_sel:[0,1] op_sel_hi:[1,0] neg_hi:[0,1]
	v_pk_add_f32 v[178:179], v[116:117], v[120:121] op_sel:[0,1] op_sel_hi:[1,0] neg_lo:[0,1]
	v_pk_add_f32 v[180:181], v[118:119], v[122:123]
	v_pk_add_f32 v[182:183], v[118:119], v[122:123] neg_lo:[0,1] neg_hi:[0,1]
	v_pk_add_f32 v[116:117], v[176:177], v[180:181]
	v_pk_add_f32 v[120:121], v[176:177], v[180:181] neg_lo:[0,1] neg_hi:[0,1]
	v_pk_add_f32 v[118:119], v[178:179], v[182:183] op_sel:[0,1] op_sel_hi:[1,0] neg_hi:[0,1]
	v_pk_add_f32 v[122:123], v[178:179], v[182:183] op_sel:[0,1] op_sel_hi:[1,0] neg_lo:[0,1]
	v_pk_add_f32 v[184:185], v[124:125], v[128:129]
	v_pk_add_f32 v[186:187], v[124:125], v[128:129] neg_lo:[0,1] neg_hi:[0,1]
	v_pk_add_f32 v[188:189], v[126:127], v[130:131]
	v_pk_add_f32 v[166:167], v[126:127], v[130:131] neg_lo:[0,1] neg_hi:[0,1]
	v_pk_add_f32 v[124:125], v[184:185], v[188:189]
	v_pk_add_f32 v[128:129], v[184:185], v[188:189] neg_lo:[0,1] neg_hi:[0,1]
	v_pk_add_f32 v[126:127], v[186:187], v[166:167] op_sel:[0,1] op_sel_hi:[1,0] neg_hi:[0,1]
	v_pk_add_f32 v[130:131], v[186:187], v[166:167] op_sel:[0,1] op_sel_hi:[1,0] neg_lo:[0,1]
	v_add_u32_e32 v65, 0x10800, v3
	ds_write_b64 v65, v[100:101]
	v_pk_mul_f32 v[174:175], v[108:109], v[6:7] op_sel:[1,1] op_sel_hi:[0,1]
	v_pk_fma_f32 v[168:169], v[108:109], v[6:7], v[174:175] op_sel_hi:[1,0,1] neg_lo:[0,0,1]
	ds_write_b64 v65, v[168:169] offset:4224
	v_pk_mul_f32 v[178:179], v[116:117], v[8:9] op_sel:[1,1] op_sel_hi:[0,1]
	v_pk_fma_f32 v[176:177], v[116:117], v[8:9], v[178:179] op_sel_hi:[1,0,1] neg_lo:[0,0,1]
	ds_write_b64 v65, v[176:177] offset:8448
	v_pk_mul_f32 v[182:183], v[124:125], v[10:11] op_sel:[1,1] op_sel_hi:[0,1]
	v_pk_fma_f32 v[180:181], v[124:125], v[10:11], v[182:183] op_sel_hi:[1,0,1] neg_lo:[0,0,1]
	ds_write_b64 v65, v[180:181] offset:12672
	v_pk_mul_f32 v[186:187], v[102:103], v[12:13] op_sel:[1,1] op_sel_hi:[0,1]
	v_pk_fma_f32 v[184:185], v[102:103], v[12:13], v[186:187] op_sel_hi:[1,0,1] neg_lo:[0,0,1]
	ds_write_b64 v65, v[184:185] offset:16896
	v_pk_mul_f32 v[166:167], v[110:111], v[14:15] op_sel:[1,1] op_sel_hi:[0,1]
	v_pk_fma_f32 v[188:189], v[110:111], v[14:15], v[166:167] op_sel_hi:[1,0,1] neg_lo:[0,0,1]
	ds_write_b64 v65, v[188:189] offset:21120
	v_pk_mul_f32 v[168:169], v[118:119], v[16:17] op_sel:[1,1] op_sel_hi:[0,1]
	v_pk_fma_f32 v[174:175], v[118:119], v[16:17], v[168:169] op_sel_hi:[1,0,1] neg_lo:[0,0,1]
	ds_write_b64 v65, v[174:175] offset:25344
	v_pk_mul_f32 v[176:177], v[126:127], v[18:19] op_sel:[1,1] op_sel_hi:[0,1]
	v_pk_fma_f32 v[178:179], v[126:127], v[18:19], v[176:177] op_sel_hi:[1,0,1] neg_lo:[0,0,1]
	ds_write_b64 v65, v[178:179] offset:29568
	v_pk_mul_f32 v[180:181], v[104:105], v[20:21] op_sel:[1,1] op_sel_hi:[0,1]
	v_pk_fma_f32 v[182:183], v[104:105], v[20:21], v[180:181] op_sel_hi:[1,0,1] neg_lo:[0,0,1]
	ds_write_b64 v65, v[182:183] offset:33792
	v_pk_mul_f32 v[184:185], v[112:113], v[22:23] op_sel:[1,1] op_sel_hi:[0,1]
	v_pk_fma_f32 v[186:187], v[112:113], v[22:23], v[184:185] op_sel_hi:[1,0,1] neg_lo:[0,0,1]
	ds_write_b64 v65, v[186:187] offset:38016
	v_pk_mul_f32 v[188:189], v[120:121], v[24:25] op_sel:[1,1] op_sel_hi:[0,1]
	v_pk_fma_f32 v[166:167], v[120:121], v[24:25], v[188:189] op_sel_hi:[1,0,1] neg_lo:[0,0,1]
	ds_write_b64 v65, v[166:167] offset:42240
	v_pk_mul_f32 v[174:175], v[128:129], v[26:27] op_sel:[1,1] op_sel_hi:[0,1]
	v_pk_fma_f32 v[168:169], v[128:129], v[26:27], v[174:175] op_sel_hi:[1,0,1] neg_lo:[0,0,1]
	ds_write_b64 v65, v[168:169] offset:46464
	v_pk_mul_f32 v[178:179], v[106:107], v[28:29] op_sel:[1,1] op_sel_hi:[0,1]
	v_pk_fma_f32 v[176:177], v[106:107], v[28:29], v[178:179] op_sel_hi:[1,0,1] neg_lo:[0,0,1]
	ds_write_b64 v65, v[176:177] offset:50688
	v_pk_mul_f32 v[182:183], v[114:115], v[30:31] op_sel:[1,1] op_sel_hi:[0,1]
	v_pk_fma_f32 v[180:181], v[114:115], v[30:31], v[182:183] op_sel_hi:[1,0,1] neg_lo:[0,0,1]
	ds_write_b64 v65, v[180:181] offset:54912
	v_pk_mul_f32 v[186:187], v[122:123], v[32:33] op_sel:[1,1] op_sel_hi:[0,1]
	v_pk_fma_f32 v[184:185], v[122:123], v[32:33], v[186:187] op_sel_hi:[1,0,1] neg_lo:[0,0,1]
	ds_write_b64 v65, v[184:185] offset:59136
	v_pk_mul_f32 v[166:167], v[130:131], v[34:35] op_sel:[1,1] op_sel_hi:[0,1]
	v_pk_fma_f32 v[188:189], v[130:131], v[34:35], v[166:167] op_sel_hi:[1,0,1] neg_lo:[0,0,1]
	ds_write_b64 v65, v[188:189] offset:63360
	s_waitcnt vmcnt(7)
; #define LAS __attribute__((address_space(3)))
; #define WG_SYNC() do { asm volatile("s_waitcnt lgkmcnt(0)" ::: "memory"); __builtin_amdgcn_s_barrier(); asm volatile("" ::: "memory"); } while (0)
; __device__ __forceinline__ void hy_stage(LAS float* plane, const bf16_t* PHY, int cg, int jc, int tid) {
;     asm volatile("" : "+v"(tid));
;     const u32x4* src = (const u32x4*)(PHY + (size_t)cg * MT * 4);
; #pragma unroll
;     for (int k = 0; k < 8; ++k) { const int i = tid + 512 * k; const u32x4 v = src[i];
;         const unsigned w0 = (jc & 2) ? v.y : v.x, w1 = (jc & 2) ? v.w : v.z;
;         f32x2 o; o.x = (jc & 1) ? bf_hi(w0) : bf_lo(w0); o.y = (jc & 1) ? bf_hi(w1) : bf_lo(w1);
;         *(LAS f32x2*)(plane + 2 * i) = o; }
; }
; __device__ __forceinline__ void hy_sconv(const LAS float* plane, float w0, float w1, float w2, float cb, int n2, float (&u)[8][2]) {
;     asm volatile("" : "+v"(n2));
; #pragma unroll
;     for (int r = 0; r < 8; ++r)
; #pragma unroll
;         for (int b = 0; b < 2; ++b) { const int t = n2 + 512 * r, row = b * SEQ + t;
;             float a = cb + w1 * plane[row];
;             if (t > 0) a += w0 * plane[row - 1];
;             if (t < SEQ - 1) a += w2 * plane[row + 1];
;             u[r][b] = a; }
; }
; __device__ __forceinline__ void hyena_fft(LAS unsigned char* lds, int layer, int G, const int wave_s) {
;     ...
;             hy_stage(pl0, PHY, 2 * (HY / 4) + unit, jc, tid); __builtin_amdgcn_sched_barrier(0); hy_stage(pl1, PHY, unit, jc, tid); __builtin_amdgcn_sched_barrier(0);
;             WG_SYNC();
;             float uz[8][2], ux[8][2];
;             hy_sconv(pl0, cw[2 * HY + c], cw[3 * HY + 2 * HY + c], cw[6 * HY + 2 * HY + c], cb[2 * HY + c], n2, uz);
	v_perm_b32 v174, 0, v58, s15
	v_perm_b32 v175, 0, v60, s15
	ds_write_b64 v206, v[174:175]
	s_waitcnt vmcnt(6)
	v_perm_b32 v168, 0, v62, s15
	v_perm_b32 v169, 0, v64, s15
	ds_write_b64 v206, v[168:169] offset:4096
	s_waitcnt vmcnt(5)
	v_perm_b32 v178, 0, v66, s15
	v_perm_b32 v179, 0, v68, s15
	ds_write_b64 v206, v[178:179] offset:8192
	s_waitcnt vmcnt(4)
	v_perm_b32 v176, 0, v70, s15
	v_perm_b32 v177, 0, v72, s15
	ds_write_b64 v206, v[176:177] offset:12288
	s_waitcnt vmcnt(3)
	v_perm_b32 v182, 0, v74, s15
	v_perm_b32 v183, 0, v76, s15
	ds_write_b64 v206, v[182:183] offset:16384
	s_waitcnt vmcnt(2)
	v_perm_b32 v180, 0, v78, s15
	v_perm_b32 v181, 0, v80, s15
	ds_write_b64 v206, v[180:181] offset:20480
	s_waitcnt vmcnt(1)
	v_perm_b32 v186, 0, v82, s15
	v_perm_b32 v187, 0, v84, s15
	ds_write_b64 v206, v[186:187] offset:24576
	s_waitcnt vmcnt(0)
	v_perm_b32 v184, 0, v86, s15
	v_perm_b32 v185, 0, v88, s15
	ds_write_b64 v206, v[184:185] offset:28672
	s_add_u32 s56, s38, s73
	s_addc_u32 s57, s39, 0
	global_load_dwordx3 v[58:60], v216, s[56:57]
	global_load_dwordx3 v[62:64], v218, s[56:57]
	global_load_dwordx3 v[66:68], v220, s[56:57]
	global_load_dwordx3 v[70:72], v222, s[56:57]
	global_load_dwordx3 v[74:76], v240, s[56:57]
	global_load_dwordx3 v[78:80], v242, s[56:57]
	global_load_dwordx3 v[82:84], v244, s[56:57]
	global_load_dwordx3 v[86:88], v61, s[56:57]
	s_load_dwordx2 s[60:61], s[94:95], 0x48
	s_load_dwordx2 s[62:63], s[94:95], 0x50
	s_load_dwordx2 s[50:51], s[94:95], 0x88
	s_lshl_b32 s43, s80, 2
	s_mul_i32 s53, s76, 0x9000
	s_add_u32 s53, s53, s43
	s_mul_i32 s55, s76, 0x3000
	s_add_u32 s55, s55, s43
	s_waitcnt lgkmcnt(0)
	s_add_u32 s60, s60, s53
	s_addc_u32 s61, s61, 0
	s_add_u32 s62, s62, s55
	s_addc_u32 s63, s63, 0
	s_mul_i32 s53, s76, 0x2000
	s_add_u32 s53, s53, s43
	s_add_u32 s50, s50, s53
	s_addc_u32 s51, s51, 0
	s_load_dword s17, s[60:61], 0x2000
	s_load_dword s23, s[60:61], 0x5000
	s_load_dword s25, s[60:61], 0x8000
	s_load_dword s26, s[62:63], 0x2000
	s_waitcnt lgkmcnt(0)
	s_barrier
	v_mov_b32_e32 v166, s17
	v_mov_b32_e32 v167, s23
	v_mov_b32_e32 v188, s25
	v_mov_b32_e32 v189, s26
	ds_read_b32 v174, v208
	ds_read_b32 v168, v210
	ds_read_b32 v178, v208 offset:4
	ds_read_b32 v175, v208 offset:16384
	ds_read_b32 v169, v210 offset:16384
	ds_read_b32 v179, v208 offset:16388
	ds_read_b32 v176, v208 offset:2048
	ds_read_b32 v182, v208 offset:2044
	ds_read_b32 v180, v208 offset:2052
	ds_read_b32 v177, v208 offset:18432
	ds_read_b32 v183, v208 offset:18428
	ds_read_b32 v181, v208 offset:18436
	s_waitcnt lgkmcnt(10)
	v_cndmask_b32_e64 v168, v168, 0, s[10:11]
	s_waitcnt lgkmcnt(7)
	v_cndmask_b32_e64 v169, v169, 0, s[10:11]
	v_pk_fma_f32 v[132:133], v[166:167], v[174:175], v[188:189] op_sel:[1,0,1]
	v_pk_fma_f32 v[132:133], v[166:167], v[168:169], v[132:133] op_sel_hi:[0,1,1]
	s_waitcnt lgkmcnt(6)
	v_pk_fma_f32 v[132:133], v[188:189], v[178:179], v[132:133] op_sel_hi:[0,1,1]
	s_waitcnt lgkmcnt(2)
	v_pk_fma_f32 v[134:135], v[166:167], v[176:177], v[188:189] op_sel:[1,0,1]
	s_waitcnt lgkmcnt(1)
	v_pk_fma_f32 v[134:135], v[166:167], v[182:183], v[134:135] op_sel_hi:[0,1,1]
	s_waitcnt lgkmcnt(0)
	v_pk_fma_f32 v[134:135], v[188:189], v[180:181], v[134:135] op_sel_hi:[0,1,1]
	ds_read_b32 v186, v208 offset:4096
	ds_read_b32 v184, v208 offset:4092
	ds_read_b32 v174, v208 offset:4100
	ds_read_b32 v187, v208 offset:20480
	ds_read_b32 v185, v208 offset:20476
	ds_read_b32 v175, v208 offset:20484
	ds_read_b32 v168, v208 offset:6144
	ds_read_b32 v178, v208 offset:6140
	ds_read_b32 v176, v208 offset:6148
	ds_read_b32 v169, v208 offset:22528
	ds_read_b32 v179, v208 offset:22524
	ds_read_b32 v177, v208 offset:22532
	s_waitcnt lgkmcnt(8)
	v_pk_fma_f32 v[136:137], v[166:167], v[186:187], v[188:189] op_sel:[1,0,1]
	s_waitcnt lgkmcnt(7)
	v_pk_fma_f32 v[136:137], v[166:167], v[184:185], v[136:137] op_sel_hi:[0,1,1]
	s_waitcnt lgkmcnt(6)
	v_pk_fma_f32 v[136:137], v[188:189], v[174:175], v[136:137] op_sel_hi:[0,1,1]
	s_waitcnt lgkmcnt(2)
	v_pk_fma_f32 v[138:139], v[166:167], v[168:169], v[188:189] op_sel:[1,0,1]
	s_waitcnt lgkmcnt(1)
	v_pk_fma_f32 v[138:139], v[166:167], v[178:179], v[138:139] op_sel_hi:[0,1,1]
	s_waitcnt lgkmcnt(0)
	v_pk_fma_f32 v[138:139], v[188:189], v[176:177], v[138:139] op_sel_hi:[0,1,1]
	ds_read_b32 v182, v208 offset:8192
	ds_read_b32 v180, v208 offset:8188
	ds_read_b32 v186, v208 offset:8196
	ds_read_b32 v183, v208 offset:24576
	ds_read_b32 v181, v208 offset:24572
	ds_read_b32 v187, v208 offset:24580
	ds_read_b32 v184, v208 offset:10240
	ds_read_b32 v174, v208 offset:10236
	ds_read_b32 v168, v208 offset:10244
	ds_read_b32 v185, v208 offset:26624
	ds_read_b32 v175, v208 offset:26620
	ds_read_b32 v169, v208 offset:26628
	s_waitcnt lgkmcnt(8)
	v_pk_fma_f32 v[140:141], v[166:167], v[182:183], v[188:189] op_sel:[1,0,1]
	s_waitcnt lgkmcnt(7)
	v_pk_fma_f32 v[140:141], v[166:167], v[180:181], v[140:141] op_sel_hi:[0,1,1]
	s_waitcnt lgkmcnt(6)
	v_pk_fma_f32 v[140:141], v[188:189], v[186:187], v[140:141] op_sel_hi:[0,1,1]
	s_waitcnt lgkmcnt(2)
	v_pk_fma_f32 v[142:143], v[166:167], v[184:185], v[188:189] op_sel:[1,0,1]
	s_waitcnt lgkmcnt(1)
	v_pk_fma_f32 v[142:143], v[166:167], v[174:175], v[142:143] op_sel_hi:[0,1,1]
	s_waitcnt lgkmcnt(0)
	v_pk_fma_f32 v[142:143], v[188:189], v[168:169], v[142:143] op_sel_hi:[0,1,1]
	ds_read_b32 v178, v208 offset:12288
	ds_read_b32 v176, v208 offset:12284
	ds_read_b32 v182, v208 offset:12292
	ds_read_b32 v179, v208 offset:28672
	ds_read_b32 v177, v208 offset:28668
	ds_read_b32 v183, v208 offset:28676
	ds_read_b32 v180, v208 offset:14336
	ds_read_b32 v186, v208 offset:14332
	ds_read_b32 v184, v208 offset:14340
	ds_read_b32 v181, v208 offset:30720
	ds_read_b32 v187, v208 offset:30716
	ds_read_b32 v185, v208 offset:30724
	s_waitcnt lgkmcnt(8)
; #define LAS __attribute__((address_space(3)))
; __device__ __forceinline__ void fft_fwd2(LAS f32x2* B, const LAS f32x2* TW2, int tid) {
;     asm volatile("" : "+v"(tid));
;     const int b = tid >> 5, n2 = tid & 31, base = 512 * b + n2; f32x2 x[16];
; #pragma unroll
;     for (int r = 0; r < 16; ++r) x[r] = B[fpad(base + 32 * r)];
;     dft16<false>(x);
; __device__ __forceinline__ void hy_stage(LAS float* plane, const bf16_t* PHY, int cg, int jc, int tid) {
;     asm volatile("" : "+v"(tid));
;     const u32x4* src = (const u32x4*)(PHY + (size_t)cg * MT * 4);
; #pragma unroll
;     for (int k = 0; k < 8; ++k) { const int i = tid + 512 * k; const u32x4 v = src[i];
;         const unsigned w0 = (jc & 2) ? v.y : v.x, w1 = (jc & 2) ? v.w : v.z;
;         f32x2 o; o.x = (jc & 1) ? bf_hi(w0) : bf_lo(w0); o.y = (jc & 1) ? bf_hi(w1) : bf_lo(w1);
;         *(LAS f32x2*)(plane + 2 * i) = o; }
; }
; __device__ __forceinline__ void hy_sconv(const LAS float* plane, float w0, float w1, float w2, float cb, int n2, float (&u)[8][2]) {
;     asm volatile("" : "+v"(n2));
; #pragma unroll
;     for (int r = 0; r < 8; ++r)
; #pragma unroll
;         for (int b = 0; b < 2; ++b) { const int t = n2 + 512 * r, row = b * SEQ + t;
;             float a = cb + w1 * plane[row];
;             if (t > 0) a += w0 * plane[row - 1];
;             if (t < SEQ - 1) a += w2 * plane[row + 1];
;             u[r][b] = a; }
; }
	v_pk_fma_f32 v[144:145], v[166:167], v[178:179], v[188:189] op_sel:[1,0,1]
	s_waitcnt lgkmcnt(7)
	v_pk_fma_f32 v[144:145], v[166:167], v[176:177], v[144:145] op_sel_hi:[0,1,1]
	s_waitcnt lgkmcnt(6)
	v_pk_fma_f32 v[144:145], v[188:189], v[182:183], v[144:145] op_sel_hi:[0,1,1]
	s_waitcnt lgkmcnt(3)
	v_cndmask_b32_e64 v184, v184, 0, s[28:29]
	s_waitcnt lgkmcnt(0)
	v_cndmask_b32_e64 v185, v185, 0, s[28:29]
	v_pk_fma_f32 v[146:147], v[166:167], v[180:181], v[188:189] op_sel:[1,0,1]
	v_pk_fma_f32 v[146:147], v[166:167], v[186:187], v[146:147] op_sel_hi:[0,1,1]
	v_pk_fma_f32 v[146:147], v[188:189], v[184:185], v[146:147] op_sel_hi:[0,1,1]
	s_load_dword s17, s[60:61], 0x0
	s_load_dword s23, s[60:61], 0x3000
	s_load_dword s25, s[60:61], 0x6000
	s_load_dword s26, s[62:63], 0x0
	s_waitcnt vmcnt(7)
	v_perm_b32 v174, 0, v58, s15
	v_perm_b32 v175, 0, v60, s15
	ds_write_b64 v206, v[174:175] offset:32768
	s_waitcnt vmcnt(6)
	v_perm_b32 v168, 0, v62, s15
	v_perm_b32 v169, 0, v64, s15
	ds_write_b64 v206, v[168:169] offset:36864
	s_waitcnt vmcnt(5)
	v_perm_b32 v178, 0, v66, s15
	v_perm_b32 v179, 0, v68, s15
	ds_write_b64 v206, v[178:179] offset:40960
	s_waitcnt vmcnt(4)
	v_perm_b32 v176, 0, v70, s15
	v_perm_b32 v177, 0, v72, s15
	ds_write_b64 v206, v[176:177] offset:45056
	s_waitcnt vmcnt(3)
	v_perm_b32 v182, 0, v74, s15
	v_perm_b32 v183, 0, v76, s15
	ds_write_b64 v206, v[182:183] offset:49152
	s_waitcnt vmcnt(2)
	v_perm_b32 v180, 0, v78, s15
	v_perm_b32 v181, 0, v80, s15
	ds_write_b64 v206, v[180:181] offset:53248
	s_waitcnt vmcnt(1)
	v_perm_b32 v186, 0, v82, s15
	v_perm_b32 v187, 0, v84, s15
	ds_write_b64 v206, v[186:187] offset:57344
	s_waitcnt vmcnt(0)
	v_perm_b32 v184, 0, v86, s15
	v_perm_b32 v185, 0, v88, s15
	ds_write_b64 v206, v[184:185] offset:61440
	s_add_u32 s56, s38, s73
	s_addc_u32 s57, s39, 0
	s_add_u32 s56, s56, 0x1100000
	s_addc_u32 s57, s57, 0
	global_load_dwordx3 v[58:60], v216, s[56:57]
	global_load_dwordx3 v[62:64], v218, s[56:57]
	global_load_dwordx3 v[66:68], v220, s[56:57]
	global_load_dwordx3 v[70:72], v222, s[56:57]
	global_load_dwordx3 v[74:76], v240, s[56:57]
	global_load_dwordx3 v[78:80], v242, s[56:57]
	global_load_dwordx3 v[82:84], v244, s[56:57]
	global_load_dwordx3 v[86:88], v61, s[56:57]
	v_add_u32_e32 v65, 0x10800, v5
	ds_read_b64 v[100:101], v65
	ds_read_b64 v[108:109], v65 offset:264
	ds_read_b64 v[116:117], v65 offset:528
	ds_read_b64 v[124:125], v65 offset:792
	ds_read_b64 v[102:103], v65 offset:1056
	ds_read_b64 v[110:111], v65 offset:1320
	ds_read_b64 v[118:119], v65 offset:1584
	ds_read_b64 v[126:127], v65 offset:1848
	ds_read_b64 v[104:105], v65 offset:2112
	ds_read_b64 v[112:113], v65 offset:2376
	ds_read_b64 v[120:121], v65 offset:2640
	ds_read_b64 v[128:129], v65 offset:2904
	s_waitcnt lgkmcnt(8)
	ds_read_b64 v[106:107], v65 offset:3168
	ds_read_b64 v[114:115], v65 offset:3432
	ds_read_b64 v[122:123], v65 offset:3696
	ds_read_b64 v[130:131], v65 offset:3960
	s_waitcnt lgkmcnt(7)
	v_pk_add_f32 v[166:167], v[100:101], v[104:105]
	v_pk_add_f32 v[188:189], v[100:101], v[104:105] neg_lo:[0,1] neg_hi:[0,1]
	s_waitcnt lgkmcnt(3)
	v_pk_add_f32 v[174:175], v[102:103], v[106:107]
	v_pk_add_f32 v[168:169], v[102:103], v[106:107] neg_lo:[0,1] neg_hi:[0,1]
	v_pk_add_f32 v[100:101], v[166:167], v[174:175]
	v_pk_add_f32 v[104:105], v[166:167], v[174:175] neg_lo:[0,1] neg_hi:[0,1]
	v_pk_add_f32 v[102:103], v[188:189], v[168:169] op_sel:[0,1] op_sel_hi:[1,0] neg_hi:[0,1]
	v_pk_add_f32 v[106:107], v[188:189], v[168:169] op_sel:[0,1] op_sel_hi:[1,0] neg_lo:[0,1]
	v_pk_add_f32 v[178:179], v[108:109], v[112:113]
	v_pk_add_f32 v[176:177], v[108:109], v[112:113] neg_lo:[0,1] neg_hi:[0,1]
	s_waitcnt lgkmcnt(2)
	v_pk_add_f32 v[182:183], v[110:111], v[114:115]
	v_pk_add_f32 v[180:181], v[110:111], v[114:115] neg_lo:[0,1] neg_hi:[0,1]
	v_pk_add_f32 v[108:109], v[178:179], v[182:183]
	v_pk_add_f32 v[112:113], v[178:179], v[182:183] neg_lo:[0,1] neg_hi:[0,1]
	v_pk_add_f32 v[110:111], v[176:177], v[180:181] op_sel:[0,1] op_sel_hi:[1,0] neg_hi:[0,1]
	v_pk_add_f32 v[114:115], v[176:177], v[180:181] op_sel:[0,1] op_sel_hi:[1,0] neg_lo:[0,1]
	v_pk_add_f32 v[186:187], v[116:117], v[120:121]
	v_pk_add_f32 v[184:185], v[116:117], v[120:121] neg_lo:[0,1] neg_hi:[0,1]
	s_waitcnt lgkmcnt(1)
	v_pk_add_f32 v[166:167], v[118:119], v[122:123]
	v_pk_add_f32 v[188:189], v[118:119], v[122:123] neg_lo:[0,1] neg_hi:[0,1]
	v_pk_add_f32 v[116:117], v[186:187], v[166:167]
	v_pk_add_f32 v[120:121], v[186:187], v[166:167] neg_lo:[0,1] neg_hi:[0,1]
	v_pk_add_f32 v[118:119], v[184:185], v[188:189] op_sel:[0,1] op_sel_hi:[1,0] neg_hi:[0,1]
	v_pk_add_f32 v[122:123], v[184:185], v[188:189] op_sel:[0,1] op_sel_hi:[1,0] neg_lo:[0,1]
	v_pk_add_f32 v[174:175], v[124:125], v[128:129]
	v_pk_add_f32 v[168:169], v[124:125], v[128:129] neg_lo:[0,1] neg_hi:[0,1]
	s_waitcnt lgkmcnt(0)
; #define LAS __attribute__((address_space(3)))
; __device__ __forceinline__ f32x2 cmul(f32x2 a, f32x2 b) { return (f32x2){a.x * b.x - a.y * b.y, a.x * b.y + a.y * b.x}; }
; template <bool INV> __device__ __forceinline__ f32x2 cmul_tw(f32x2 a, f32x2 w) { return INV ? cmulc(a, w) : cmul(a, w); }
; template <bool INV> __device__ __forceinline__ void dft16(f32x2 (&x)[16]) {
;     constexpr float C1 = 0.92387953251128674f, S1 = 0.38268343236508977f, C2 = 0.70710678118654752f;
; #pragma unroll
;     for (int b = 0; b < 4; ++b) dft4<INV>(x[b], x[4 + b], x[8 + b], x[12 + b]);
;     const f32x2 w1 = {C1, -S1}, w2 = {C2, -C2}, w3 = {S1, -C1}, w4 = {0.f, -1.f}, w6 = {-C2, -C2}, w9 = {-C1, S1};
;     x[4 * 1 + 1] = cmul_tw<INV>(x[5], w1); x[4 * 1 + 2] = cmul_tw<INV>(x[6], w2); x[4 * 1 + 3] = cmul_tw<INV>(x[7], w3);
;     x[4 * 2 + 1] = cmul_tw<INV>(x[9], w2); x[4 * 2 + 2] = cmul_tw<INV>(x[10], w4); x[4 * 2 + 3] = cmul_tw<INV>(x[11], w6);
;     x[4 * 3 + 1] = cmul_tw<INV>(x[13], w3); x[4 * 3 + 2] = cmul_tw<INV>(x[14], w6); x[4 * 3 + 3] = cmul_tw<INV>(x[15], w9);
; #pragma unroll
;     for (int c = 0; c < 4; ++c) dft4<INV>(x[4 * c], x[4 * c + 1], x[4 * c + 2], x[4 * c + 3]);
;     f32x2 y[16];
; #pragma unroll
;     for (int k = 0; k < 16; ++k) y[k] = x[4 * (k & 3) + (k >> 2)];
; #pragma unroll
;     for (int k = 0; k < 16; ++k) x[k] = y[k];
; __device__ __forceinline__ void fft_fwd2(LAS f32x2* B, const LAS f32x2* TW2, int tid) {
;     asm volatile("" : "+v"(tid));
;     const int b = tid >> 5, n2 = tid & 31, base = 512 * b + n2; f32x2 x[16];
; #pragma unroll
;     for (int r = 0; r < 16; ++r) x[r] = B[fpad(base + 32 * r)];
;     dft16<false>(x);
;     B[fpad(base)] = x[0];
; #pragma unroll
;     for (int k = 1; k < 16; ++k) B[fpad(base + 32 * k)] = cmul(x[k], TW2[k * 32 + n2]);
; }
	v_pk_add_f32 v[178:179], v[126:127], v[130:131]
	v_pk_add_f32 v[176:177], v[126:127], v[130:131] neg_lo:[0,1] neg_hi:[0,1]
	v_pk_add_f32 v[124:125], v[174:175], v[178:179]
	v_pk_add_f32 v[128:129], v[174:175], v[178:179] neg_lo:[0,1] neg_hi:[0,1]
	v_pk_add_f32 v[126:127], v[168:169], v[176:177] op_sel:[0,1] op_sel_hi:[1,0] neg_hi:[0,1]
	v_pk_add_f32 v[130:131], v[168:169], v[176:177] op_sel:[0,1] op_sel_hi:[1,0] neg_lo:[0,1]
	v_pk_mul_f32 v[182:183], v[110:111], s[68:69] op_sel:[1,1] op_sel_hi:[0,1]
	v_pk_fma_f32 v[110:111], v[110:111], s[68:69], v[182:183] op_sel_hi:[1,0,1] neg_lo:[0,0,1]
	v_pk_mul_f32 v[180:181], v[118:119], s[84:85] op_sel:[1,1] op_sel_hi:[0,1]
	v_pk_fma_f32 v[118:119], v[118:119], s[84:85], v[180:181] op_sel_hi:[1,0,1] neg_lo:[0,0,1]
	v_pk_mul_f32 v[186:187], v[126:127], s[88:89] op_sel:[1,1] op_sel_hi:[0,1]
	v_pk_fma_f32 v[126:127], v[126:127], s[88:89], v[186:187] op_sel_hi:[1,0,1] neg_lo:[0,0,1]
	v_pk_mul_f32 v[184:185], v[112:113], s[84:85] op_sel:[1,1] op_sel_hi:[0,1]
	v_pk_fma_f32 v[112:113], v[112:113], s[84:85], v[184:185] op_sel_hi:[1,0,1] neg_lo:[0,0,1]
	v_pk_mul_f32 v[166:167], v[128:129], s[90:91] op_sel:[1,1] op_sel_hi:[0,1]
	v_pk_fma_f32 v[128:129], v[128:129], s[90:91], v[166:167] op_sel_hi:[1,0,1] neg_lo:[0,0,1]
	v_pk_mul_f32 v[188:189], v[114:115], s[88:89] op_sel:[1,1] op_sel_hi:[0,1]
	v_pk_fma_f32 v[114:115], v[114:115], s[88:89], v[188:189] op_sel_hi:[1,0,1] neg_lo:[0,0,1]
	v_pk_mul_f32 v[174:175], v[122:123], s[90:91] op_sel:[1,1] op_sel_hi:[0,1]
	v_pk_fma_f32 v[122:123], v[122:123], s[90:91], v[174:175] op_sel_hi:[1,0,1] neg_lo:[0,0,1]
	v_pk_mul_f32 v[168:169], v[130:131], s[98:99] op_sel:[1,1] op_sel_hi:[0,1]
	v_pk_fma_f32 v[130:131], v[130:131], s[98:99], v[168:169] op_sel_hi:[1,0,1] neg_lo:[0,0,1]
	v_pk_add_f32 v[178:179], v[100:101], v[116:117]
	v_pk_add_f32 v[176:177], v[100:101], v[116:117] neg_lo:[0,1] neg_hi:[0,1]
	v_pk_add_f32 v[182:183], v[108:109], v[124:125]
	v_pk_add_f32 v[180:181], v[108:109], v[124:125] neg_lo:[0,1] neg_hi:[0,1]
	v_pk_add_f32 v[100:101], v[178:179], v[182:183]
	v_pk_add_f32 v[116:117], v[178:179], v[182:183] neg_lo:[0,1] neg_hi:[0,1]
	v_pk_add_f32 v[108:109], v[176:177], v[180:181] op_sel:[0,1] op_sel_hi:[1,0] neg_hi:[0,1]
	v_pk_add_f32 v[124:125], v[176:177], v[180:181] op_sel:[0,1] op_sel_hi:[1,0] neg_lo:[0,1]
	v_pk_add_f32 v[186:187], v[102:103], v[118:119]
	v_pk_add_f32 v[184:185], v[102:103], v[118:119] neg_lo:[0,1] neg_hi:[0,1]
	v_pk_add_f32 v[166:167], v[110:111], v[126:127]
	v_pk_add_f32 v[188:189], v[110:111], v[126:127] neg_lo:[0,1] neg_hi:[0,1]
	v_pk_add_f32 v[102:103], v[186:187], v[166:167]
	v_pk_add_f32 v[118:119], v[186:187], v[166:167] neg_lo:[0,1] neg_hi:[0,1]
	v_pk_add_f32 v[110:111], v[184:185], v[188:189] op_sel:[0,1] op_sel_hi:[1,0] neg_hi:[0,1]
	v_pk_add_f32 v[126:127], v[184:185], v[188:189] op_sel:[0,1] op_sel_hi:[1,0] neg_lo:[0,1]
	v_pk_add_f32 v[174:175], v[104:105], v[120:121] op_sel:[0,1] op_sel_hi:[1,0] neg_hi:[0,1]
	v_pk_add_f32 v[168:169], v[104:105], v[120:121] op_sel:[0,1] op_sel_hi:[1,0] neg_lo:[0,1]
	v_pk_add_f32 v[178:179], v[112:113], v[128:129]
	v_pk_add_f32 v[176:177], v[112:113], v[128:129] neg_lo:[0,1] neg_hi:[0,1]
	v_pk_add_f32 v[104:105], v[174:175], v[178:179]
	v_pk_add_f32 v[120:121], v[174:175], v[178:179] neg_lo:[0,1] neg_hi:[0,1]
	v_pk_add_f32 v[112:113], v[168:169], v[176:177] op_sel:[0,1] op_sel_hi:[1,0] neg_hi:[0,1]
	v_pk_add_f32 v[128:129], v[168:169], v[176:177] op_sel:[0,1] op_sel_hi:[1,0] neg_lo:[0,1]
	v_pk_add_f32 v[182:183], v[106:107], v[122:123]
	v_pk_add_f32 v[180:181], v[106:107], v[122:123] neg_lo:[0,1] neg_hi:[0,1]
	v_pk_add_f32 v[186:187], v[114:115], v[130:131]
	v_pk_add_f32 v[184:185], v[114:115], v[130:131] neg_lo:[0,1] neg_hi:[0,1]
	v_pk_add_f32 v[106:107], v[182:183], v[186:187]
	v_pk_add_f32 v[122:123], v[182:183], v[186:187] neg_lo:[0,1] neg_hi:[0,1]
	v_pk_add_f32 v[114:115], v[180:181], v[184:185] op_sel:[0,1] op_sel_hi:[1,0] neg_hi:[0,1]
	v_pk_add_f32 v[130:131], v[180:181], v[184:185] op_sel:[0,1] op_sel_hi:[1,0] neg_lo:[0,1]
	ds_write_b64 v65, v[100:101]
	ds_read_b64 v[166:167], v56 offset:256
	ds_read_b64 v[188:189], v56 offset:512
	ds_read_b64 v[174:175], v56 offset:768
	ds_read_b64 v[168:169], v56 offset:1024
	s_waitcnt lgkmcnt(3)
	v_pk_mul_f32 v[178:179], v[102:103], v[166:167] op_sel:[1,1] op_sel_hi:[0,1]
	v_pk_fma_f32 v[102:103], v[102:103], v[166:167], v[178:179] op_sel_hi:[1,0,1] neg_lo:[0,0,1]
	ds_write_b64 v65, v[102:103] offset:264
	s_waitcnt lgkmcnt(3)
	v_pk_mul_f32 v[176:177], v[104:105], v[188:189] op_sel:[1,1] op_sel_hi:[0,1]
	v_pk_fma_f32 v[104:105], v[104:105], v[188:189], v[176:177] op_sel_hi:[1,0,1] neg_lo:[0,0,1]
	ds_write_b64 v65, v[104:105] offset:528
	s_waitcnt lgkmcnt(3)
	v_pk_mul_f32 v[182:183], v[106:107], v[174:175] op_sel:[1,1] op_sel_hi:[0,1]
	v_pk_fma_f32 v[106:107], v[106:107], v[174:175], v[182:183] op_sel_hi:[1,0,1] neg_lo:[0,0,1]
	ds_write_b64 v65, v[106:107] offset:792
	s_waitcnt lgkmcnt(3)
	v_pk_mul_f32 v[180:181], v[108:109], v[168:169] op_sel:[1,1] op_sel_hi:[0,1]
	v_pk_fma_f32 v[108:109], v[108:109], v[168:169], v[180:181] op_sel_hi:[1,0,1] neg_lo:[0,0,1]
	ds_write_b64 v65, v[108:109] offset:1056
	ds_read_b64 v[186:187], v56 offset:1280
	ds_read_b64 v[184:185], v56 offset:1536
	ds_read_b64 v[178:179], v56 offset:1792
	ds_read_b64 v[176:177], v56 offset:2048
	s_waitcnt lgkmcnt(3)
	v_pk_mul_f32 v[182:183], v[110:111], v[186:187] op_sel:[1,1] op_sel_hi:[0,1]
	v_pk_fma_f32 v[110:111], v[110:111], v[186:187], v[182:183] op_sel_hi:[1,0,1] neg_lo:[0,0,1]
	ds_write_b64 v65, v[110:111] offset:1320
	s_waitcnt lgkmcnt(3)
; #define LAS __attribute__((address_space(3)))
; __device__ __forceinline__ f32x2 cmul(f32x2 a, f32x2 b) { return (f32x2){a.x * b.x - a.y * b.y, a.x * b.y + a.y * b.x}; }
; __device__ __forceinline__ void fft_fwd2(LAS f32x2* B, const LAS f32x2* TW2, int tid) {
;     ...
;     B[fpad(base)] = x[0];
; #pragma unroll
;     for (int k = 1; k < 16; ++k) B[fpad(base + 32 * k)] = cmul(x[k], TW2[k * 32 + n2]);
; __device__ __forceinline__ void hy_sconv(const LAS float* plane, float w0, float w1, float w2, float cb, int n2, float (&u)[8][2]) {
;     asm volatile("" : "+v"(n2));
; #pragma unroll
;     for (int r = 0; r < 8; ++r)
; #pragma unroll
;         for (int b = 0; b < 2; ++b) { const int t = n2 + 512 * r, row = b * SEQ + t;
;             float a = cb + w1 * plane[row];
;             if (t > 0) a += w0 * plane[row - 1];
;             if (t < SEQ - 1) a += w2 * plane[row + 1];
;             u[r][b] = a; }
; }
	v_pk_mul_f32 v[180:181], v[112:113], v[184:185] op_sel:[1,1] op_sel_hi:[0,1]
	v_pk_fma_f32 v[112:113], v[112:113], v[184:185], v[180:181] op_sel_hi:[1,0,1] neg_lo:[0,0,1]
	ds_write_b64 v65, v[112:113] offset:1584
	s_waitcnt lgkmcnt(3)
	v_pk_mul_f32 v[166:167], v[114:115], v[178:179] op_sel:[1,1] op_sel_hi:[0,1]
	v_pk_fma_f32 v[114:115], v[114:115], v[178:179], v[166:167] op_sel_hi:[1,0,1] neg_lo:[0,0,1]
	ds_write_b64 v65, v[114:115] offset:1848
	s_waitcnt lgkmcnt(3)
	v_pk_mul_f32 v[188:189], v[116:117], v[176:177] op_sel:[1,1] op_sel_hi:[0,1]
	v_pk_fma_f32 v[116:117], v[116:117], v[176:177], v[188:189] op_sel_hi:[1,0,1] neg_lo:[0,0,1]
	ds_write_b64 v65, v[116:117] offset:2112
	ds_read_b64 v[174:175], v56 offset:2304
	ds_read_b64 v[168:169], v56 offset:2560
	ds_read_b64 v[182:183], v56 offset:2816
	ds_read_b64 v[180:181], v56 offset:3072
	s_waitcnt lgkmcnt(3)
	v_pk_mul_f32 v[166:167], v[118:119], v[174:175] op_sel:[1,1] op_sel_hi:[0,1]
	v_pk_fma_f32 v[118:119], v[118:119], v[174:175], v[166:167] op_sel_hi:[1,0,1] neg_lo:[0,0,1]
	ds_write_b64 v65, v[118:119] offset:2376
	s_waitcnt lgkmcnt(3)
	v_pk_mul_f32 v[188:189], v[120:121], v[168:169] op_sel:[1,1] op_sel_hi:[0,1]
	v_pk_fma_f32 v[120:121], v[120:121], v[168:169], v[188:189] op_sel_hi:[1,0,1] neg_lo:[0,0,1]
	ds_write_b64 v65, v[120:121] offset:2640
	s_waitcnt lgkmcnt(3)
	v_pk_mul_f32 v[186:187], v[122:123], v[182:183] op_sel:[1,1] op_sel_hi:[0,1]
	v_pk_fma_f32 v[122:123], v[122:123], v[182:183], v[186:187] op_sel_hi:[1,0,1] neg_lo:[0,0,1]
	ds_write_b64 v65, v[122:123] offset:2904
	s_waitcnt lgkmcnt(3)
	v_pk_mul_f32 v[184:185], v[124:125], v[180:181] op_sel:[1,1] op_sel_hi:[0,1]
	v_pk_fma_f32 v[124:125], v[124:125], v[180:181], v[184:185] op_sel_hi:[1,0,1] neg_lo:[0,0,1]
	ds_write_b64 v65, v[124:125] offset:3168
	ds_read_b64 v[178:179], v56 offset:3328
	ds_read_b64 v[176:177], v56 offset:3584
	ds_read_b64 v[166:167], v56 offset:3840
	s_waitcnt lgkmcnt(2)
	v_pk_mul_f32 v[188:189], v[126:127], v[178:179] op_sel:[1,1] op_sel_hi:[0,1]
	v_pk_fma_f32 v[126:127], v[126:127], v[178:179], v[188:189] op_sel_hi:[1,0,1] neg_lo:[0,0,1]
	ds_write_b64 v65, v[126:127] offset:3432
	s_waitcnt lgkmcnt(2)
	v_pk_mul_f32 v[186:187], v[128:129], v[176:177] op_sel:[1,1] op_sel_hi:[0,1]
	v_pk_fma_f32 v[128:129], v[128:129], v[176:177], v[186:187] op_sel_hi:[1,0,1] neg_lo:[0,0,1]
	ds_write_b64 v65, v[128:129] offset:3696
	s_waitcnt lgkmcnt(2)
	v_pk_mul_f32 v[184:185], v[130:131], v[166:167] op_sel:[1,1] op_sel_hi:[0,1]
	v_pk_fma_f32 v[130:131], v[130:131], v[166:167], v[184:185] op_sel_hi:[1,0,1] neg_lo:[0,0,1]
	ds_write_b64 v65, v[130:131] offset:3960
	s_waitcnt lgkmcnt(0)
	s_barrier
	v_mov_b32_e32 v174, s17
	v_mov_b32_e32 v175, s23
	v_mov_b32_e32 v168, s25
	v_mov_b32_e32 v169, s26
	ds_read_b32 v182, v208 offset:32768
	ds_read_b32 v180, v210 offset:32768
	ds_read_b32 v188, v208 offset:32772
	ds_read_b32 v183, v208 offset:49152
	ds_read_b32 v181, v210 offset:49152
	ds_read_b32 v189, v208 offset:49156
	ds_read_b32 v186, v208 offset:34816
	ds_read_b32 v184, v208 offset:34812
	ds_read_b32 v178, v208 offset:34820
	ds_read_b32 v187, v208 offset:51200
	ds_read_b32 v185, v208 offset:51196
	ds_read_b32 v179, v208 offset:51204
	s_waitcnt lgkmcnt(10)
	v_cndmask_b32_e64 v180, v180, 0, s[10:11]
	s_waitcnt lgkmcnt(7)
	v_cndmask_b32_e64 v181, v181, 0, s[10:11]
	v_pk_fma_f32 v[148:149], v[174:175], v[182:183], v[168:169] op_sel:[1,0,1]
	v_pk_fma_f32 v[148:149], v[174:175], v[180:181], v[148:149] op_sel_hi:[0,1,1]
	s_waitcnt lgkmcnt(6)
	v_pk_fma_f32 v[148:149], v[168:169], v[188:189], v[148:149] op_sel_hi:[0,1,1]
	s_waitcnt lgkmcnt(2)
	v_pk_fma_f32 v[150:151], v[174:175], v[186:187], v[168:169] op_sel:[1,0,1]
	s_waitcnt lgkmcnt(1)
	v_pk_fma_f32 v[150:151], v[174:175], v[184:185], v[150:151] op_sel_hi:[0,1,1]
	s_waitcnt lgkmcnt(0)
	v_pk_fma_f32 v[150:151], v[168:169], v[178:179], v[150:151] op_sel_hi:[0,1,1]
	ds_read_b32 v176, v208 offset:36864
	ds_read_b32 v166, v208 offset:36860
	ds_read_b32 v182, v208 offset:36868
	ds_read_b32 v177, v208 offset:53248
	ds_read_b32 v167, v208 offset:53244
	ds_read_b32 v183, v208 offset:53252
	ds_read_b32 v180, v208 offset:38912
	ds_read_b32 v188, v208 offset:38908
	ds_read_b32 v186, v208 offset:38916
	ds_read_b32 v181, v208 offset:55296
	ds_read_b32 v189, v208 offset:55292
	ds_read_b32 v187, v208 offset:55300
	s_waitcnt lgkmcnt(8)
	v_pk_fma_f32 v[152:153], v[174:175], v[176:177], v[168:169] op_sel:[1,0,1]
	s_waitcnt lgkmcnt(7)
	v_pk_fma_f32 v[152:153], v[174:175], v[166:167], v[152:153] op_sel_hi:[0,1,1]
	s_waitcnt lgkmcnt(6)
	v_pk_fma_f32 v[152:153], v[168:169], v[182:183], v[152:153] op_sel_hi:[0,1,1]
	s_waitcnt lgkmcnt(2)
	v_pk_fma_f32 v[154:155], v[174:175], v[180:181], v[168:169] op_sel:[1,0,1]
	s_waitcnt lgkmcnt(1)
	v_pk_fma_f32 v[154:155], v[174:175], v[188:189], v[154:155] op_sel_hi:[0,1,1]
	s_waitcnt lgkmcnt(0)
	v_pk_fma_f32 v[154:155], v[168:169], v[186:187], v[154:155] op_sel_hi:[0,1,1]
	ds_read_b32 v184, v208 offset:40960
	ds_read_b32 v178, v208 offset:40956
	ds_read_b32 v176, v208 offset:40964
	ds_read_b32 v185, v208 offset:57344
	ds_read_b32 v179, v208 offset:57340
	ds_read_b32 v177, v208 offset:57348
	ds_read_b32 v166, v208 offset:43008
	ds_read_b32 v182, v208 offset:43004
	ds_read_b32 v180, v208 offset:43012
	ds_read_b32 v167, v208 offset:59392
	ds_read_b32 v183, v208 offset:59388
	ds_read_b32 v181, v208 offset:59396
	s_waitcnt lgkmcnt(8)
	v_pk_fma_f32 v[158:159], v[174:175], v[184:185], v[168:169] op_sel:[1,0,1]
	s_waitcnt lgkmcnt(7)
	v_pk_fma_f32 v[158:159], v[174:175], v[178:179], v[158:159] op_sel_hi:[0,1,1]
	s_waitcnt lgkmcnt(6)
; #define LAS __attribute__((address_space(3)))
; __device__ __forceinline__ f32x2 cmul(f32x2 a, f32x2 b) { return (f32x2){a.x * b.x - a.y * b.y, a.x * b.y + a.y * b.x}; }
; template <int MODE> __device__ __forceinline__ void fft_pair32(LAS f32x2* B, const LAS f32x2* F, int wave, int lane) {
;     asm volatile("" : "+v"(lane));
;     constexpr float CS[16] = {1.f, 0.98078528040323043f, 0.92387953251128674f, 0.83146961230254524f, 0.70710678118654752f, 0.55557023301960218f, 0.38268343236508977f, 0.19509032201612825f,
;                               0.f, -0.19509032201612825f, -0.38268343236508977f, -0.55557023301960218f, -0.70710678118654752f, -0.83146961230254524f, -0.92387953251128674f, -0.98078528040323043f};
;     constexpr float SN[16] = {0.f, 0.19509032201612825f, 0.38268343236508977f, 0.55557023301960218f, 0.70710678118654752f, 0.83146961230254524f, 0.92387953251128674f, 0.98078528040323043f,
;                               1.f, 0.98078528040323043f, 0.92387953251128674f, 0.83146961230254524f, 0.70710678118654752f, 0.55557023301960218f, 0.38268343236508977f, 0.19509032201612825f};
;     const int hi = lane >> 5, blk = 32 * wave + (lane & 31); const float sg = hi ? -1.f : 1.f;
;     LAS f32x2* p = B + 33 * blk; f32x2 v[16];
; #pragma unroll
;     for (int j = 0; j < 16; ++j) { const f32x2 d = p[j] + p[j + 16] * sg;
;         const f32x2 w = {hi ? CS[j] : 1.f, hi ? -SN[j] : 0.f}; v[j] = j == 0 ? d : cmul(d, w); }
; __device__ __forceinline__ void hy_sconv(const LAS float* plane, float w0, float w1, float w2, float cb, int n2, float (&u)[8][2]) {
;     asm volatile("" : "+v"(n2));
; #pragma unroll
;     for (int r = 0; r < 8; ++r)
; #pragma unroll
;         for (int b = 0; b < 2; ++b) { const int t = n2 + 512 * r, row = b * SEQ + t;
;             float a = cb + w1 * plane[row];
;             if (t > 0) a += w0 * plane[row - 1];
;             if (t < SEQ - 1) a += w2 * plane[row + 1];
;             u[r][b] = a; }
; }
	v_pk_fma_f32 v[158:159], v[168:169], v[176:177], v[158:159] op_sel_hi:[0,1,1]
	s_waitcnt lgkmcnt(2)
	v_pk_fma_f32 v[160:161], v[174:175], v[166:167], v[168:169] op_sel:[1,0,1]
	s_waitcnt lgkmcnt(1)
	v_pk_fma_f32 v[160:161], v[174:175], v[182:183], v[160:161] op_sel_hi:[0,1,1]
	s_waitcnt lgkmcnt(0)
	v_pk_fma_f32 v[160:161], v[168:169], v[180:181], v[160:161] op_sel_hi:[0,1,1]
	ds_read_b32 v188, v208 offset:45056
	ds_read_b32 v186, v208 offset:45052
	ds_read_b32 v184, v208 offset:45060
	ds_read_b32 v189, v208 offset:61440
	ds_read_b32 v187, v208 offset:61436
	ds_read_b32 v185, v208 offset:61444
	ds_read_b32 v178, v208 offset:47104
	ds_read_b32 v176, v208 offset:47100
	ds_read_b32 v166, v208 offset:47108
	ds_read_b32 v179, v208 offset:63488
	ds_read_b32 v177, v208 offset:63484
	ds_read_b32 v167, v208 offset:63492
	s_waitcnt lgkmcnt(8)
	v_pk_fma_f32 v[162:163], v[174:175], v[188:189], v[168:169] op_sel:[1,0,1]
	s_waitcnt lgkmcnt(7)
	v_pk_fma_f32 v[162:163], v[174:175], v[186:187], v[162:163] op_sel_hi:[0,1,1]
	s_waitcnt lgkmcnt(6)
	v_pk_fma_f32 v[162:163], v[168:169], v[184:185], v[162:163] op_sel_hi:[0,1,1]
	s_waitcnt lgkmcnt(3)
	v_cndmask_b32_e64 v166, v166, 0, s[28:29]
	s_waitcnt lgkmcnt(0)
	v_cndmask_b32_e64 v167, v167, 0, s[28:29]
	v_pk_fma_f32 v[164:165], v[174:175], v[178:179], v[168:169] op_sel:[1,0,1]
	v_pk_fma_f32 v[164:165], v[174:175], v[176:177], v[164:165] op_sel_hi:[0,1,1]
	v_pk_fma_f32 v[164:165], v[168:169], v[166:167], v[164:165] op_sel_hi:[0,1,1]
	s_load_dword s17, s[60:61], 0x1000
	s_load_dword s23, s[60:61], 0x4000
	s_load_dword s25, s[60:61], 0x7000
	s_load_dword s26, s[62:63], 0x1000
	v_add_u32_e32 v65, 0x10800, v156
	v_add_u32_e32 v69, 0x10800, v196
	ds_read_b64 v[100:101], v65
	ds_read_b64 v[182:183], v65 offset:128
	ds_read_b64 v[102:103], v65 offset:8
	ds_read_b64 v[180:181], v65 offset:136
	ds_read_b64 v[104:105], v65 offset:16
	ds_read_b64 v[188:189], v65 offset:144
	ds_read_b64 v[106:107], v65 offset:24
	ds_read_b64 v[186:187], v65 offset:152
	s_waitcnt lgkmcnt(0)
	v_pk_fma_f32 v[100:101], v[182:183], v[190:191], v[100:101] op_sel_hi:[1,0,1]
	v_pk_fma_f32 v[102:103], v[180:181], v[190:191], v[102:103] op_sel_hi:[1,0,1]
	v_pk_mul_f32 v[184:185], v[102:103], v[36:37] op_sel:[1,1] op_sel_hi:[0,1]
	v_pk_fma_f32 v[102:103], v[102:103], v[36:37], v[184:185] op_sel_hi:[1,0,1] neg_lo:[0,0,1]
	v_pk_fma_f32 v[104:105], v[188:189], v[190:191], v[104:105] op_sel_hi:[1,0,1]
	v_pk_mul_f32 v[178:179], v[104:105], v[38:39] op_sel:[1,1] op_sel_hi:[0,1]
	v_pk_fma_f32 v[104:105], v[104:105], v[38:39], v[178:179] op_sel_hi:[1,0,1] neg_lo:[0,0,1]
	v_pk_fma_f32 v[106:107], v[186:187], v[190:191], v[106:107] op_sel_hi:[1,0,1]
	v_pk_mul_f32 v[176:177], v[106:107], v[40:41] op_sel:[1,1] op_sel_hi:[0,1]
	v_pk_fma_f32 v[106:107], v[106:107], v[40:41], v[176:177] op_sel_hi:[1,0,1] neg_lo:[0,0,1]
	ds_read_b64 v[108:109], v65 offset:32
	ds_read_b64 v[166:167], v65 offset:160
	ds_read_b64 v[110:111], v65 offset:40
	ds_read_b64 v[174:175], v65 offset:168
	ds_read_b64 v[112:113], v65 offset:48
	ds_read_b64 v[168:169], v65 offset:176
	ds_read_b64 v[114:115], v65 offset:56
	ds_read_b64 v[184:185], v65 offset:184
	s_waitcnt lgkmcnt(6)
	v_pk_fma_f32 v[108:109], v[166:167], v[190:191], v[108:109] op_sel_hi:[1,0,1]
	v_pk_mul_f32 v[178:179], v[108:109], v[42:43] op_sel:[1,1] op_sel_hi:[0,1]
	v_pk_fma_f32 v[108:109], v[108:109], v[42:43], v[178:179] op_sel_hi:[1,0,1] neg_lo:[0,0,1]
	s_waitcnt lgkmcnt(4)
	v_pk_fma_f32 v[110:111], v[174:175], v[190:191], v[110:111] op_sel_hi:[1,0,1]
	v_pk_mul_f32 v[176:177], v[110:111], v[44:45] op_sel:[1,1] op_sel_hi:[0,1]
	v_pk_fma_f32 v[110:111], v[110:111], v[44:45], v[176:177] op_sel_hi:[1,0,1] neg_lo:[0,0,1]
	s_waitcnt lgkmcnt(2)
	v_pk_fma_f32 v[112:113], v[168:169], v[190:191], v[112:113] op_sel_hi:[1,0,1]
	v_pk_mul_f32 v[182:183], v[112:113], v[46:47] op_sel:[1,1] op_sel_hi:[0,1]
	v_pk_fma_f32 v[112:113], v[112:113], v[46:47], v[182:183] op_sel_hi:[1,0,1] neg_lo:[0,0,1]
	s_waitcnt lgkmcnt(0)
	v_pk_fma_f32 v[114:115], v[184:185], v[190:191], v[114:115] op_sel_hi:[1,0,1]
	v_pk_mul_f32 v[180:181], v[114:115], v[48:49] op_sel:[1,1] op_sel_hi:[0,1]
	v_pk_fma_f32 v[114:115], v[114:115], v[48:49], v[180:181] op_sel_hi:[1,0,1] neg_lo:[0,0,1]
	ds_read_b64 v[116:117], v65 offset:64
	ds_read_b64 v[188:189], v65 offset:192
	ds_read_b64 v[118:119], v65 offset:72
	ds_read_b64 v[186:187], v65 offset:200
	ds_read_b64 v[120:121], v65 offset:80
	ds_read_b64 v[178:179], v65 offset:208
	ds_read_b64 v[122:123], v65 offset:88
	ds_read_b64 v[176:177], v65 offset:216
	s_waitcnt lgkmcnt(6)
	v_pk_fma_f32 v[116:117], v[188:189], v[190:191], v[116:117] op_sel_hi:[1,0,1]
	v_pk_mul_f32 v[182:183], v[116:117], v[50:51] op_sel:[1,1] op_sel_hi:[0,1]
	v_pk_fma_f32 v[116:117], v[116:117], v[50:51], v[182:183] op_sel_hi:[1,0,1] neg_lo:[0,0,1]
	s_waitcnt lgkmcnt(4)
	v_pk_fma_f32 v[118:119], v[186:187], v[190:191], v[118:119] op_sel_hi:[1,0,1]
	v_pk_mul_f32 v[180:181], v[118:119], v[52:53] op_sel:[1,1] op_sel_hi:[0,1]
	v_pk_fma_f32 v[118:119], v[118:119], v[52:53], v[180:181] op_sel_hi:[1,0,1] neg_lo:[0,0,1]
	s_waitcnt lgkmcnt(2)
	v_pk_fma_f32 v[120:121], v[178:179], v[190:191], v[120:121] op_sel_hi:[1,0,1]
	v_pk_mul_f32 v[166:167], v[120:121], v[54:55] op_sel:[1,1] op_sel_hi:[0,1]
	v_pk_fma_f32 v[120:121], v[120:121], v[54:55], v[166:167] op_sel_hi:[1,0,1] neg_lo:[0,0,1]
	s_waitcnt lgkmcnt(0)
; #define LAS __attribute__((address_space(3)))
; template <bool INV> __device__ __forceinline__ void dft16(f32x2 (&x)[16]) {
;     constexpr float C1 = 0.92387953251128674f, S1 = 0.38268343236508977f, C2 = 0.70710678118654752f;
; #pragma unroll
;     for (int b = 0; b < 4; ++b) dft4<INV>(x[b], x[4 + b], x[8 + b], x[12 + b]);
;     const f32x2 w1 = {C1, -S1}, w2 = {C2, -C2}, w3 = {S1, -C1}, w4 = {0.f, -1.f}, w6 = {-C2, -C2}, w9 = {-C1, S1};
;     x[4 * 1 + 1] = cmul_tw<INV>(x[5], w1); x[4 * 1 + 2] = cmul_tw<INV>(x[6], w2); x[4 * 1 + 3] = cmul_tw<INV>(x[7], w3);
;     x[4 * 2 + 1] = cmul_tw<INV>(x[9], w2); x[4 * 2 + 2] = cmul_tw<INV>(x[10], w4); x[4 * 2 + 3] = cmul_tw<INV>(x[11], w6);
;     x[4 * 3 + 1] = cmul_tw<INV>(x[13], w3); x[4 * 3 + 2] = cmul_tw<INV>(x[14], w6); x[4 * 3 + 3] = cmul_tw<INV>(x[15], w9);
; #pragma unroll
;     for (int c = 0; c < 4; ++c) dft4<INV>(x[4 * c], x[4 * c + 1], x[4 * c + 2], x[4 * c + 3]);
;     f32x2 y[16];
; #pragma unroll
;     for (int k = 0; k < 16; ++k) y[k] = x[4 * (k & 3) + (k >> 2)];
; #pragma unroll
;     for (int k = 0; k < 16; ++k) x[k] = y[k];
; template <int MODE> __device__ __forceinline__ void fft_pair32(LAS f32x2* B, const LAS f32x2* F, int wave, int lane) {
;     asm volatile("" : "+v"(lane));
;     constexpr float CS[16] = {1.f, 0.98078528040323043f, 0.92387953251128674f, 0.83146961230254524f, 0.70710678118654752f, 0.55557023301960218f, 0.38268343236508977f, 0.19509032201612825f,
;                               0.f, -0.19509032201612825f, -0.38268343236508977f, -0.55557023301960218f, -0.70710678118654752f, -0.83146961230254524f, -0.92387953251128674f, -0.98078528040323043f};
;     constexpr float SN[16] = {0.f, 0.19509032201612825f, 0.38268343236508977f, 0.55557023301960218f, 0.70710678118654752f, 0.83146961230254524f, 0.92387953251128674f, 0.98078528040323043f,
;                               1.f, 0.98078528040323043f, 0.92387953251128674f, 0.83146961230254524f, 0.70710678118654752f, 0.55557023301960218f, 0.38268343236508977f, 0.19509032201612825f};
;     const int hi = lane >> 5, blk = 32 * wave + (lane & 31); const float sg = hi ? -1.f : 1.f;
;     LAS f32x2* p = B + 33 * blk; f32x2 v[16];
; #pragma unroll
;     for (int j = 0; j < 16; ++j) { const f32x2 d = p[j] + p[j + 16] * sg;
;         const f32x2 w = {hi ? CS[j] : 1.f, hi ? -SN[j] : 0.f}; v[j] = j == 0 ? d : cmul(d, w); }
;     dft16<false>(v);
	v_pk_fma_f32 v[122:123], v[176:177], v[190:191], v[122:123] op_sel_hi:[1,0,1]
	v_pk_mul_f32 v[174:175], v[122:123], v[90:91] op_sel:[1,1] op_sel_hi:[0,1]
	v_pk_fma_f32 v[122:123], v[122:123], v[90:91], v[174:175] op_sel_hi:[1,0,1] neg_lo:[0,0,1]
	ds_read_b64 v[124:125], v65 offset:96
	ds_read_b64 v[168:169], v65 offset:224
	ds_read_b64 v[126:127], v65 offset:104
	ds_read_b64 v[184:185], v65 offset:232
	ds_read_b64 v[128:129], v65 offset:112
	ds_read_b64 v[182:183], v65 offset:240
	ds_read_b64 v[130:131], v65 offset:120
	ds_read_b64 v[180:181], v65 offset:248
	s_waitcnt lgkmcnt(6)
	v_pk_fma_f32 v[124:125], v[168:169], v[190:191], v[124:125] op_sel_hi:[1,0,1]
	v_pk_mul_f32 v[166:167], v[124:125], v[92:93] op_sel:[1,1] op_sel_hi:[0,1]
	v_pk_fma_f32 v[124:125], v[124:125], v[92:93], v[166:167] op_sel_hi:[1,0,1] neg_lo:[0,0,1]
	s_waitcnt lgkmcnt(4)
	v_pk_fma_f32 v[126:127], v[184:185], v[190:191], v[126:127] op_sel_hi:[1,0,1]
	v_pk_mul_f32 v[174:175], v[126:127], v[94:95] op_sel:[1,1] op_sel_hi:[0,1]
	v_pk_fma_f32 v[126:127], v[126:127], v[94:95], v[174:175] op_sel_hi:[1,0,1] neg_lo:[0,0,1]
	s_waitcnt lgkmcnt(2)
	v_pk_fma_f32 v[128:129], v[182:183], v[190:191], v[128:129] op_sel_hi:[1,0,1]
	v_pk_mul_f32 v[188:189], v[128:129], v[96:97] op_sel:[1,1] op_sel_hi:[0,1]
	v_pk_fma_f32 v[128:129], v[128:129], v[96:97], v[188:189] op_sel_hi:[1,0,1] neg_lo:[0,0,1]
	s_waitcnt lgkmcnt(0)
	v_pk_fma_f32 v[130:131], v[180:181], v[190:191], v[130:131] op_sel_hi:[1,0,1]
	v_pk_mul_f32 v[186:187], v[130:131], v[98:99] op_sel:[1,1] op_sel_hi:[0,1]
	v_pk_fma_f32 v[130:131], v[130:131], v[98:99], v[186:187] op_sel_hi:[1,0,1] neg_lo:[0,0,1]
	v_pk_add_f32 v[178:179], v[100:101], v[116:117]
	v_pk_add_f32 v[176:177], v[100:101], v[116:117] neg_lo:[0,1] neg_hi:[0,1]
	v_pk_add_f32 v[166:167], v[108:109], v[124:125]
	v_pk_add_f32 v[174:175], v[108:109], v[124:125] neg_lo:[0,1] neg_hi:[0,1]
	v_pk_add_f32 v[100:101], v[178:179], v[166:167]
	v_pk_add_f32 v[116:117], v[178:179], v[166:167] neg_lo:[0,1] neg_hi:[0,1]
	v_pk_add_f32 v[108:109], v[176:177], v[174:175] op_sel:[0,1] op_sel_hi:[1,0] neg_hi:[0,1]
	v_pk_add_f32 v[124:125], v[176:177], v[174:175] op_sel:[0,1] op_sel_hi:[1,0] neg_lo:[0,1]
	v_pk_add_f32 v[188:189], v[102:103], v[118:119]
	v_pk_add_f32 v[186:187], v[102:103], v[118:119] neg_lo:[0,1] neg_hi:[0,1]
	v_pk_add_f32 v[168:169], v[110:111], v[126:127]
	v_pk_add_f32 v[184:185], v[110:111], v[126:127] neg_lo:[0,1] neg_hi:[0,1]
	v_pk_add_f32 v[102:103], v[188:189], v[168:169]
	v_pk_add_f32 v[118:119], v[188:189], v[168:169] neg_lo:[0,1] neg_hi:[0,1]
	v_pk_add_f32 v[110:111], v[186:187], v[184:185] op_sel:[0,1] op_sel_hi:[1,0] neg_hi:[0,1]
	v_pk_add_f32 v[126:127], v[186:187], v[184:185] op_sel:[0,1] op_sel_hi:[1,0] neg_lo:[0,1]
	v_pk_add_f32 v[182:183], v[104:105], v[120:121]
	v_pk_add_f32 v[180:181], v[104:105], v[120:121] neg_lo:[0,1] neg_hi:[0,1]
	v_pk_add_f32 v[178:179], v[112:113], v[128:129]
	v_pk_add_f32 v[176:177], v[112:113], v[128:129] neg_lo:[0,1] neg_hi:[0,1]
	v_pk_add_f32 v[104:105], v[182:183], v[178:179]
	v_pk_add_f32 v[120:121], v[182:183], v[178:179] neg_lo:[0,1] neg_hi:[0,1]
	v_pk_add_f32 v[112:113], v[180:181], v[176:177] op_sel:[0,1] op_sel_hi:[1,0] neg_hi:[0,1]
	v_pk_add_f32 v[128:129], v[180:181], v[176:177] op_sel:[0,1] op_sel_hi:[1,0] neg_lo:[0,1]
	v_pk_add_f32 v[166:167], v[106:107], v[122:123]
	v_pk_add_f32 v[174:175], v[106:107], v[122:123] neg_lo:[0,1] neg_hi:[0,1]
	v_pk_add_f32 v[188:189], v[114:115], v[130:131]
	v_pk_add_f32 v[186:187], v[114:115], v[130:131] neg_lo:[0,1] neg_hi:[0,1]
	v_pk_add_f32 v[106:107], v[166:167], v[188:189]
	v_pk_add_f32 v[122:123], v[166:167], v[188:189] neg_lo:[0,1] neg_hi:[0,1]
	v_pk_add_f32 v[114:115], v[174:175], v[186:187] op_sel:[0,1] op_sel_hi:[1,0] neg_hi:[0,1]
	v_pk_add_f32 v[130:131], v[174:175], v[186:187] op_sel:[0,1] op_sel_hi:[1,0] neg_lo:[0,1]
	v_pk_mul_f32 v[168:169], v[110:111], s[68:69] op_sel:[1,1] op_sel_hi:[0,1]
	v_pk_fma_f32 v[110:111], v[110:111], s[68:69], v[168:169] op_sel_hi:[1,0,1] neg_lo:[0,0,1]
	v_pk_mul_f32 v[184:185], v[112:113], s[84:85] op_sel:[1,1] op_sel_hi:[0,1]
	v_pk_fma_f32 v[112:113], v[112:113], s[84:85], v[184:185] op_sel_hi:[1,0,1] neg_lo:[0,0,1]
	v_pk_mul_f32 v[182:183], v[114:115], s[88:89] op_sel:[1,1] op_sel_hi:[0,1]
	v_pk_fma_f32 v[114:115], v[114:115], s[88:89], v[182:183] op_sel_hi:[1,0,1] neg_lo:[0,0,1]
	v_pk_mul_f32 v[180:181], v[118:119], s[84:85] op_sel:[1,1] op_sel_hi:[0,1]
	v_pk_fma_f32 v[118:119], v[118:119], s[84:85], v[180:181] op_sel_hi:[1,0,1] neg_lo:[0,0,1]
	v_pk_mul_f32 v[178:179], v[122:123], s[90:91] op_sel:[1,1] op_sel_hi:[0,1]
	v_pk_fma_f32 v[122:123], v[122:123], s[90:91], v[178:179] op_sel_hi:[1,0,1] neg_lo:[0,0,1]
	v_pk_mul_f32 v[176:177], v[126:127], s[88:89] op_sel:[1,1] op_sel_hi:[0,1]
	v_pk_fma_f32 v[126:127], v[126:127], s[88:89], v[176:177] op_sel_hi:[1,0,1] neg_lo:[0,0,1]
	v_pk_mul_f32 v[166:167], v[128:129], s[90:91] op_sel:[1,1] op_sel_hi:[0,1]
	v_pk_fma_f32 v[128:129], v[128:129], s[90:91], v[166:167] op_sel_hi:[1,0,1] neg_lo:[0,0,1]
	v_pk_mul_f32 v[174:175], v[130:131], s[98:99] op_sel:[1,1] op_sel_hi:[0,1]
	v_pk_fma_f32 v[130:131], v[130:131], s[98:99], v[174:175] op_sel_hi:[1,0,1] neg_lo:[0,0,1]
	v_pk_add_f32 v[188:189], v[100:101], v[104:105]
	v_pk_add_f32 v[186:187], v[100:101], v[104:105] neg_lo:[0,1] neg_hi:[0,1]
	v_pk_add_f32 v[168:169], v[102:103], v[106:107]
	v_pk_add_f32 v[184:185], v[102:103], v[106:107] neg_lo:[0,1] neg_hi:[0,1]
	v_pk_add_f32 v[100:101], v[188:189], v[168:169]
	v_pk_add_f32 v[104:105], v[188:189], v[168:169] neg_lo:[0,1] neg_hi:[0,1]
	v_pk_add_f32 v[102:103], v[186:187], v[184:185] op_sel:[0,1] op_sel_hi:[1,0] neg_hi:[0,1]
; __device__ __forceinline__ f32x2 cmul(f32x2 a, f32x2 b) { return (f32x2){a.x * b.x - a.y * b.y, a.x * b.y + a.y * b.x}; }
; #define WG_SYNC() do { asm volatile("s_waitcnt lgkmcnt(0)" ::: "memory"); __builtin_amdgcn_s_barrier(); asm volatile("" ::: "memory"); } while (0)
; #define WAVE_FENCE() do { asm volatile("s_waitcnt lgkmcnt(0)" ::: "memory"); __builtin_amdgcn_sched_barrier(0); } while (0)
; __device__ __forceinline__ void dft16_fwd_lo(f32x2 (&x)[16]) {
;     constexpr float C1 = 0.92387953251128674f, S1 = 0.38268343236508977f, C2 = 0.70710678118654752f;
; #pragma unroll
;     for (int b = 0; b < 4; ++b) { const f32x2 x0 = x[b], x1 = x[4 + b]; const f32x2 j1 = {x1.y, -x1.x};
;         x[b] = x0 + x1; x[4 + b] = x0 + j1; x[8 + b] = x0 - x1; x[12 + b] = x0 - j1; }
;     const f32x2 w1 = {C1, -S1}, w2 = {C2, -C2}, w3 = {S1, -C1}, w4 = {0.f, -1.f}, w6 = {-C2, -C2}, w9 = {-C1, S1};
;     x[5] = cmul(x[5], w1); x[6] = cmul(x[6], w2); x[7] = cmul(x[7], w3);
;     x[9] = cmul(x[9], w2); x[10] = cmul(x[10], w4); x[11] = cmul(x[11], w6);
;     x[13] = cmul(x[13], w3); x[14] = cmul(x[14], w6); x[15] = cmul(x[15], w9);
; __device__ __forceinline__ void hyena_fft(LAS unsigned char* lds, int layer, int G, const int wave_s) {
;     ...
;             fft_fwd2(Fb, TW2, tid); WAVE_FENCE(); fft_pair32<2>(Fb, Fb, wave, lane); __builtin_amdgcn_sched_barrier(0);
;             WG_SYNC();
;             f32x2 x[16];
; #pragma unroll
;             for (int r = 0; r < 8; ++r) { x[r] = (f32x2){uz[r][0], uz[r][1]}; x[r + 8] = (f32x2){0.f, 0.f}; }
;             fft_fwd1<true>(x, Db, n2, w1p); WG_SYNC();
	v_pk_add_f32 v[106:107], v[186:187], v[184:185] op_sel:[0,1] op_sel_hi:[1,0] neg_lo:[0,1]
	v_pk_add_f32 v[182:183], v[108:109], v[112:113]
	v_pk_add_f32 v[180:181], v[108:109], v[112:113] neg_lo:[0,1] neg_hi:[0,1]
	v_pk_add_f32 v[178:179], v[110:111], v[114:115]
	v_pk_add_f32 v[176:177], v[110:111], v[114:115] neg_lo:[0,1] neg_hi:[0,1]
	v_pk_add_f32 v[108:109], v[182:183], v[178:179]
	v_pk_add_f32 v[112:113], v[182:183], v[178:179] neg_lo:[0,1] neg_hi:[0,1]
	v_pk_add_f32 v[110:111], v[180:181], v[176:177] op_sel:[0,1] op_sel_hi:[1,0] neg_hi:[0,1]
	v_pk_add_f32 v[114:115], v[180:181], v[176:177] op_sel:[0,1] op_sel_hi:[1,0] neg_lo:[0,1]
	v_pk_add_f32 v[166:167], v[116:117], v[120:121] op_sel:[0,1] op_sel_hi:[1,0] neg_hi:[0,1]
	v_pk_add_f32 v[174:175], v[116:117], v[120:121] op_sel:[0,1] op_sel_hi:[1,0] neg_lo:[0,1]
	v_pk_add_f32 v[188:189], v[118:119], v[122:123]
	v_pk_add_f32 v[186:187], v[118:119], v[122:123] neg_lo:[0,1] neg_hi:[0,1]
	v_pk_add_f32 v[116:117], v[166:167], v[188:189]
	v_pk_add_f32 v[120:121], v[166:167], v[188:189] neg_lo:[0,1] neg_hi:[0,1]
	v_pk_add_f32 v[118:119], v[174:175], v[186:187] op_sel:[0,1] op_sel_hi:[1,0] neg_hi:[0,1]
	v_pk_add_f32 v[122:123], v[174:175], v[186:187] op_sel:[0,1] op_sel_hi:[1,0] neg_lo:[0,1]
	v_pk_add_f32 v[168:169], v[124:125], v[128:129]
	v_pk_add_f32 v[184:185], v[124:125], v[128:129] neg_lo:[0,1] neg_hi:[0,1]
	v_pk_add_f32 v[182:183], v[126:127], v[130:131]
	v_pk_add_f32 v[180:181], v[126:127], v[130:131] neg_lo:[0,1] neg_hi:[0,1]
	v_pk_add_f32 v[124:125], v[168:169], v[182:183]
	v_pk_add_f32 v[128:129], v[168:169], v[182:183] neg_lo:[0,1] neg_hi:[0,1]
	v_pk_add_f32 v[126:127], v[184:185], v[180:181] op_sel:[0,1] op_sel_hi:[1,0] neg_hi:[0,1]
	v_pk_add_f32 v[130:131], v[184:185], v[180:181] op_sel:[0,1] op_sel_hi:[1,0] neg_lo:[0,1]
	v_pk_mul_f32 v[100:101], v[100:101], v[192:193] op_sel_hi:[1,0]
	ds_write_b64 v69, v[100:101]
	v_pk_mul_f32 v[108:109], v[108:109], v[192:193] op_sel_hi:[1,0]
	ds_write_b64 v69, v[108:109] offset:16
	v_pk_mul_f32 v[116:117], v[116:117], v[192:193] op_sel_hi:[1,0]
	ds_write_b64 v69, v[116:117] offset:32
	v_pk_mul_f32 v[124:125], v[124:125], v[192:193] op_sel_hi:[1,0]
	ds_write_b64 v69, v[124:125] offset:48
	v_pk_mul_f32 v[102:103], v[102:103], v[192:193] op_sel_hi:[1,0]
	ds_write_b64 v69, v[102:103] offset:64
	v_pk_mul_f32 v[110:111], v[110:111], v[192:193] op_sel_hi:[1,0]
	ds_write_b64 v69, v[110:111] offset:80
	v_pk_mul_f32 v[118:119], v[118:119], v[192:193] op_sel_hi:[1,0]
	ds_write_b64 v69, v[118:119] offset:96
	v_pk_mul_f32 v[126:127], v[126:127], v[192:193] op_sel_hi:[1,0]
	ds_write_b64 v69, v[126:127] offset:112
	v_pk_mul_f32 v[104:105], v[104:105], v[192:193] op_sel_hi:[1,0]
	ds_write_b64 v69, v[104:105] offset:128
	v_pk_mul_f32 v[112:113], v[112:113], v[192:193] op_sel_hi:[1,0]
	ds_write_b64 v69, v[112:113] offset:144
	v_pk_mul_f32 v[120:121], v[120:121], v[192:193] op_sel_hi:[1,0]
	ds_write_b64 v69, v[120:121] offset:160
	v_pk_mul_f32 v[128:129], v[128:129], v[192:193] op_sel_hi:[1,0]
	ds_write_b64 v69, v[128:129] offset:176
	v_pk_mul_f32 v[106:107], v[106:107], v[192:193] op_sel_hi:[1,0]
	ds_write_b64 v69, v[106:107] offset:192
	v_pk_mul_f32 v[114:115], v[114:115], v[192:193] op_sel_hi:[1,0]
	ds_write_b64 v69, v[114:115] offset:208
	v_pk_mul_f32 v[122:123], v[122:123], v[192:193] op_sel_hi:[1,0]
	ds_write_b64 v69, v[122:123] offset:224
	v_pk_mul_f32 v[130:131], v[130:131], v[192:193] op_sel_hi:[1,0]
	ds_write_b64 v69, v[130:131] offset:240
	s_waitcnt lgkmcnt(0)
	s_barrier
	v_pk_add_f32 v[104:105], v[132:133], v[140:141] neg_lo:[0,1] neg_hi:[0,1]
	v_pk_add_f32 v[106:107], v[132:133], v[140:141] op_sel:[0,1] op_sel_hi:[1,0] neg_lo:[0,1]
	v_pk_add_f32 v[178:179], v[132:133], v[140:141] op_sel:[0,1] op_sel_hi:[1,0] neg_hi:[0,1]
	v_pk_add_f32 v[100:101], v[132:133], v[140:141]
	v_pk_add_f32 v[112:113], v[134:135], v[142:143] neg_lo:[0,1] neg_hi:[0,1]
	v_pk_add_f32 v[114:115], v[134:135], v[142:143] op_sel:[0,1] op_sel_hi:[1,0] neg_lo:[0,1]
	v_pk_add_f32 v[176:177], v[134:135], v[142:143] op_sel:[0,1] op_sel_hi:[1,0] neg_hi:[0,1]
	v_pk_add_f32 v[108:109], v[134:135], v[142:143]
	v_pk_add_f32 v[120:121], v[136:137], v[144:145] neg_lo:[0,1] neg_hi:[0,1]
	v_pk_add_f32 v[122:123], v[136:137], v[144:145] op_sel:[0,1] op_sel_hi:[1,0] neg_lo:[0,1]
	v_pk_add_f32 v[166:167], v[136:137], v[144:145] op_sel:[0,1] op_sel_hi:[1,0] neg_hi:[0,1]
	v_pk_add_f32 v[116:117], v[136:137], v[144:145]
	v_pk_add_f32 v[128:129], v[138:139], v[146:147] neg_lo:[0,1] neg_hi:[0,1]
	v_pk_add_f32 v[130:131], v[138:139], v[146:147] op_sel:[0,1] op_sel_hi:[1,0] neg_lo:[0,1]
	v_pk_add_f32 v[174:175], v[138:139], v[146:147] op_sel:[0,1] op_sel_hi:[1,0] neg_hi:[0,1]
	v_pk_add_f32 v[124:125], v[138:139], v[146:147]
	v_pk_mul_f32 v[188:189], v[176:177], s[68:69] op_sel:[1,1] op_sel_hi:[0,1]
	v_pk_fma_f32 v[176:177], v[176:177], s[68:69], v[188:189] op_sel_hi:[1,0,1] neg_lo:[0,0,1]
	v_pk_mul_f32 v[186:187], v[166:167], s[84:85] op_sel:[1,1] op_sel_hi:[0,1]
	v_pk_fma_f32 v[166:167], v[166:167], s[84:85], v[186:187] op_sel_hi:[1,0,1] neg_lo:[0,0,1]
	v_pk_mul_f32 v[168:169], v[174:175], s[88:89] op_sel:[1,1] op_sel_hi:[0,1]
	v_pk_fma_f32 v[174:175], v[174:175], s[88:89], v[168:169] op_sel_hi:[1,0,1] neg_lo:[0,0,1]
	v_pk_mul_f32 v[184:185], v[112:113], s[84:85] op_sel:[1,1] op_sel_hi:[0,1]
	v_pk_fma_f32 v[112:113], v[112:113], s[84:85], v[184:185] op_sel_hi:[1,0,1] neg_lo:[0,0,1]
	v_pk_mul_f32 v[182:183], v[128:129], s[90:91] op_sel:[1,1] op_sel_hi:[0,1]
	v_pk_fma_f32 v[128:129], v[128:129], s[90:91], v[182:183] op_sel_hi:[1,0,1] neg_lo:[0,0,1]
	v_pk_mul_f32 v[180:181], v[114:115], s[88:89] op_sel:[1,1] op_sel_hi:[0,1]
; #define LAS __attribute__((address_space(3)))
; __device__ __forceinline__ f32x2 cmul(f32x2 a, f32x2 b) { return (f32x2){a.x * b.x - a.y * b.y, a.x * b.y + a.y * b.x}; }
; __device__ __forceinline__ void dft16_fwd_lo(f32x2 (&x)[16]) {
;     ...
;     const f32x2 w1 = {C1, -S1}, w2 = {C2, -C2}, w3 = {S1, -C1}, w4 = {0.f, -1.f}, w6 = {-C2, -C2}, w9 = {-C1, S1};
;     x[5] = cmul(x[5], w1); x[6] = cmul(x[6], w2); x[7] = cmul(x[7], w3);
;     x[9] = cmul(x[9], w2); x[10] = cmul(x[10], w4); x[11] = cmul(x[11], w6);
;     x[13] = cmul(x[13], w3); x[14] = cmul(x[14], w6); x[15] = cmul(x[15], w9);
; #pragma unroll
;     for (int c = 0; c < 4; ++c) dft4<false>(x[4 * c], x[4 * c + 1], x[4 * c + 2], x[4 * c + 3]);
;     f32x2 y[16];
; #pragma unroll
;     for (int k = 0; k < 16; ++k) y[k] = x[4 * (k & 3) + (k >> 2)];
; #pragma unroll
;     for (int k = 0; k < 16; ++k) x[k] = y[k];
; template <bool LO> __device__ __forceinline__ void fft_fwd1(f32x2 (&x)[16], LAS f32x2* B, int n2, const f32x2 (&w)[16]) {
;     asm volatile("" : "+v"(n2));
;     if (LO) dft16_fwd_lo(x); else dft16<false>(x);
;     B[fpad(n2)] = x[0];
; #pragma unroll
;     for (int k = 1; k < 16; ++k) B[fpad(512 * k + n2)] = cmul(x[k], w[k]);
; }
	v_pk_fma_f32 v[114:115], v[114:115], s[88:89], v[180:181] op_sel_hi:[1,0,1] neg_lo:[0,0,1]
	v_pk_mul_f32 v[102:103], v[122:123], s[90:91] op_sel:[1,1] op_sel_hi:[0,1]
	v_pk_fma_f32 v[122:123], v[122:123], s[90:91], v[102:103] op_sel_hi:[1,0,1] neg_lo:[0,0,1]
	v_pk_mul_f32 v[110:111], v[130:131], s[98:99] op_sel:[1,1] op_sel_hi:[0,1]
	v_pk_fma_f32 v[130:131], v[130:131], s[98:99], v[110:111] op_sel_hi:[1,0,1] neg_lo:[0,0,1]
	v_pk_add_f32 v[118:119], v[100:101], v[116:117]
	v_pk_add_f32 v[126:127], v[100:101], v[116:117] neg_lo:[0,1] neg_hi:[0,1]
	v_pk_add_f32 v[188:189], v[108:109], v[124:125]
	v_pk_add_f32 v[186:187], v[108:109], v[124:125] neg_lo:[0,1] neg_hi:[0,1]
	v_pk_add_f32 v[100:101], v[118:119], v[188:189]
	v_pk_add_f32 v[116:117], v[118:119], v[188:189] neg_lo:[0,1] neg_hi:[0,1]
	v_pk_add_f32 v[108:109], v[126:127], v[186:187] op_sel:[0,1] op_sel_hi:[1,0] neg_hi:[0,1]
	v_pk_add_f32 v[124:125], v[126:127], v[186:187] op_sel:[0,1] op_sel_hi:[1,0] neg_lo:[0,1]
	v_pk_add_f32 v[168:169], v[178:179], v[166:167]
	v_pk_add_f32 v[184:185], v[178:179], v[166:167] neg_lo:[0,1] neg_hi:[0,1]
	v_pk_add_f32 v[182:183], v[176:177], v[174:175]
	v_pk_add_f32 v[180:181], v[176:177], v[174:175] neg_lo:[0,1] neg_hi:[0,1]
	v_pk_add_f32 v[178:179], v[168:169], v[182:183]
	v_pk_add_f32 v[166:167], v[168:169], v[182:183] neg_lo:[0,1] neg_hi:[0,1]
	v_pk_add_f32 v[176:177], v[184:185], v[180:181] op_sel:[0,1] op_sel_hi:[1,0] neg_hi:[0,1]
	v_pk_add_f32 v[174:175], v[184:185], v[180:181] op_sel:[0,1] op_sel_hi:[1,0] neg_lo:[0,1]
	v_pk_add_f32 v[102:103], v[104:105], v[120:121] op_sel:[0,1] op_sel_hi:[1,0] neg_hi:[0,1]
	v_pk_add_f32 v[110:111], v[104:105], v[120:121] op_sel:[0,1] op_sel_hi:[1,0] neg_lo:[0,1]
	v_pk_add_f32 v[118:119], v[112:113], v[128:129]
	v_pk_add_f32 v[126:127], v[112:113], v[128:129] neg_lo:[0,1] neg_hi:[0,1]
	v_pk_add_f32 v[104:105], v[102:103], v[118:119]
	v_pk_add_f32 v[120:121], v[102:103], v[118:119] neg_lo:[0,1] neg_hi:[0,1]
	v_pk_add_f32 v[112:113], v[110:111], v[126:127] op_sel:[0,1] op_sel_hi:[1,0] neg_hi:[0,1]
	v_pk_add_f32 v[128:129], v[110:111], v[126:127] op_sel:[0,1] op_sel_hi:[1,0] neg_lo:[0,1]
	v_pk_add_f32 v[188:189], v[106:107], v[122:123]
	v_pk_add_f32 v[186:187], v[106:107], v[122:123] neg_lo:[0,1] neg_hi:[0,1]
	v_pk_add_f32 v[168:169], v[114:115], v[130:131]
	v_pk_add_f32 v[184:185], v[114:115], v[130:131] neg_lo:[0,1] neg_hi:[0,1]
	v_pk_add_f32 v[106:107], v[188:189], v[168:169]
	v_pk_add_f32 v[122:123], v[188:189], v[168:169] neg_lo:[0,1] neg_hi:[0,1]
	v_pk_add_f32 v[114:115], v[186:187], v[184:185] op_sel:[0,1] op_sel_hi:[1,0] neg_hi:[0,1]
	v_pk_add_f32 v[130:131], v[186:187], v[184:185] op_sel:[0,1] op_sel_hi:[1,0] neg_lo:[0,1]
	ds_write_b64 v3, v[100:101]
	v_pk_mul_f32 v[180:181], v[178:179], v[6:7] op_sel:[1,1] op_sel_hi:[0,1]
	v_pk_fma_f32 v[182:183], v[178:179], v[6:7], v[180:181] op_sel_hi:[1,0,1] neg_lo:[0,0,1]
	ds_write_b64 v3, v[182:183] offset:4224
	v_pk_mul_f32 v[110:111], v[104:105], v[8:9] op_sel:[1,1] op_sel_hi:[0,1]
	v_pk_fma_f32 v[102:103], v[104:105], v[8:9], v[110:111] op_sel_hi:[1,0,1] neg_lo:[0,0,1]
	ds_write_b64 v3, v[102:103] offset:8448
	v_pk_mul_f32 v[126:127], v[106:107], v[10:11] op_sel:[1,1] op_sel_hi:[0,1]
	v_pk_fma_f32 v[118:119], v[106:107], v[10:11], v[126:127] op_sel_hi:[1,0,1] neg_lo:[0,0,1]
	ds_write_b64 v3, v[118:119] offset:12672
	v_pk_mul_f32 v[186:187], v[108:109], v[12:13] op_sel:[1,1] op_sel_hi:[0,1]
	v_pk_fma_f32 v[188:189], v[108:109], v[12:13], v[186:187] op_sel_hi:[1,0,1] neg_lo:[0,0,1]
	ds_write_b64 v3, v[188:189] offset:16896
	v_pk_mul_f32 v[184:185], v[176:177], v[14:15] op_sel:[1,1] op_sel_hi:[0,1]
	v_pk_fma_f32 v[168:169], v[176:177], v[14:15], v[184:185] op_sel_hi:[1,0,1] neg_lo:[0,0,1]
	ds_write_b64 v3, v[168:169] offset:21120
	v_pk_mul_f32 v[182:183], v[112:113], v[16:17] op_sel:[1,1] op_sel_hi:[0,1]
	v_pk_fma_f32 v[180:181], v[112:113], v[16:17], v[182:183] op_sel_hi:[1,0,1] neg_lo:[0,0,1]
	ds_write_b64 v3, v[180:181] offset:25344
	v_pk_mul_f32 v[102:103], v[114:115], v[18:19] op_sel:[1,1] op_sel_hi:[0,1]
	v_pk_fma_f32 v[110:111], v[114:115], v[18:19], v[102:103] op_sel_hi:[1,0,1] neg_lo:[0,0,1]
	ds_write_b64 v3, v[110:111] offset:29568
	v_pk_mul_f32 v[118:119], v[116:117], v[20:21] op_sel:[1,1] op_sel_hi:[0,1]
	v_pk_fma_f32 v[126:127], v[116:117], v[20:21], v[118:119] op_sel_hi:[1,0,1] neg_lo:[0,0,1]
	ds_write_b64 v3, v[126:127] offset:33792
	v_pk_mul_f32 v[188:189], v[166:167], v[22:23] op_sel:[1,1] op_sel_hi:[0,1]
	v_pk_fma_f32 v[186:187], v[166:167], v[22:23], v[188:189] op_sel_hi:[1,0,1] neg_lo:[0,0,1]
	ds_write_b64 v3, v[186:187] offset:38016
	v_pk_mul_f32 v[168:169], v[120:121], v[24:25] op_sel:[1,1] op_sel_hi:[0,1]
	v_pk_fma_f32 v[184:185], v[120:121], v[24:25], v[168:169] op_sel_hi:[1,0,1] neg_lo:[0,0,1]
	ds_write_b64 v3, v[184:185] offset:42240
	v_pk_mul_f32 v[180:181], v[122:123], v[26:27] op_sel:[1,1] op_sel_hi:[0,1]
	v_pk_fma_f32 v[182:183], v[122:123], v[26:27], v[180:181] op_sel_hi:[1,0,1] neg_lo:[0,0,1]
	ds_write_b64 v3, v[182:183] offset:46464
	v_pk_mul_f32 v[110:111], v[124:125], v[28:29] op_sel:[1,1] op_sel_hi:[0,1]
	v_pk_fma_f32 v[102:103], v[124:125], v[28:29], v[110:111] op_sel_hi:[1,0,1] neg_lo:[0,0,1]
	ds_write_b64 v3, v[102:103] offset:50688
	v_pk_mul_f32 v[126:127], v[174:175], v[30:31] op_sel:[1,1] op_sel_hi:[0,1]
	v_pk_fma_f32 v[118:119], v[174:175], v[30:31], v[126:127] op_sel_hi:[1,0,1] neg_lo:[0,0,1]
	ds_write_b64 v3, v[118:119] offset:54912
	v_pk_mul_f32 v[186:187], v[128:129], v[32:33] op_sel:[1,1] op_sel_hi:[0,1]
	v_pk_fma_f32 v[188:189], v[128:129], v[32:33], v[186:187] op_sel_hi:[1,0,1] neg_lo:[0,0,1]
	ds_write_b64 v3, v[188:189] offset:59136
	v_pk_mul_f32 v[184:185], v[130:131], v[34:35] op_sel:[1,1] op_sel_hi:[0,1]
	v_pk_fma_f32 v[168:169], v[130:131], v[34:35], v[184:185] op_sel_hi:[1,0,1] neg_lo:[0,0,1]
	ds_write_b64 v3, v[168:169] offset:63360
	s_waitcnt lgkmcnt(0)
	s_barrier
; #define LAS __attribute__((address_space(3)))
; __device__ __forceinline__ f32x2 cmul(f32x2 a, f32x2 b) { return (f32x2){a.x * b.x - a.y * b.y, a.x * b.y + a.y * b.x}; }
; __device__ __forceinline__ void fft_fwd2(LAS f32x2* B, const LAS f32x2* TW2, int tid) {
;     asm volatile("" : "+v"(tid));
;     const int b = tid >> 5, n2 = tid & 31, base = 512 * b + n2; f32x2 x[16];
; #pragma unroll
;     for (int r = 0; r < 16; ++r) x[r] = B[fpad(base + 32 * r)];
;     dft16<false>(x);
;     B[fpad(base)] = x[0];
; #pragma unroll
;     for (int k = 1; k < 16; ++k) B[fpad(base + 32 * k)] = cmul(x[k], TW2[k * 32 + n2]);
; }
	ds_read_b64 v[100:101], v5
	ds_read_b64 v[178:179], v5 offset:264
	ds_read_b64 v[104:105], v5 offset:528
	ds_read_b64 v[106:107], v5 offset:792
	ds_read_b64 v[108:109], v5 offset:1056
	ds_read_b64 v[176:177], v5 offset:1320
	ds_read_b64 v[112:113], v5 offset:1584
	ds_read_b64 v[114:115], v5 offset:1848
	ds_read_b64 v[116:117], v5 offset:2112
	ds_read_b64 v[166:167], v5 offset:2376
	ds_read_b64 v[120:121], v5 offset:2640
	ds_read_b64 v[122:123], v5 offset:2904
	s_waitcnt lgkmcnt(8)
	ds_read_b64 v[124:125], v5 offset:3168
	ds_read_b64 v[174:175], v5 offset:3432
	ds_read_b64 v[128:129], v5 offset:3696
	ds_read_b64 v[130:131], v5 offset:3960
	s_waitcnt lgkmcnt(7)
	v_pk_add_f32 v[180:181], v[100:101], v[116:117]
	v_pk_add_f32 v[182:183], v[100:101], v[116:117] neg_lo:[0,1] neg_hi:[0,1]
	s_waitcnt lgkmcnt(3)
	v_pk_add_f32 v[110:111], v[108:109], v[124:125]
	v_pk_add_f32 v[102:103], v[108:109], v[124:125] neg_lo:[0,1] neg_hi:[0,1]
	v_pk_add_f32 v[100:101], v[180:181], v[110:111]
	v_pk_add_f32 v[116:117], v[180:181], v[110:111] neg_lo:[0,1] neg_hi:[0,1]
	v_pk_add_f32 v[108:109], v[182:183], v[102:103] op_sel:[0,1] op_sel_hi:[1,0] neg_hi:[0,1]
	v_pk_add_f32 v[124:125], v[182:183], v[102:103] op_sel:[0,1] op_sel_hi:[1,0] neg_lo:[0,1]
	v_pk_add_f32 v[126:127], v[178:179], v[166:167]
	v_pk_add_f32 v[118:119], v[178:179], v[166:167] neg_lo:[0,1] neg_hi:[0,1]
	s_waitcnt lgkmcnt(2)
	v_pk_add_f32 v[186:187], v[176:177], v[174:175]
	v_pk_add_f32 v[188:189], v[176:177], v[174:175] neg_lo:[0,1] neg_hi:[0,1]
	v_pk_add_f32 v[178:179], v[126:127], v[186:187]
	v_pk_add_f32 v[166:167], v[126:127], v[186:187] neg_lo:[0,1] neg_hi:[0,1]
	v_pk_add_f32 v[176:177], v[118:119], v[188:189] op_sel:[0,1] op_sel_hi:[1,0] neg_hi:[0,1]
	v_pk_add_f32 v[174:175], v[118:119], v[188:189] op_sel:[0,1] op_sel_hi:[1,0] neg_lo:[0,1]
	v_pk_add_f32 v[184:185], v[104:105], v[120:121]
	v_pk_add_f32 v[168:169], v[104:105], v[120:121] neg_lo:[0,1] neg_hi:[0,1]
	s_waitcnt lgkmcnt(1)
	v_pk_add_f32 v[180:181], v[112:113], v[128:129]
	v_pk_add_f32 v[182:183], v[112:113], v[128:129] neg_lo:[0,1] neg_hi:[0,1]
	v_pk_add_f32 v[104:105], v[184:185], v[180:181]
	v_pk_add_f32 v[120:121], v[184:185], v[180:181] neg_lo:[0,1] neg_hi:[0,1]
	v_pk_add_f32 v[112:113], v[168:169], v[182:183] op_sel:[0,1] op_sel_hi:[1,0] neg_hi:[0,1]
	v_pk_add_f32 v[128:129], v[168:169], v[182:183] op_sel:[0,1] op_sel_hi:[1,0] neg_lo:[0,1]
	v_pk_add_f32 v[110:111], v[106:107], v[122:123]
	v_pk_add_f32 v[102:103], v[106:107], v[122:123] neg_lo:[0,1] neg_hi:[0,1]
	s_waitcnt lgkmcnt(0)
	v_pk_add_f32 v[126:127], v[114:115], v[130:131]
	v_pk_add_f32 v[118:119], v[114:115], v[130:131] neg_lo:[0,1] neg_hi:[0,1]
	v_pk_add_f32 v[106:107], v[110:111], v[126:127]
	v_pk_add_f32 v[122:123], v[110:111], v[126:127] neg_lo:[0,1] neg_hi:[0,1]
	v_pk_add_f32 v[114:115], v[102:103], v[118:119] op_sel:[0,1] op_sel_hi:[1,0] neg_hi:[0,1]
	v_pk_add_f32 v[130:131], v[102:103], v[118:119] op_sel:[0,1] op_sel_hi:[1,0] neg_lo:[0,1]
	v_pk_mul_f32 v[186:187], v[176:177], s[68:69] op_sel:[1,1] op_sel_hi:[0,1]
	v_pk_fma_f32 v[176:177], v[176:177], s[68:69], v[186:187] op_sel_hi:[1,0,1] neg_lo:[0,0,1]
	v_pk_mul_f32 v[188:189], v[112:113], s[84:85] op_sel:[1,1] op_sel_hi:[0,1]
	v_pk_fma_f32 v[112:113], v[112:113], s[84:85], v[188:189] op_sel_hi:[1,0,1] neg_lo:[0,0,1]
	v_pk_mul_f32 v[184:185], v[114:115], s[88:89] op_sel:[1,1] op_sel_hi:[0,1]
	v_pk_fma_f32 v[114:115], v[114:115], s[88:89], v[184:185] op_sel_hi:[1,0,1] neg_lo:[0,0,1]
	v_pk_mul_f32 v[168:169], v[166:167], s[84:85] op_sel:[1,1] op_sel_hi:[0,1]
	v_pk_fma_f32 v[166:167], v[166:167], s[84:85], v[168:169] op_sel_hi:[1,0,1] neg_lo:[0,0,1]
	v_pk_mul_f32 v[180:181], v[122:123], s[90:91] op_sel:[1,1] op_sel_hi:[0,1]
	v_pk_fma_f32 v[122:123], v[122:123], s[90:91], v[180:181] op_sel_hi:[1,0,1] neg_lo:[0,0,1]
	v_pk_mul_f32 v[182:183], v[174:175], s[88:89] op_sel:[1,1] op_sel_hi:[0,1]
	v_pk_fma_f32 v[174:175], v[174:175], s[88:89], v[182:183] op_sel_hi:[1,0,1] neg_lo:[0,0,1]
	v_pk_mul_f32 v[110:111], v[128:129], s[90:91] op_sel:[1,1] op_sel_hi:[0,1]
	v_pk_fma_f32 v[128:129], v[128:129], s[90:91], v[110:111] op_sel_hi:[1,0,1] neg_lo:[0,0,1]
	v_pk_mul_f32 v[102:103], v[130:131], s[98:99] op_sel:[1,1] op_sel_hi:[0,1]
	v_pk_fma_f32 v[130:131], v[130:131], s[98:99], v[102:103] op_sel_hi:[1,0,1] neg_lo:[0,0,1]
	v_pk_add_f32 v[126:127], v[100:101], v[104:105]
	v_pk_add_f32 v[118:119], v[100:101], v[104:105] neg_lo:[0,1] neg_hi:[0,1]
	v_pk_add_f32 v[186:187], v[178:179], v[106:107]
	v_pk_add_f32 v[188:189], v[178:179], v[106:107] neg_lo:[0,1] neg_hi:[0,1]
	v_pk_add_f32 v[100:101], v[126:127], v[186:187]
	v_pk_add_f32 v[104:105], v[126:127], v[186:187] neg_lo:[0,1] neg_hi:[0,1]
	v_pk_add_f32 v[178:179], v[118:119], v[188:189] op_sel:[0,1] op_sel_hi:[1,0] neg_hi:[0,1]
	v_pk_add_f32 v[106:107], v[118:119], v[188:189] op_sel:[0,1] op_sel_hi:[1,0] neg_lo:[0,1]
	v_pk_add_f32 v[184:185], v[108:109], v[112:113]
	v_pk_add_f32 v[168:169], v[108:109], v[112:113] neg_lo:[0,1] neg_hi:[0,1]
	v_pk_add_f32 v[180:181], v[176:177], v[114:115]
	v_pk_add_f32 v[182:183], v[176:177], v[114:115] neg_lo:[0,1] neg_hi:[0,1]
	v_pk_add_f32 v[108:109], v[184:185], v[180:181]
	v_pk_add_f32 v[112:113], v[184:185], v[180:181] neg_lo:[0,1] neg_hi:[0,1]
	v_pk_add_f32 v[176:177], v[168:169], v[182:183] op_sel:[0,1] op_sel_hi:[1,0] neg_hi:[0,1]
	v_pk_add_f32 v[114:115], v[168:169], v[182:183] op_sel:[0,1] op_sel_hi:[1,0] neg_lo:[0,1]
	v_pk_add_f32 v[110:111], v[116:117], v[120:121] op_sel:[0,1] op_sel_hi:[1,0] neg_hi:[0,1]
	v_pk_add_f32 v[102:103], v[116:117], v[120:121] op_sel:[0,1] op_sel_hi:[1,0] neg_lo:[0,1]
	v_pk_add_f32 v[126:127], v[166:167], v[122:123]
	v_pk_add_f32 v[118:119], v[166:167], v[122:123] neg_lo:[0,1] neg_hi:[0,1]
	v_pk_add_f32 v[116:117], v[110:111], v[126:127]
	v_pk_add_f32 v[120:121], v[110:111], v[126:127] neg_lo:[0,1] neg_hi:[0,1]
	v_pk_add_f32 v[166:167], v[102:103], v[118:119] op_sel:[0,1] op_sel_hi:[1,0] neg_hi:[0,1]
	v_pk_add_f32 v[122:123], v[102:103], v[118:119] op_sel:[0,1] op_sel_hi:[1,0] neg_lo:[0,1]
	v_pk_add_f32 v[186:187], v[124:125], v[128:129]
	v_pk_add_f32 v[188:189], v[124:125], v[128:129] neg_lo:[0,1] neg_hi:[0,1]
	v_pk_add_f32 v[184:185], v[174:175], v[130:131]
	v_pk_add_f32 v[168:169], v[174:175], v[130:131] neg_lo:[0,1] neg_hi:[0,1]
	v_pk_add_f32 v[124:125], v[186:187], v[184:185]
	v_pk_add_f32 v[128:129], v[186:187], v[184:185] neg_lo:[0,1] neg_hi:[0,1]
	v_pk_add_f32 v[174:175], v[188:189], v[168:169] op_sel:[0,1] op_sel_hi:[1,0] neg_hi:[0,1]
	v_pk_add_f32 v[130:131], v[188:189], v[168:169] op_sel:[0,1] op_sel_hi:[1,0] neg_lo:[0,1]
	ds_write_b64 v5, v[100:101]
	ds_read_b64 v[180:181], v56 offset:256
	ds_read_b64 v[182:183], v56 offset:512
	ds_read_b64 v[110:111], v56 offset:768
	ds_read_b64 v[102:103], v56 offset:1024
	s_waitcnt lgkmcnt(3)
; #define LAS __attribute__((address_space(3)))
; __device__ __forceinline__ f32x2 cmul(f32x2 a, f32x2 b) { return (f32x2){a.x * b.x - a.y * b.y, a.x * b.y + a.y * b.x}; }
; __device__ __forceinline__ void fft_fwd2(LAS f32x2* B, const LAS f32x2* TW2, int tid) {
;     ...
;     B[fpad(base)] = x[0];
; #pragma unroll
;     for (int k = 1; k < 16; ++k) B[fpad(base + 32 * k)] = cmul(x[k], TW2[k * 32 + n2]);
; }
; template <int MODE> __device__ __forceinline__ void fft_pair32(LAS f32x2* B, const LAS f32x2* F, int wave, int lane) {
;     asm volatile("" : "+v"(lane));
;     constexpr float CS[16] = {1.f, 0.98078528040323043f, 0.92387953251128674f, 0.83146961230254524f, 0.70710678118654752f, 0.55557023301960218f, 0.38268343236508977f, 0.19509032201612825f,
;                               0.f, -0.19509032201612825f, -0.38268343236508977f, -0.55557023301960218f, -0.70710678118654752f, -0.83146961230254524f, -0.92387953251128674f, -0.98078528040323043f};
;     constexpr float SN[16] = {0.f, 0.19509032201612825f, 0.38268343236508977f, 0.55557023301960218f, 0.70710678118654752f, 0.83146961230254524f, 0.92387953251128674f, 0.98078528040323043f,
;                               1.f, 0.98078528040323043f, 0.92387953251128674f, 0.83146961230254524f, 0.70710678118654752f, 0.55557023301960218f, 0.38268343236508977f, 0.19509032201612825f};
;     const int hi = lane >> 5, blk = 32 * wave + (lane & 31); const float sg = hi ? -1.f : 1.f;
;     LAS f32x2* p = B + 33 * blk; f32x2 v[16];
; #pragma unroll
;     for (int j = 0; j < 16; ++j) { const f32x2 d = p[j] + p[j + 16] * sg;
;         const f32x2 w = {hi ? CS[j] : 1.f, hi ? -SN[j] : 0.f}; v[j] = j == 0 ? d : cmul(d, w); }
	v_pk_mul_f32 v[126:127], v[108:109], v[180:181] op_sel:[1,1] op_sel_hi:[0,1]
	v_pk_fma_f32 v[108:109], v[108:109], v[180:181], v[126:127] op_sel_hi:[1,0,1] neg_lo:[0,0,1]
	ds_write_b64 v5, v[108:109] offset:264
	s_waitcnt lgkmcnt(3)
	v_pk_mul_f32 v[118:119], v[116:117], v[182:183] op_sel:[1,1] op_sel_hi:[0,1]
	v_pk_fma_f32 v[116:117], v[116:117], v[182:183], v[118:119] op_sel_hi:[1,0,1] neg_lo:[0,0,1]
	ds_write_b64 v5, v[116:117] offset:528
	s_waitcnt lgkmcnt(3)
	v_pk_mul_f32 v[186:187], v[124:125], v[110:111] op_sel:[1,1] op_sel_hi:[0,1]
	v_pk_fma_f32 v[124:125], v[124:125], v[110:111], v[186:187] op_sel_hi:[1,0,1] neg_lo:[0,0,1]
	ds_write_b64 v5, v[124:125] offset:792
	s_waitcnt lgkmcnt(3)
	v_pk_mul_f32 v[188:189], v[178:179], v[102:103] op_sel:[1,1] op_sel_hi:[0,1]
	v_pk_fma_f32 v[178:179], v[178:179], v[102:103], v[188:189] op_sel_hi:[1,0,1] neg_lo:[0,0,1]
	ds_write_b64 v5, v[178:179] offset:1056
	ds_read_b64 v[184:185], v56 offset:1280
	ds_read_b64 v[168:169], v56 offset:1536
	ds_read_b64 v[126:127], v56 offset:1792
	ds_read_b64 v[118:119], v56 offset:2048
	s_waitcnt lgkmcnt(3)
	v_pk_mul_f32 v[186:187], v[176:177], v[184:185] op_sel:[1,1] op_sel_hi:[0,1]
	v_pk_fma_f32 v[176:177], v[176:177], v[184:185], v[186:187] op_sel_hi:[1,0,1] neg_lo:[0,0,1]
	ds_write_b64 v5, v[176:177] offset:1320
	s_waitcnt lgkmcnt(3)
	v_pk_mul_f32 v[188:189], v[166:167], v[168:169] op_sel:[1,1] op_sel_hi:[0,1]
	v_pk_fma_f32 v[166:167], v[166:167], v[168:169], v[188:189] op_sel_hi:[1,0,1] neg_lo:[0,0,1]
	ds_write_b64 v5, v[166:167] offset:1584
	s_waitcnt lgkmcnt(3)
	v_pk_mul_f32 v[180:181], v[174:175], v[126:127] op_sel:[1,1] op_sel_hi:[0,1]
	v_pk_fma_f32 v[174:175], v[174:175], v[126:127], v[180:181] op_sel_hi:[1,0,1] neg_lo:[0,0,1]
	ds_write_b64 v5, v[174:175] offset:1848
	s_waitcnt lgkmcnt(3)
	v_pk_mul_f32 v[182:183], v[104:105], v[118:119] op_sel:[1,1] op_sel_hi:[0,1]
	v_pk_fma_f32 v[104:105], v[104:105], v[118:119], v[182:183] op_sel_hi:[1,0,1] neg_lo:[0,0,1]
	ds_write_b64 v5, v[104:105] offset:2112
	ds_read_b64 v[110:111], v56 offset:2304
	ds_read_b64 v[102:103], v56 offset:2560
	ds_read_b64 v[186:187], v56 offset:2816
	ds_read_b64 v[188:189], v56 offset:3072
	s_waitcnt lgkmcnt(3)
	v_pk_mul_f32 v[180:181], v[112:113], v[110:111] op_sel:[1,1] op_sel_hi:[0,1]
	v_pk_fma_f32 v[112:113], v[112:113], v[110:111], v[180:181] op_sel_hi:[1,0,1] neg_lo:[0,0,1]
	ds_write_b64 v5, v[112:113] offset:2376
	s_waitcnt lgkmcnt(3)
	v_pk_mul_f32 v[182:183], v[120:121], v[102:103] op_sel:[1,1] op_sel_hi:[0,1]
	v_pk_fma_f32 v[120:121], v[120:121], v[102:103], v[182:183] op_sel_hi:[1,0,1] neg_lo:[0,0,1]
	ds_write_b64 v5, v[120:121] offset:2640
	s_waitcnt lgkmcnt(3)
	v_pk_mul_f32 v[184:185], v[128:129], v[186:187] op_sel:[1,1] op_sel_hi:[0,1]
	v_pk_fma_f32 v[128:129], v[128:129], v[186:187], v[184:185] op_sel_hi:[1,0,1] neg_lo:[0,0,1]
	ds_write_b64 v5, v[128:129] offset:2904
	s_waitcnt lgkmcnt(3)
	v_pk_mul_f32 v[168:169], v[106:107], v[188:189] op_sel:[1,1] op_sel_hi:[0,1]
	v_pk_fma_f32 v[106:107], v[106:107], v[188:189], v[168:169] op_sel_hi:[1,0,1] neg_lo:[0,0,1]
	ds_write_b64 v5, v[106:107] offset:3168
	ds_read_b64 v[126:127], v56 offset:3328
	ds_read_b64 v[118:119], v56 offset:3584
	ds_read_b64 v[180:181], v56 offset:3840
	s_waitcnt lgkmcnt(2)
	v_pk_mul_f32 v[182:183], v[114:115], v[126:127] op_sel:[1,1] op_sel_hi:[0,1]
	v_pk_fma_f32 v[114:115], v[114:115], v[126:127], v[182:183] op_sel_hi:[1,0,1] neg_lo:[0,0,1]
	ds_write_b64 v5, v[114:115] offset:3432
	s_waitcnt lgkmcnt(2)
	v_pk_mul_f32 v[184:185], v[122:123], v[118:119] op_sel:[1,1] op_sel_hi:[0,1]
	v_pk_fma_f32 v[122:123], v[122:123], v[118:119], v[184:185] op_sel_hi:[1,0,1] neg_lo:[0,0,1]
	ds_write_b64 v5, v[122:123] offset:3696
	s_waitcnt lgkmcnt(2)
	v_pk_mul_f32 v[168:169], v[130:131], v[180:181] op_sel:[1,1] op_sel_hi:[0,1]
	v_pk_fma_f32 v[130:131], v[130:131], v[180:181], v[168:169] op_sel_hi:[1,0,1] neg_lo:[0,0,1]
	ds_write_b64 v5, v[130:131] offset:3960
	s_waitcnt lgkmcnt(0)
	ds_read_b64 v[100:101], v156
	ds_read_b64 v[110:111], v156 offset:128
	ds_read_b64 v[108:109], v156 offset:8
	ds_read_b64 v[102:103], v156 offset:136
	ds_read_b64 v[116:117], v156 offset:16
	ds_read_b64 v[186:187], v156 offset:144
	ds_read_b64 v[124:125], v156 offset:24
	ds_read_b64 v[188:189], v156 offset:152
	s_waitcnt lgkmcnt(6)
	v_pk_fma_f32 v[100:101], v[110:111], v[190:191], v[100:101] op_sel_hi:[1,0,1]
	s_waitcnt lgkmcnt(4)
	v_pk_fma_f32 v[108:109], v[102:103], v[190:191], v[108:109] op_sel_hi:[1,0,1]
	v_pk_mul_f32 v[182:183], v[108:109], v[36:37] op_sel:[1,1] op_sel_hi:[0,1]
	v_pk_fma_f32 v[108:109], v[108:109], v[36:37], v[182:183] op_sel_hi:[1,0,1] neg_lo:[0,0,1]
	s_waitcnt lgkmcnt(2)
	v_pk_fma_f32 v[116:117], v[186:187], v[190:191], v[116:117] op_sel_hi:[1,0,1]
	v_pk_mul_f32 v[184:185], v[116:117], v[38:39] op_sel:[1,1] op_sel_hi:[0,1]
	v_pk_fma_f32 v[116:117], v[116:117], v[38:39], v[184:185] op_sel_hi:[1,0,1] neg_lo:[0,0,1]
	s_waitcnt lgkmcnt(0)
	v_pk_fma_f32 v[124:125], v[188:189], v[190:191], v[124:125] op_sel_hi:[1,0,1]
	v_pk_mul_f32 v[168:169], v[124:125], v[40:41] op_sel:[1,1] op_sel_hi:[0,1]
	v_pk_fma_f32 v[124:125], v[124:125], v[40:41], v[168:169] op_sel_hi:[1,0,1] neg_lo:[0,0,1]
	ds_read_b64 v[178:179], v156 offset:32
	ds_read_b64 v[126:127], v156 offset:160
	ds_read_b64 v[176:177], v156 offset:40
	ds_read_b64 v[118:119], v156 offset:168
	ds_read_b64 v[166:167], v156 offset:48
	ds_read_b64 v[180:181], v156 offset:176
	ds_read_b64 v[174:175], v156 offset:56
	ds_read_b64 v[182:183], v156 offset:184
	s_waitcnt lgkmcnt(6)
; #define LAS __attribute__((address_space(3)))
; __device__ __forceinline__ f32x2 cmul(f32x2 a, f32x2 b) { return (f32x2){a.x * b.x - a.y * b.y, a.x * b.y + a.y * b.x}; }
; template <bool INV> __device__ __forceinline__ f32x2 cmul_tw(f32x2 a, f32x2 w) { return INV ? cmulc(a, w) : cmul(a, w); }
; template <bool INV> __device__ __forceinline__ void dft16(f32x2 (&x)[16]) {
;     constexpr float C1 = 0.92387953251128674f, S1 = 0.38268343236508977f, C2 = 0.70710678118654752f;
; #pragma unroll
;     for (int b = 0; b < 4; ++b) dft4<INV>(x[b], x[4 + b], x[8 + b], x[12 + b]);
;     const f32x2 w1 = {C1, -S1}, w2 = {C2, -C2}, w3 = {S1, -C1}, w4 = {0.f, -1.f}, w6 = {-C2, -C2}, w9 = {-C1, S1};
;     x[4 * 1 + 1] = cmul_tw<INV>(x[5], w1); x[4 * 1 + 2] = cmul_tw<INV>(x[6], w2); x[4 * 1 + 3] = cmul_tw<INV>(x[7], w3);
;     x[4 * 2 + 1] = cmul_tw<INV>(x[9], w2); x[4 * 2 + 2] = cmul_tw<INV>(x[10], w4); x[4 * 2 + 3] = cmul_tw<INV>(x[11], w6);
;     x[4 * 3 + 1] = cmul_tw<INV>(x[13], w3); x[4 * 3 + 2] = cmul_tw<INV>(x[14], w6); x[4 * 3 + 3] = cmul_tw<INV>(x[15], w9);
; #pragma unroll
;     for (int c = 0; c < 4; ++c) dft4<INV>(x[4 * c], x[4 * c + 1], x[4 * c + 2], x[4 * c + 3]);
; template <int MODE> __device__ __forceinline__ void fft_pair32(LAS f32x2* B, const LAS f32x2* F, int wave, int lane) {
;     ...
;     const int hi = lane >> 5, blk = 32 * wave + (lane & 31); const float sg = hi ? -1.f : 1.f;
;     LAS f32x2* p = B + 33 * blk; f32x2 v[16];
; #pragma unroll
;     for (int j = 0; j < 16; ++j) { const f32x2 d = p[j] + p[j + 16] * sg;
;         const f32x2 w = {hi ? CS[j] : 1.f, hi ? -SN[j] : 0.f}; v[j] = j == 0 ? d : cmul(d, w); }
;     dft16<false>(v);
	v_pk_fma_f32 v[178:179], v[126:127], v[190:191], v[178:179] op_sel_hi:[1,0,1]
	v_pk_mul_f32 v[184:185], v[178:179], v[42:43] op_sel:[1,1] op_sel_hi:[0,1]
	v_pk_fma_f32 v[178:179], v[178:179], v[42:43], v[184:185] op_sel_hi:[1,0,1] neg_lo:[0,0,1]
	s_waitcnt lgkmcnt(4)
	v_pk_fma_f32 v[176:177], v[118:119], v[190:191], v[176:177] op_sel_hi:[1,0,1]
	v_pk_mul_f32 v[168:169], v[176:177], v[44:45] op_sel:[1,1] op_sel_hi:[0,1]
	v_pk_fma_f32 v[176:177], v[176:177], v[44:45], v[168:169] op_sel_hi:[1,0,1] neg_lo:[0,0,1]
	s_waitcnt lgkmcnt(2)
	v_pk_fma_f32 v[166:167], v[180:181], v[190:191], v[166:167] op_sel_hi:[1,0,1]
	v_pk_mul_f32 v[110:111], v[166:167], v[46:47] op_sel:[1,1] op_sel_hi:[0,1]
	v_pk_fma_f32 v[166:167], v[166:167], v[46:47], v[110:111] op_sel_hi:[1,0,1] neg_lo:[0,0,1]
	s_waitcnt lgkmcnt(0)
	v_pk_fma_f32 v[174:175], v[182:183], v[190:191], v[174:175] op_sel_hi:[1,0,1]
	v_pk_mul_f32 v[102:103], v[174:175], v[48:49] op_sel:[1,1] op_sel_hi:[0,1]
	v_pk_fma_f32 v[174:175], v[174:175], v[48:49], v[102:103] op_sel_hi:[1,0,1] neg_lo:[0,0,1]
	ds_read_b64 v[104:105], v156 offset:64
	ds_read_b64 v[186:187], v156 offset:192
	ds_read_b64 v[112:113], v156 offset:72
	ds_read_b64 v[188:189], v156 offset:200
	ds_read_b64 v[120:121], v156 offset:80
	ds_read_b64 v[184:185], v156 offset:208
	ds_read_b64 v[128:129], v156 offset:88
	ds_read_b64 v[168:169], v156 offset:216
	s_waitcnt lgkmcnt(6)
	v_pk_fma_f32 v[104:105], v[186:187], v[190:191], v[104:105] op_sel_hi:[1,0,1]
	v_pk_mul_f32 v[110:111], v[104:105], v[50:51] op_sel:[1,1] op_sel_hi:[0,1]
	v_pk_fma_f32 v[104:105], v[104:105], v[50:51], v[110:111] op_sel_hi:[1,0,1] neg_lo:[0,0,1]
	s_waitcnt lgkmcnt(4)
	v_pk_fma_f32 v[112:113], v[188:189], v[190:191], v[112:113] op_sel_hi:[1,0,1]
	v_pk_mul_f32 v[102:103], v[112:113], v[52:53] op_sel:[1,1] op_sel_hi:[0,1]
	v_pk_fma_f32 v[112:113], v[112:113], v[52:53], v[102:103] op_sel_hi:[1,0,1] neg_lo:[0,0,1]
	s_waitcnt lgkmcnt(2)
	v_pk_fma_f32 v[120:121], v[184:185], v[190:191], v[120:121] op_sel_hi:[1,0,1]
	v_pk_mul_f32 v[126:127], v[120:121], v[54:55] op_sel:[1,1] op_sel_hi:[0,1]
	v_pk_fma_f32 v[120:121], v[120:121], v[54:55], v[126:127] op_sel_hi:[1,0,1] neg_lo:[0,0,1]
	s_waitcnt lgkmcnt(0)
	v_pk_fma_f32 v[128:129], v[168:169], v[190:191], v[128:129] op_sel_hi:[1,0,1]
	v_pk_mul_f32 v[118:119], v[128:129], v[90:91] op_sel:[1,1] op_sel_hi:[0,1]
	v_pk_fma_f32 v[128:129], v[128:129], v[90:91], v[118:119] op_sel_hi:[1,0,1] neg_lo:[0,0,1]
	ds_read_b64 v[106:107], v156 offset:96
	ds_read_b64 v[180:181], v156 offset:224
	ds_read_b64 v[114:115], v156 offset:104
	ds_read_b64 v[182:183], v156 offset:232
	ds_read_b64 v[122:123], v156 offset:112
	ds_read_b64 v[110:111], v156 offset:240
	ds_read_b64 v[130:131], v156 offset:120
	ds_read_b64 v[102:103], v156 offset:248
	s_waitcnt lgkmcnt(6)
	v_pk_fma_f32 v[106:107], v[180:181], v[190:191], v[106:107] op_sel_hi:[1,0,1]
	v_pk_mul_f32 v[126:127], v[106:107], v[92:93] op_sel:[1,1] op_sel_hi:[0,1]
	v_pk_fma_f32 v[106:107], v[106:107], v[92:93], v[126:127] op_sel_hi:[1,0,1] neg_lo:[0,0,1]
	s_waitcnt lgkmcnt(4)
	v_pk_fma_f32 v[114:115], v[182:183], v[190:191], v[114:115] op_sel_hi:[1,0,1]
	v_pk_mul_f32 v[118:119], v[114:115], v[94:95] op_sel:[1,1] op_sel_hi:[0,1]
	v_pk_fma_f32 v[114:115], v[114:115], v[94:95], v[118:119] op_sel_hi:[1,0,1] neg_lo:[0,0,1]
	s_waitcnt lgkmcnt(2)
	v_pk_fma_f32 v[122:123], v[110:111], v[190:191], v[122:123] op_sel_hi:[1,0,1]
	v_pk_mul_f32 v[186:187], v[122:123], v[96:97] op_sel:[1,1] op_sel_hi:[0,1]
	v_pk_fma_f32 v[122:123], v[122:123], v[96:97], v[186:187] op_sel_hi:[1,0,1] neg_lo:[0,0,1]
	s_waitcnt lgkmcnt(0)
	v_pk_fma_f32 v[130:131], v[102:103], v[190:191], v[130:131] op_sel_hi:[1,0,1]
	v_pk_mul_f32 v[188:189], v[130:131], v[98:99] op_sel:[1,1] op_sel_hi:[0,1]
	v_pk_fma_f32 v[130:131], v[130:131], v[98:99], v[188:189] op_sel_hi:[1,0,1] neg_lo:[0,0,1]
	v_pk_add_f32 v[184:185], v[100:101], v[104:105]
	v_pk_add_f32 v[168:169], v[100:101], v[104:105] neg_lo:[0,1] neg_hi:[0,1]
	v_pk_add_f32 v[126:127], v[178:179], v[106:107]
	v_pk_add_f32 v[118:119], v[178:179], v[106:107] neg_lo:[0,1] neg_hi:[0,1]
	v_pk_add_f32 v[100:101], v[184:185], v[126:127]
	v_pk_add_f32 v[104:105], v[184:185], v[126:127] neg_lo:[0,1] neg_hi:[0,1]
	v_pk_add_f32 v[178:179], v[168:169], v[118:119] op_sel:[0,1] op_sel_hi:[1,0] neg_hi:[0,1]
	v_pk_add_f32 v[106:107], v[168:169], v[118:119] op_sel:[0,1] op_sel_hi:[1,0] neg_lo:[0,1]
	v_pk_add_f32 v[186:187], v[108:109], v[112:113]
	v_pk_add_f32 v[188:189], v[108:109], v[112:113] neg_lo:[0,1] neg_hi:[0,1]
	v_pk_add_f32 v[180:181], v[176:177], v[114:115]
	v_pk_add_f32 v[182:183], v[176:177], v[114:115] neg_lo:[0,1] neg_hi:[0,1]
	v_pk_add_f32 v[108:109], v[186:187], v[180:181]
	v_pk_add_f32 v[112:113], v[186:187], v[180:181] neg_lo:[0,1] neg_hi:[0,1]
	v_pk_add_f32 v[176:177], v[188:189], v[182:183] op_sel:[0,1] op_sel_hi:[1,0] neg_hi:[0,1]
	v_pk_add_f32 v[114:115], v[188:189], v[182:183] op_sel:[0,1] op_sel_hi:[1,0] neg_lo:[0,1]
	v_pk_add_f32 v[110:111], v[116:117], v[120:121]
	v_pk_add_f32 v[102:103], v[116:117], v[120:121] neg_lo:[0,1] neg_hi:[0,1]
	v_pk_add_f32 v[184:185], v[166:167], v[122:123]
	v_pk_add_f32 v[168:169], v[166:167], v[122:123] neg_lo:[0,1] neg_hi:[0,1]
	v_pk_add_f32 v[116:117], v[110:111], v[184:185]
	v_pk_add_f32 v[120:121], v[110:111], v[184:185] neg_lo:[0,1] neg_hi:[0,1]
	v_pk_add_f32 v[166:167], v[102:103], v[168:169] op_sel:[0,1] op_sel_hi:[1,0] neg_hi:[0,1]
	v_pk_add_f32 v[122:123], v[102:103], v[168:169] op_sel:[0,1] op_sel_hi:[1,0] neg_lo:[0,1]
	v_pk_add_f32 v[126:127], v[124:125], v[128:129]
	v_pk_add_f32 v[118:119], v[124:125], v[128:129] neg_lo:[0,1] neg_hi:[0,1]
; #define LAS __attribute__((address_space(3)))
; __device__ __forceinline__ f32x2 cmul(f32x2 a, f32x2 b) { return (f32x2){a.x * b.x - a.y * b.y, a.x * b.y + a.y * b.x}; }
; template <bool INV> __device__ __forceinline__ f32x2 cmul_tw(f32x2 a, f32x2 w) { return INV ? cmulc(a, w) : cmul(a, w); }
; template <bool INV> __device__ __forceinline__ void dft16(f32x2 (&x)[16]) {
;     constexpr float C1 = 0.92387953251128674f, S1 = 0.38268343236508977f, C2 = 0.70710678118654752f;
; #pragma unroll
;     for (int b = 0; b < 4; ++b) dft4<INV>(x[b], x[4 + b], x[8 + b], x[12 + b]);
;     const f32x2 w1 = {C1, -S1}, w2 = {C2, -C2}, w3 = {S1, -C1}, w4 = {0.f, -1.f}, w6 = {-C2, -C2}, w9 = {-C1, S1};
;     x[4 * 1 + 1] = cmul_tw<INV>(x[5], w1); x[4 * 1 + 2] = cmul_tw<INV>(x[6], w2); x[4 * 1 + 3] = cmul_tw<INV>(x[7], w3);
;     x[4 * 2 + 1] = cmul_tw<INV>(x[9], w2); x[4 * 2 + 2] = cmul_tw<INV>(x[10], w4); x[4 * 2 + 3] = cmul_tw<INV>(x[11], w6);
;     x[4 * 3 + 1] = cmul_tw<INV>(x[13], w3); x[4 * 3 + 2] = cmul_tw<INV>(x[14], w6); x[4 * 3 + 3] = cmul_tw<INV>(x[15], w9);
; #pragma unroll
;     for (int c = 0; c < 4; ++c) dft4<INV>(x[4 * c], x[4 * c + 1], x[4 * c + 2], x[4 * c + 3]);
;     f32x2 y[16];
; #pragma unroll
;     for (int k = 0; k < 16; ++k) y[k] = x[4 * (k & 3) + (k >> 2)];
; #pragma unroll
;     for (int k = 0; k < 16; ++k) x[k] = y[k];
; template <int MODE> __device__ __forceinline__ void fft_pair32(LAS f32x2* B, const LAS f32x2* F, int wave, int lane) {
;     ...
;     const int k1 = blk >> 4, k2 = blk & 15, kb1 = (16 - k1) & 15, b1 = k1 != 0 ? 1 : 0, kb2 = (16 - k2 - b1) & 15, b2 = (k2 != 0 || b1) ? 1 : 0;
;     const LAS f32x2* fa = F + 33 * blk; const LAS f32x2* fb = F + 33 * (16 * kb1 + kb2);
;     const LAS f32x2* fah = fa + hi; const LAS f32x2* fbh = fb + (1 - b2) - hi;
;     constexpr float SC = 1.0f / (2.0f * (float)FN);
; #pragma unroll
;     for (int k = 0; k < 16; ++k) { const f32x2 A = fah[2 * k]; f32x2 Bm = fbh[31 - 2 * k];
;         if (k == 0) { const f32x2 m0 = b2 ? fb[31] : fa[0]; Bm = hi ? Bm : m0; }
;         const f32x2 H = MODE == 0 ? (f32x2){(A.x + Bm.x) * SC, (A.y - Bm.y) * SC} : (f32x2){(A.y + Bm.y) * SC, (Bm.x - A.x) * SC};
;         v[k] = cmul(v[k], H); }
	v_pk_add_f32 v[186:187], v[174:175], v[130:131]
	v_pk_add_f32 v[188:189], v[174:175], v[130:131] neg_lo:[0,1] neg_hi:[0,1]
	v_pk_add_f32 v[124:125], v[126:127], v[186:187]
	v_pk_add_f32 v[128:129], v[126:127], v[186:187] neg_lo:[0,1] neg_hi:[0,1]
	v_pk_add_f32 v[174:175], v[118:119], v[188:189] op_sel:[0,1] op_sel_hi:[1,0] neg_hi:[0,1]
	v_pk_add_f32 v[130:131], v[118:119], v[188:189] op_sel:[0,1] op_sel_hi:[1,0] neg_lo:[0,1]
	v_pk_mul_f32 v[180:181], v[176:177], s[68:69] op_sel:[1,1] op_sel_hi:[0,1]
	v_pk_fma_f32 v[176:177], v[176:177], s[68:69], v[180:181] op_sel_hi:[1,0,1] neg_lo:[0,0,1]
	v_pk_mul_f32 v[182:183], v[166:167], s[84:85] op_sel:[1,1] op_sel_hi:[0,1]
	v_pk_fma_f32 v[166:167], v[166:167], s[84:85], v[182:183] op_sel_hi:[1,0,1] neg_lo:[0,0,1]
	v_pk_mul_f32 v[110:111], v[174:175], s[88:89] op_sel:[1,1] op_sel_hi:[0,1]
	v_pk_fma_f32 v[174:175], v[174:175], s[88:89], v[110:111] op_sel_hi:[1,0,1] neg_lo:[0,0,1]
	v_pk_mul_f32 v[102:103], v[112:113], s[84:85] op_sel:[1,1] op_sel_hi:[0,1]
	v_pk_fma_f32 v[112:113], v[112:113], s[84:85], v[102:103] op_sel_hi:[1,0,1] neg_lo:[0,0,1]
	v_pk_mul_f32 v[184:185], v[128:129], s[90:91] op_sel:[1,1] op_sel_hi:[0,1]
	v_pk_fma_f32 v[128:129], v[128:129], s[90:91], v[184:185] op_sel_hi:[1,0,1] neg_lo:[0,0,1]
	v_pk_mul_f32 v[168:169], v[114:115], s[88:89] op_sel:[1,1] op_sel_hi:[0,1]
	v_pk_fma_f32 v[114:115], v[114:115], s[88:89], v[168:169] op_sel_hi:[1,0,1] neg_lo:[0,0,1]
	v_pk_mul_f32 v[126:127], v[122:123], s[90:91] op_sel:[1,1] op_sel_hi:[0,1]
	v_pk_fma_f32 v[122:123], v[122:123], s[90:91], v[126:127] op_sel_hi:[1,0,1] neg_lo:[0,0,1]
	v_pk_mul_f32 v[118:119], v[130:131], s[98:99] op_sel:[1,1] op_sel_hi:[0,1]
	v_pk_fma_f32 v[130:131], v[130:131], s[98:99], v[118:119] op_sel_hi:[1,0,1] neg_lo:[0,0,1]
	v_pk_add_f32 v[186:187], v[100:101], v[116:117]
	v_pk_add_f32 v[188:189], v[100:101], v[116:117] neg_lo:[0,1] neg_hi:[0,1]
	v_pk_add_f32 v[180:181], v[108:109], v[124:125]
	v_pk_add_f32 v[182:183], v[108:109], v[124:125] neg_lo:[0,1] neg_hi:[0,1]
	v_pk_add_f32 v[100:101], v[186:187], v[180:181]
	v_pk_add_f32 v[116:117], v[186:187], v[180:181] neg_lo:[0,1] neg_hi:[0,1]
	v_pk_add_f32 v[108:109], v[188:189], v[182:183] op_sel:[0,1] op_sel_hi:[1,0] neg_hi:[0,1]
	v_pk_add_f32 v[124:125], v[188:189], v[182:183] op_sel:[0,1] op_sel_hi:[1,0] neg_lo:[0,1]
	v_pk_add_f32 v[110:111], v[178:179], v[166:167]
	v_pk_add_f32 v[102:103], v[178:179], v[166:167] neg_lo:[0,1] neg_hi:[0,1]
	v_pk_add_f32 v[184:185], v[176:177], v[174:175]
	v_pk_add_f32 v[168:169], v[176:177], v[174:175] neg_lo:[0,1] neg_hi:[0,1]
	v_pk_add_f32 v[178:179], v[110:111], v[184:185]
	v_pk_add_f32 v[166:167], v[110:111], v[184:185] neg_lo:[0,1] neg_hi:[0,1]
	v_pk_add_f32 v[176:177], v[102:103], v[168:169] op_sel:[0,1] op_sel_hi:[1,0] neg_hi:[0,1]
	v_pk_add_f32 v[174:175], v[102:103], v[168:169] op_sel:[0,1] op_sel_hi:[1,0] neg_lo:[0,1]
	v_pk_add_f32 v[126:127], v[104:105], v[120:121] op_sel:[0,1] op_sel_hi:[1,0] neg_hi:[0,1]
	v_pk_add_f32 v[118:119], v[104:105], v[120:121] op_sel:[0,1] op_sel_hi:[1,0] neg_lo:[0,1]
	v_pk_add_f32 v[186:187], v[112:113], v[128:129]
	v_pk_add_f32 v[188:189], v[112:113], v[128:129] neg_lo:[0,1] neg_hi:[0,1]
	v_pk_add_f32 v[104:105], v[126:127], v[186:187]
	v_pk_add_f32 v[120:121], v[126:127], v[186:187] neg_lo:[0,1] neg_hi:[0,1]
	v_pk_add_f32 v[112:113], v[118:119], v[188:189] op_sel:[0,1] op_sel_hi:[1,0] neg_hi:[0,1]
	v_pk_add_f32 v[128:129], v[118:119], v[188:189] op_sel:[0,1] op_sel_hi:[1,0] neg_lo:[0,1]
	v_pk_add_f32 v[180:181], v[106:107], v[122:123]
	v_pk_add_f32 v[182:183], v[106:107], v[122:123] neg_lo:[0,1] neg_hi:[0,1]
	v_pk_add_f32 v[110:111], v[114:115], v[130:131]
	v_pk_add_f32 v[102:103], v[114:115], v[130:131] neg_lo:[0,1] neg_hi:[0,1]
	v_pk_add_f32 v[106:107], v[180:181], v[110:111]
	v_pk_add_f32 v[122:123], v[180:181], v[110:111] neg_lo:[0,1] neg_hi:[0,1]
	v_pk_add_f32 v[114:115], v[182:183], v[102:103] op_sel:[0,1] op_sel_hi:[1,0] neg_hi:[0,1]
	v_pk_add_f32 v[130:131], v[182:183], v[102:103] op_sel:[0,1] op_sel_hi:[1,0] neg_lo:[0,1]
	ds_read_b64 v[184:185], v200
	ds_read_b64 v[186:187], v204
	ds_read_b64 v[168:169], v200 offset:16
	ds_read_b64 v[188:189], v202 offset:232
	ds_read_b64 v[126:127], v200 offset:32
	ds_read_b64 v[180:181], v202 offset:216
	ds_read_b64 v[118:119], v200 offset:48
	ds_read_b64 v[182:183], v202 offset:200
	s_waitcnt lgkmcnt(6)
	v_pk_add_f32 v[184:185], v[184:185], v[186:187] neg_hi:[0,1]
	v_pk_mul_f32 v[110:111], v[100:101], v[184:185] op_sel:[1,1] op_sel_hi:[0,1]
	v_pk_fma_f32 v[100:101], v[100:101], v[184:185], v[110:111] op_sel_hi:[1,0,1] neg_lo:[0,0,1]
	s_waitcnt lgkmcnt(4)
	v_pk_add_f32 v[168:169], v[168:169], v[188:189] neg_hi:[0,1]
	v_pk_mul_f32 v[102:103], v[178:179], v[168:169] op_sel:[1,1] op_sel_hi:[0,1]
	v_pk_fma_f32 v[178:179], v[178:179], v[168:169], v[102:103] op_sel_hi:[1,0,1] neg_lo:[0,0,1]
	s_waitcnt lgkmcnt(2)
	v_pk_add_f32 v[126:127], v[126:127], v[180:181] neg_hi:[0,1]
	v_pk_mul_f32 v[110:111], v[104:105], v[126:127] op_sel:[1,1] op_sel_hi:[0,1]
	v_pk_fma_f32 v[104:105], v[104:105], v[126:127], v[110:111] op_sel_hi:[1,0,1] neg_lo:[0,0,1]
	s_waitcnt lgkmcnt(0)
	v_pk_add_f32 v[118:119], v[118:119], v[182:183] neg_hi:[0,1]
	v_pk_mul_f32 v[102:103], v[106:107], v[118:119] op_sel:[1,1] op_sel_hi:[0,1]
	v_pk_fma_f32 v[106:107], v[106:107], v[118:119], v[102:103] op_sel_hi:[1,0,1] neg_lo:[0,0,1]
	ds_read_b64 v[110:111], v200 offset:64
	ds_read_b64 v[126:127], v202 offset:184
	ds_read_b64 v[102:103], v200 offset:80
	ds_read_b64 v[118:119], v202 offset:168
	ds_read_b64 v[184:185], v200 offset:96
	ds_read_b64 v[186:187], v202 offset:152
	ds_read_b64 v[168:169], v200 offset:112
	ds_read_b64 v[188:189], v202 offset:136
	s_waitcnt lgkmcnt(6)
; #define LAS __attribute__((address_space(3)))
; __device__ __forceinline__ f32x2 cmul(f32x2 a, f32x2 b) { return (f32x2){a.x * b.x - a.y * b.y, a.x * b.y + a.y * b.x}; }
; template <bool INV> __device__ __forceinline__ f32x2 cmul_tw(f32x2 a, f32x2 w) { return INV ? cmulc(a, w) : cmul(a, w); }
; template <bool INV> __device__ __forceinline__ void dft16(f32x2 (&x)[16]) {
;     constexpr float C1 = 0.92387953251128674f, S1 = 0.38268343236508977f, C2 = 0.70710678118654752f;
; #pragma unroll
;     for (int b = 0; b < 4; ++b) dft4<INV>(x[b], x[4 + b], x[8 + b], x[12 + b]);
;     const f32x2 w1 = {C1, -S1}, w2 = {C2, -C2}, w3 = {S1, -C1}, w4 = {0.f, -1.f}, w6 = {-C2, -C2}, w9 = {-C1, S1};
;     x[4 * 1 + 1] = cmul_tw<INV>(x[5], w1); x[4 * 1 + 2] = cmul_tw<INV>(x[6], w2); x[4 * 1 + 3] = cmul_tw<INV>(x[7], w3);
;     x[4 * 2 + 1] = cmul_tw<INV>(x[9], w2); x[4 * 2 + 2] = cmul_tw<INV>(x[10], w4); x[4 * 2 + 3] = cmul_tw<INV>(x[11], w6);
;     x[4 * 3 + 1] = cmul_tw<INV>(x[13], w3); x[4 * 3 + 2] = cmul_tw<INV>(x[14], w6); x[4 * 3 + 3] = cmul_tw<INV>(x[15], w9);
; #pragma unroll
;     for (int c = 0; c < 4; ++c) dft4<INV>(x[4 * c], x[4 * c + 1], x[4 * c + 2], x[4 * c + 3]);
; template <int MODE> __device__ __forceinline__ void fft_pair32(LAS f32x2* B, const LAS f32x2* F, int wave, int lane) {
;     ...
;     const int k1 = blk >> 4, k2 = blk & 15, kb1 = (16 - k1) & 15, b1 = k1 != 0 ? 1 : 0, kb2 = (16 - k2 - b1) & 15, b2 = (k2 != 0 || b1) ? 1 : 0;
;     const LAS f32x2* fa = F + 33 * blk; const LAS f32x2* fb = F + 33 * (16 * kb1 + kb2);
;     const LAS f32x2* fah = fa + hi; const LAS f32x2* fbh = fb + (1 - b2) - hi;
;     constexpr float SC = 1.0f / (2.0f * (float)FN);
; #pragma unroll
;     for (int k = 0; k < 16; ++k) { const f32x2 A = fah[2 * k]; f32x2 Bm = fbh[31 - 2 * k];
;         if (k == 0) { const f32x2 m0 = b2 ? fb[31] : fa[0]; Bm = hi ? Bm : m0; }
;         const f32x2 H = MODE == 0 ? (f32x2){(A.x + Bm.x) * SC, (A.y - Bm.y) * SC} : (f32x2){(A.y + Bm.y) * SC, (Bm.x - A.x) * SC};
;         v[k] = cmul(v[k], H); }
;     dft16<true>(v);
	v_pk_add_f32 v[110:111], v[110:111], v[126:127] neg_hi:[0,1]
	v_pk_mul_f32 v[180:181], v[108:109], v[110:111] op_sel:[1,1] op_sel_hi:[0,1]
	v_pk_fma_f32 v[108:109], v[108:109], v[110:111], v[180:181] op_sel_hi:[1,0,1] neg_lo:[0,0,1]
	s_waitcnt lgkmcnt(4)
	v_pk_add_f32 v[102:103], v[102:103], v[118:119] neg_hi:[0,1]
	v_pk_mul_f32 v[182:183], v[176:177], v[102:103] op_sel:[1,1] op_sel_hi:[0,1]
	v_pk_fma_f32 v[176:177], v[176:177], v[102:103], v[182:183] op_sel_hi:[1,0,1] neg_lo:[0,0,1]
	s_waitcnt lgkmcnt(2)
	v_pk_add_f32 v[184:185], v[184:185], v[186:187] neg_hi:[0,1]
	v_pk_mul_f32 v[180:181], v[112:113], v[184:185] op_sel:[1,1] op_sel_hi:[0,1]
	v_pk_fma_f32 v[112:113], v[112:113], v[184:185], v[180:181] op_sel_hi:[1,0,1] neg_lo:[0,0,1]
	s_waitcnt lgkmcnt(0)
	v_pk_add_f32 v[168:169], v[168:169], v[188:189] neg_hi:[0,1]
	v_pk_mul_f32 v[182:183], v[114:115], v[168:169] op_sel:[1,1] op_sel_hi:[0,1]
	v_pk_fma_f32 v[114:115], v[114:115], v[168:169], v[182:183] op_sel_hi:[1,0,1] neg_lo:[0,0,1]
	ds_read_b64 v[180:181], v200 offset:128
	ds_read_b64 v[184:185], v202 offset:120
	ds_read_b64 v[182:183], v200 offset:144
	ds_read_b64 v[168:169], v202 offset:104
	ds_read_b64 v[110:111], v200 offset:160
	ds_read_b64 v[126:127], v202 offset:88
	ds_read_b64 v[102:103], v200 offset:176
	ds_read_b64 v[118:119], v202 offset:72
	s_waitcnt lgkmcnt(6)
	v_pk_add_f32 v[180:181], v[180:181], v[184:185] neg_hi:[0,1]
	v_pk_mul_f32 v[186:187], v[116:117], v[180:181] op_sel:[1,1] op_sel_hi:[0,1]
	v_pk_fma_f32 v[116:117], v[116:117], v[180:181], v[186:187] op_sel_hi:[1,0,1] neg_lo:[0,0,1]
	s_waitcnt lgkmcnt(4)
	v_pk_add_f32 v[182:183], v[182:183], v[168:169] neg_hi:[0,1]
	v_pk_mul_f32 v[188:189], v[166:167], v[182:183] op_sel:[1,1] op_sel_hi:[0,1]
	v_pk_fma_f32 v[166:167], v[166:167], v[182:183], v[188:189] op_sel_hi:[1,0,1] neg_lo:[0,0,1]
	s_waitcnt lgkmcnt(2)
	v_pk_add_f32 v[110:111], v[110:111], v[126:127] neg_hi:[0,1]
	v_pk_mul_f32 v[186:187], v[120:121], v[110:111] op_sel:[1,1] op_sel_hi:[0,1]
	v_pk_fma_f32 v[120:121], v[120:121], v[110:111], v[186:187] op_sel_hi:[1,0,1] neg_lo:[0,0,1]
	s_waitcnt lgkmcnt(0)
	v_pk_add_f32 v[102:103], v[102:103], v[118:119] neg_hi:[0,1]
	v_pk_mul_f32 v[188:189], v[122:123], v[102:103] op_sel:[1,1] op_sel_hi:[0,1]
	v_pk_fma_f32 v[122:123], v[122:123], v[102:103], v[188:189] op_sel_hi:[1,0,1] neg_lo:[0,0,1]
	ds_read_b64 v[186:187], v200 offset:192
	ds_read_b64 v[110:111], v202 offset:56
	ds_read_b64 v[188:189], v200 offset:208
	ds_read_b64 v[102:103], v202 offset:40
	ds_read_b64 v[180:181], v200 offset:224
	ds_read_b64 v[184:185], v202 offset:24
	ds_read_b64 v[182:183], v200 offset:240
	ds_read_b64 v[168:169], v202 offset:8
	s_waitcnt lgkmcnt(6)
	v_pk_add_f32 v[186:187], v[186:187], v[110:111] neg_hi:[0,1]
	v_pk_mul_f32 v[126:127], v[124:125], v[186:187] op_sel:[1,1] op_sel_hi:[0,1]
	v_pk_fma_f32 v[124:125], v[124:125], v[186:187], v[126:127] op_sel_hi:[1,0,1] neg_lo:[0,0,1]
	s_waitcnt lgkmcnt(4)
	v_pk_add_f32 v[188:189], v[188:189], v[102:103] neg_hi:[0,1]
	v_pk_mul_f32 v[118:119], v[174:175], v[188:189] op_sel:[1,1] op_sel_hi:[0,1]
	v_pk_fma_f32 v[174:175], v[174:175], v[188:189], v[118:119] op_sel_hi:[1,0,1] neg_lo:[0,0,1]
	s_waitcnt lgkmcnt(2)
	v_pk_add_f32 v[180:181], v[180:181], v[184:185] neg_hi:[0,1]
	v_pk_mul_f32 v[126:127], v[128:129], v[180:181] op_sel:[1,1] op_sel_hi:[0,1]
	v_pk_fma_f32 v[128:129], v[128:129], v[180:181], v[126:127] op_sel_hi:[1,0,1] neg_lo:[0,0,1]
	s_waitcnt lgkmcnt(0)
	v_pk_add_f32 v[182:183], v[182:183], v[168:169] neg_hi:[0,1]
	v_pk_mul_f32 v[118:119], v[130:131], v[182:183] op_sel:[1,1] op_sel_hi:[0,1]
	v_pk_fma_f32 v[130:131], v[130:131], v[182:183], v[118:119] op_sel_hi:[1,0,1] neg_lo:[0,0,1]
	v_pk_add_f32 v[126:127], v[100:101], v[116:117]
	v_pk_add_f32 v[118:119], v[100:101], v[116:117] neg_lo:[0,1] neg_hi:[0,1]
	v_pk_add_f32 v[186:187], v[108:109], v[124:125]
	v_pk_add_f32 v[188:189], v[108:109], v[124:125] neg_lo:[0,1] neg_hi:[0,1]
	v_pk_add_f32 v[100:101], v[126:127], v[186:187]
	v_pk_add_f32 v[116:117], v[126:127], v[186:187] neg_lo:[0,1] neg_hi:[0,1]
	v_pk_add_f32 v[108:109], v[118:119], v[188:189] op_sel:[0,1] op_sel_hi:[1,0] neg_lo:[0,1]
	v_pk_add_f32 v[124:125], v[118:119], v[188:189] op_sel:[0,1] op_sel_hi:[1,0] neg_hi:[0,1]
	v_pk_add_f32 v[180:181], v[178:179], v[166:167]
	v_pk_add_f32 v[182:183], v[178:179], v[166:167] neg_lo:[0,1] neg_hi:[0,1]
	v_pk_add_f32 v[110:111], v[176:177], v[174:175]
	v_pk_add_f32 v[102:103], v[176:177], v[174:175] neg_lo:[0,1] neg_hi:[0,1]
	v_pk_add_f32 v[178:179], v[180:181], v[110:111]
	v_pk_add_f32 v[166:167], v[180:181], v[110:111] neg_lo:[0,1] neg_hi:[0,1]
	v_pk_add_f32 v[176:177], v[182:183], v[102:103] op_sel:[0,1] op_sel_hi:[1,0] neg_lo:[0,1]
	v_pk_add_f32 v[174:175], v[182:183], v[102:103] op_sel:[0,1] op_sel_hi:[1,0] neg_hi:[0,1]
	v_pk_add_f32 v[184:185], v[104:105], v[120:121]
	v_pk_add_f32 v[168:169], v[104:105], v[120:121] neg_lo:[0,1] neg_hi:[0,1]
	v_pk_add_f32 v[126:127], v[112:113], v[128:129]
	v_pk_add_f32 v[118:119], v[112:113], v[128:129] neg_lo:[0,1] neg_hi:[0,1]
	v_pk_add_f32 v[104:105], v[184:185], v[126:127]
	v_pk_add_f32 v[120:121], v[184:185], v[126:127] neg_lo:[0,1] neg_hi:[0,1]
	v_pk_add_f32 v[112:113], v[168:169], v[118:119] op_sel:[0,1] op_sel_hi:[1,0] neg_lo:[0,1]
	v_pk_add_f32 v[128:129], v[168:169], v[118:119] op_sel:[0,1] op_sel_hi:[1,0] neg_hi:[0,1]
	v_pk_add_f32 v[186:187], v[106:107], v[122:123]
	v_pk_add_f32 v[188:189], v[106:107], v[122:123] neg_lo:[0,1] neg_hi:[0,1]
	v_pk_add_f32 v[180:181], v[114:115], v[130:131]
	v_pk_add_f32 v[182:183], v[114:115], v[130:131] neg_lo:[0,1] neg_hi:[0,1]
	v_pk_add_f32 v[106:107], v[186:187], v[180:181]
; __device__ __forceinline__ f32x2 cmulc(f32x2 a, f32x2 b) { return (f32x2){a.x * b.x + a.y * b.y, a.y * b.x - a.x * b.y}; }
; template <bool INV> __device__ __forceinline__ f32x2 cmul_tw(f32x2 a, f32x2 w) { return INV ? cmulc(a, w) : cmul(a, w); }
; template <bool INV> __device__ __forceinline__ void dft16(f32x2 (&x)[16]) {
;     constexpr float C1 = 0.92387953251128674f, S1 = 0.38268343236508977f, C2 = 0.70710678118654752f;
; #pragma unroll
;     for (int b = 0; b < 4; ++b) dft4<INV>(x[b], x[4 + b], x[8 + b], x[12 + b]);
;     const f32x2 w1 = {C1, -S1}, w2 = {C2, -C2}, w3 = {S1, -C1}, w4 = {0.f, -1.f}, w6 = {-C2, -C2}, w9 = {-C1, S1};
;     x[4 * 1 + 1] = cmul_tw<INV>(x[5], w1); x[4 * 1 + 2] = cmul_tw<INV>(x[6], w2); x[4 * 1 + 3] = cmul_tw<INV>(x[7], w3);
;     x[4 * 2 + 1] = cmul_tw<INV>(x[9], w2); x[4 * 2 + 2] = cmul_tw<INV>(x[10], w4); x[4 * 2 + 3] = cmul_tw<INV>(x[11], w6);
;     x[4 * 3 + 1] = cmul_tw<INV>(x[13], w3); x[4 * 3 + 2] = cmul_tw<INV>(x[14], w6); x[4 * 3 + 3] = cmul_tw<INV>(x[15], w9);
; #pragma unroll
;     for (int c = 0; c < 4; ++c) dft4<INV>(x[4 * c], x[4 * c + 1], x[4 * c + 2], x[4 * c + 3]);
;     f32x2 y[16];
; #pragma unroll
;     for (int k = 0; k < 16; ++k) y[k] = x[4 * (k & 3) + (k >> 2)];
; #pragma unroll
;     for (int k = 0; k < 16; ++k) x[k] = y[k];
; template <int MODE> __device__ __forceinline__ void fft_pair32(LAS f32x2* B, const LAS f32x2* F, int wave, int lane) {
;     ...
;     dft16<true>(v);
; #pragma unroll
;     for (int j = 0; j < 16; ++j) { const f32x2 w = {hi ? CS[j] : 1.f, hi ? -SN[j] : 0.f}; const f32x2 u = j == 0 ? v[j] : cmulc(v[j], w);
;         const auto rx = __builtin_amdgcn_permlane32_swap(__float_as_uint(u.x), __float_as_uint(u.x), false, false);
;         const auto ry = __builtin_amdgcn_permlane32_swap(__float_as_uint(u.y), __float_as_uint(u.y), false, false);
;         const f32x2 a = {__uint_as_float(rx[0]), __uint_as_float(ry[0])}, b = {__uint_as_float(rx[1]), __uint_as_float(ry[1])};
;         p[16 * hi + j] = a + b * sg; }
	v_pk_add_f32 v[122:123], v[186:187], v[180:181] neg_lo:[0,1] neg_hi:[0,1]
	v_pk_add_f32 v[114:115], v[188:189], v[182:183] op_sel:[0,1] op_sel_hi:[1,0] neg_lo:[0,1]
	v_pk_add_f32 v[130:131], v[188:189], v[182:183] op_sel:[0,1] op_sel_hi:[1,0] neg_hi:[0,1]
	v_pk_mul_f32 v[110:111], v[176:177], s[68:69] op_sel:[1,1] op_sel_hi:[0,1]
	v_pk_fma_f32 v[176:177], v[176:177], s[68:69], v[110:111] op_sel_hi:[1,0,1] neg_hi:[0,0,1]
	v_pk_mul_f32 v[102:103], v[112:113], s[84:85] op_sel:[1,1] op_sel_hi:[0,1]
	v_pk_fma_f32 v[112:113], v[112:113], s[84:85], v[102:103] op_sel_hi:[1,0,1] neg_hi:[0,0,1]
	v_pk_mul_f32 v[184:185], v[114:115], s[88:89] op_sel:[1,1] op_sel_hi:[0,1]
	v_pk_fma_f32 v[114:115], v[114:115], s[88:89], v[184:185] op_sel_hi:[1,0,1] neg_hi:[0,0,1]
	v_pk_mul_f32 v[168:169], v[166:167], s[84:85] op_sel:[1,1] op_sel_hi:[0,1]
	v_pk_fma_f32 v[166:167], v[166:167], s[84:85], v[168:169] op_sel_hi:[1,0,1] neg_hi:[0,0,1]
	v_pk_mul_f32 v[126:127], v[122:123], s[90:91] op_sel:[1,1] op_sel_hi:[0,1]
	v_pk_fma_f32 v[122:123], v[122:123], s[90:91], v[126:127] op_sel_hi:[1,0,1] neg_hi:[0,0,1]
	v_pk_mul_f32 v[118:119], v[174:175], s[88:89] op_sel:[1,1] op_sel_hi:[0,1]
	v_pk_fma_f32 v[174:175], v[174:175], s[88:89], v[118:119] op_sel_hi:[1,0,1] neg_hi:[0,0,1]
	v_pk_mul_f32 v[186:187], v[128:129], s[90:91] op_sel:[1,1] op_sel_hi:[0,1]
	v_pk_fma_f32 v[128:129], v[128:129], s[90:91], v[186:187] op_sel_hi:[1,0,1] neg_hi:[0,0,1]
	v_pk_mul_f32 v[188:189], v[130:131], s[98:99] op_sel:[1,1] op_sel_hi:[0,1]
	v_pk_fma_f32 v[130:131], v[130:131], s[98:99], v[188:189] op_sel_hi:[1,0,1] neg_hi:[0,0,1]
	v_pk_add_f32 v[180:181], v[100:101], v[104:105]
	v_pk_add_f32 v[182:183], v[100:101], v[104:105] neg_lo:[0,1] neg_hi:[0,1]
	v_pk_add_f32 v[110:111], v[178:179], v[106:107]
	v_pk_add_f32 v[102:103], v[178:179], v[106:107] neg_lo:[0,1] neg_hi:[0,1]
	v_pk_add_f32 v[100:101], v[180:181], v[110:111]
	v_pk_add_f32 v[104:105], v[180:181], v[110:111] neg_lo:[0,1] neg_hi:[0,1]
	v_pk_add_f32 v[178:179], v[182:183], v[102:103] op_sel:[0,1] op_sel_hi:[1,0] neg_lo:[0,1]
	v_pk_add_f32 v[106:107], v[182:183], v[102:103] op_sel:[0,1] op_sel_hi:[1,0] neg_hi:[0,1]
	v_pk_add_f32 v[184:185], v[108:109], v[112:113]
	v_pk_add_f32 v[168:169], v[108:109], v[112:113] neg_lo:[0,1] neg_hi:[0,1]
	v_pk_add_f32 v[126:127], v[176:177], v[114:115]
	v_pk_add_f32 v[118:119], v[176:177], v[114:115] neg_lo:[0,1] neg_hi:[0,1]
	v_pk_add_f32 v[108:109], v[184:185], v[126:127]
	v_pk_add_f32 v[112:113], v[184:185], v[126:127] neg_lo:[0,1] neg_hi:[0,1]
	v_pk_add_f32 v[176:177], v[168:169], v[118:119] op_sel:[0,1] op_sel_hi:[1,0] neg_lo:[0,1]
	v_pk_add_f32 v[114:115], v[168:169], v[118:119] op_sel:[0,1] op_sel_hi:[1,0] neg_hi:[0,1]
	v_pk_add_f32 v[186:187], v[116:117], v[120:121] op_sel:[0,1] op_sel_hi:[1,0] neg_lo:[0,1]
	v_pk_add_f32 v[188:189], v[116:117], v[120:121] op_sel:[0,1] op_sel_hi:[1,0] neg_hi:[0,1]
	v_pk_add_f32 v[180:181], v[166:167], v[122:123]
	v_pk_add_f32 v[182:183], v[166:167], v[122:123] neg_lo:[0,1] neg_hi:[0,1]
	v_pk_add_f32 v[116:117], v[186:187], v[180:181]
	v_pk_add_f32 v[120:121], v[186:187], v[180:181] neg_lo:[0,1] neg_hi:[0,1]
	v_pk_add_f32 v[166:167], v[188:189], v[182:183] op_sel:[0,1] op_sel_hi:[1,0] neg_lo:[0,1]
	v_pk_add_f32 v[122:123], v[188:189], v[182:183] op_sel:[0,1] op_sel_hi:[1,0] neg_hi:[0,1]
	v_pk_add_f32 v[110:111], v[124:125], v[128:129]
	v_pk_add_f32 v[102:103], v[124:125], v[128:129] neg_lo:[0,1] neg_hi:[0,1]
	v_pk_add_f32 v[184:185], v[174:175], v[130:131]
	v_pk_add_f32 v[168:169], v[174:175], v[130:131] neg_lo:[0,1] neg_hi:[0,1]
	v_pk_add_f32 v[124:125], v[110:111], v[184:185]
	v_pk_add_f32 v[128:129], v[110:111], v[184:185] neg_lo:[0,1] neg_hi:[0,1]
	v_pk_add_f32 v[174:175], v[102:103], v[168:169] op_sel:[0,1] op_sel_hi:[1,0] neg_lo:[0,1]
	v_pk_add_f32 v[130:131], v[102:103], v[168:169] op_sel:[0,1] op_sel_hi:[1,0] neg_hi:[0,1]
	v_mov_b32_e32 v126, v100
	v_mov_b32_e32 v127, v101
	v_pk_mul_f32 v[180:181], v[108:109], v[36:37] op_sel:[1,1] op_sel_hi:[0,1]
	v_pk_fma_f32 v[118:119], v[108:109], v[36:37], v[180:181] op_sel_hi:[1,0,1] neg_hi:[0,0,1]
	v_pk_fma_f32 v[108:109], v[108:109], v[36:37], v[180:181] op_sel_hi:[1,0,1] neg_hi:[0,0,1]
	v_pk_mul_f32 v[182:183], v[116:117], v[38:39] op_sel:[1,1] op_sel_hi:[0,1]
	v_pk_fma_f32 v[186:187], v[116:117], v[38:39], v[182:183] op_sel_hi:[1,0,1] neg_hi:[0,0,1]
	v_pk_fma_f32 v[116:117], v[116:117], v[38:39], v[182:183] op_sel_hi:[1,0,1] neg_hi:[0,0,1]
	v_pk_mul_f32 v[110:111], v[124:125], v[40:41] op_sel:[1,1] op_sel_hi:[0,1]
	v_pk_fma_f32 v[188:189], v[124:125], v[40:41], v[110:111] op_sel_hi:[1,0,1] neg_hi:[0,0,1]
	v_pk_fma_f32 v[124:125], v[124:125], v[40:41], v[110:111] op_sel_hi:[1,0,1] neg_hi:[0,0,1]
	s_nop 1
	v_permlane32_swap_b32_e32 v100, v126
	v_permlane32_swap_b32_e32 v101, v127
	v_permlane32_swap_b32_e32 v108, v118
	v_permlane32_swap_b32_e32 v109, v119
	v_permlane32_swap_b32_e32 v116, v186
	v_permlane32_swap_b32_e32 v117, v187
	v_permlane32_swap_b32_e32 v124, v188
	v_permlane32_swap_b32_e32 v125, v189
	v_pk_fma_f32 v[100:101], v[126:127], v[190:191], v[100:101] op_sel_hi:[1,0,1]
	ds_write_b64 v198, v[100:101]
	v_pk_fma_f32 v[108:109], v[118:119], v[190:191], v[108:109] op_sel_hi:[1,0,1]
	ds_write_b64 v198, v[108:109] offset:8
	v_pk_fma_f32 v[116:117], v[186:187], v[190:191], v[116:117] op_sel_hi:[1,0,1]
	ds_write_b64 v198, v[116:117] offset:16
	v_pk_fma_f32 v[124:125], v[188:189], v[190:191], v[124:125] op_sel_hi:[1,0,1]
	ds_write_b64 v198, v[124:125] offset:24
	v_pk_mul_f32 v[182:183], v[178:179], v[42:43] op_sel:[1,1] op_sel_hi:[0,1]
	v_pk_fma_f32 v[102:103], v[178:179], v[42:43], v[182:183] op_sel_hi:[1,0,1] neg_hi:[0,0,1]
; #define LAS __attribute__((address_space(3)))
; __device__ __forceinline__ f32x2 cmulc(f32x2 a, f32x2 b) { return (f32x2){a.x * b.x + a.y * b.y, a.y * b.x - a.x * b.y}; }
; __device__ __forceinline__ void fft_inv2(LAS f32x2* B, const LAS f32x2* TW2, int tid) {
;     asm volatile("" : "+v"(tid));
;     const int b = tid >> 5, n2 = tid & 31, base = 512 * b + n2; f32x2 x[16];
;     x[0] = B[fpad(base)];
; #pragma unroll
;     for (int k = 1; k < 16; ++k) x[k] = cmulc(B[fpad(base + 32 * k)], TW2[k * 32 + n2]);
; template <int MODE> __device__ __forceinline__ void fft_pair32(LAS f32x2* B, const LAS f32x2* F, int wave, int lane) {
;     ...
;     for (int j = 0; j < 16; ++j) { const f32x2 w = {hi ? CS[j] : 1.f, hi ? -SN[j] : 0.f}; const f32x2 u = j == 0 ? v[j] : cmulc(v[j], w);
;         const auto rx = __builtin_amdgcn_permlane32_swap(__float_as_uint(u.x), __float_as_uint(u.x), false, false);
;         const auto ry = __builtin_amdgcn_permlane32_swap(__float_as_uint(u.y), __float_as_uint(u.y), false, false);
;         const f32x2 a = {__uint_as_float(rx[0]), __uint_as_float(ry[0])}, b = {__uint_as_float(rx[1]), __uint_as_float(ry[1])};
;         p[16 * hi + j] = a + b * sg; }
	v_pk_fma_f32 v[178:179], v[178:179], v[42:43], v[182:183] op_sel_hi:[1,0,1] neg_hi:[0,0,1]
	v_pk_mul_f32 v[110:111], v[176:177], v[44:45] op_sel:[1,1] op_sel_hi:[0,1]
	v_pk_fma_f32 v[184:185], v[176:177], v[44:45], v[110:111] op_sel_hi:[1,0,1] neg_hi:[0,0,1]
	v_pk_fma_f32 v[176:177], v[176:177], v[44:45], v[110:111] op_sel_hi:[1,0,1] neg_hi:[0,0,1]
	v_pk_mul_f32 v[126:127], v[166:167], v[46:47] op_sel:[1,1] op_sel_hi:[0,1]
	v_pk_fma_f32 v[168:169], v[166:167], v[46:47], v[126:127] op_sel_hi:[1,0,1] neg_hi:[0,0,1]
	v_pk_fma_f32 v[166:167], v[166:167], v[46:47], v[126:127] op_sel_hi:[1,0,1] neg_hi:[0,0,1]
	v_pk_mul_f32 v[118:119], v[174:175], v[48:49] op_sel:[1,1] op_sel_hi:[0,1]
	v_pk_fma_f32 v[180:181], v[174:175], v[48:49], v[118:119] op_sel_hi:[1,0,1] neg_hi:[0,0,1]
	v_pk_fma_f32 v[174:175], v[174:175], v[48:49], v[118:119] op_sel_hi:[1,0,1] neg_hi:[0,0,1]
	s_nop 1
	v_permlane32_swap_b32_e32 v178, v102
	v_permlane32_swap_b32_e32 v179, v103
	v_permlane32_swap_b32_e32 v176, v184
	v_permlane32_swap_b32_e32 v177, v185
	v_permlane32_swap_b32_e32 v166, v168
	v_permlane32_swap_b32_e32 v167, v169
	v_permlane32_swap_b32_e32 v174, v180
	v_permlane32_swap_b32_e32 v175, v181
	v_pk_fma_f32 v[178:179], v[102:103], v[190:191], v[178:179] op_sel_hi:[1,0,1]
	ds_write_b64 v198, v[178:179] offset:32
	v_pk_fma_f32 v[176:177], v[184:185], v[190:191], v[176:177] op_sel_hi:[1,0,1]
	ds_write_b64 v198, v[176:177] offset:40
	v_pk_fma_f32 v[166:167], v[168:169], v[190:191], v[166:167] op_sel_hi:[1,0,1]
	ds_write_b64 v198, v[166:167] offset:48
	v_pk_fma_f32 v[174:175], v[180:181], v[190:191], v[174:175] op_sel_hi:[1,0,1]
	ds_write_b64 v198, v[174:175] offset:56
	v_pk_mul_f32 v[126:127], v[104:105], v[50:51] op_sel:[1,1] op_sel_hi:[0,1]
	v_pk_fma_f32 v[186:187], v[104:105], v[50:51], v[126:127] op_sel_hi:[1,0,1] neg_hi:[0,0,1]
	v_pk_fma_f32 v[104:105], v[104:105], v[50:51], v[126:127] op_sel_hi:[1,0,1] neg_hi:[0,0,1]
	v_pk_mul_f32 v[118:119], v[112:113], v[52:53] op_sel:[1,1] op_sel_hi:[0,1]
	v_pk_fma_f32 v[188:189], v[112:113], v[52:53], v[118:119] op_sel_hi:[1,0,1] neg_hi:[0,0,1]
	v_pk_fma_f32 v[112:113], v[112:113], v[52:53], v[118:119] op_sel_hi:[1,0,1] neg_hi:[0,0,1]
	v_pk_mul_f32 v[102:103], v[120:121], v[54:55] op_sel:[1,1] op_sel_hi:[0,1]
	v_pk_fma_f32 v[182:183], v[120:121], v[54:55], v[102:103] op_sel_hi:[1,0,1] neg_hi:[0,0,1]
	v_pk_fma_f32 v[120:121], v[120:121], v[54:55], v[102:103] op_sel_hi:[1,0,1] neg_hi:[0,0,1]
	v_pk_mul_f32 v[184:185], v[128:129], v[90:91] op_sel:[1,1] op_sel_hi:[0,1]
	v_pk_fma_f32 v[110:111], v[128:129], v[90:91], v[184:185] op_sel_hi:[1,0,1] neg_hi:[0,0,1]
	v_pk_fma_f32 v[128:129], v[128:129], v[90:91], v[184:185] op_sel_hi:[1,0,1] neg_hi:[0,0,1]
	s_nop 1
	v_permlane32_swap_b32_e32 v104, v186
	v_permlane32_swap_b32_e32 v105, v187
	v_permlane32_swap_b32_e32 v112, v188
	v_permlane32_swap_b32_e32 v113, v189
	v_permlane32_swap_b32_e32 v120, v182
	v_permlane32_swap_b32_e32 v121, v183
	v_permlane32_swap_b32_e32 v128, v110
	v_permlane32_swap_b32_e32 v129, v111
	v_pk_fma_f32 v[104:105], v[186:187], v[190:191], v[104:105] op_sel_hi:[1,0,1]
	ds_write_b64 v198, v[104:105] offset:64
	v_pk_fma_f32 v[112:113], v[188:189], v[190:191], v[112:113] op_sel_hi:[1,0,1]
	ds_write_b64 v198, v[112:113] offset:72
	v_pk_fma_f32 v[120:121], v[182:183], v[190:191], v[120:121] op_sel_hi:[1,0,1]
	ds_write_b64 v198, v[120:121] offset:80
	v_pk_fma_f32 v[128:129], v[110:111], v[190:191], v[128:129] op_sel_hi:[1,0,1]
	ds_write_b64 v198, v[128:129] offset:88
	v_pk_mul_f32 v[102:103], v[106:107], v[92:93] op_sel:[1,1] op_sel_hi:[0,1]
	v_pk_fma_f32 v[168:169], v[106:107], v[92:93], v[102:103] op_sel_hi:[1,0,1] neg_hi:[0,0,1]
	v_pk_fma_f32 v[106:107], v[106:107], v[92:93], v[102:103] op_sel_hi:[1,0,1] neg_hi:[0,0,1]
	v_pk_mul_f32 v[184:185], v[114:115], v[94:95] op_sel:[1,1] op_sel_hi:[0,1]
	v_pk_fma_f32 v[180:181], v[114:115], v[94:95], v[184:185] op_sel_hi:[1,0,1] neg_hi:[0,0,1]
	v_pk_fma_f32 v[114:115], v[114:115], v[94:95], v[184:185] op_sel_hi:[1,0,1] neg_hi:[0,0,1]
	v_pk_mul_f32 v[186:187], v[122:123], v[96:97] op_sel:[1,1] op_sel_hi:[0,1]
	v_pk_fma_f32 v[126:127], v[122:123], v[96:97], v[186:187] op_sel_hi:[1,0,1] neg_hi:[0,0,1]
	v_pk_fma_f32 v[122:123], v[122:123], v[96:97], v[186:187] op_sel_hi:[1,0,1] neg_hi:[0,0,1]
	v_pk_mul_f32 v[188:189], v[130:131], v[98:99] op_sel:[1,1] op_sel_hi:[0,1]
	v_pk_fma_f32 v[118:119], v[130:131], v[98:99], v[188:189] op_sel_hi:[1,0,1] neg_hi:[0,0,1]
	v_pk_fma_f32 v[130:131], v[130:131], v[98:99], v[188:189] op_sel_hi:[1,0,1] neg_hi:[0,0,1]
	s_nop 1
	v_permlane32_swap_b32_e32 v106, v168
	v_permlane32_swap_b32_e32 v107, v169
	v_permlane32_swap_b32_e32 v114, v180
	v_permlane32_swap_b32_e32 v115, v181
	v_permlane32_swap_b32_e32 v122, v126
	v_permlane32_swap_b32_e32 v123, v127
	v_permlane32_swap_b32_e32 v130, v118
	v_permlane32_swap_b32_e32 v131, v119
	v_pk_fma_f32 v[106:107], v[168:169], v[190:191], v[106:107] op_sel_hi:[1,0,1]
	ds_write_b64 v198, v[106:107] offset:96
	v_pk_fma_f32 v[114:115], v[180:181], v[190:191], v[114:115] op_sel_hi:[1,0,1]
	ds_write_b64 v198, v[114:115] offset:104
	v_pk_fma_f32 v[122:123], v[126:127], v[190:191], v[122:123] op_sel_hi:[1,0,1]
	ds_write_b64 v198, v[122:123] offset:112
	v_pk_fma_f32 v[130:131], v[118:119], v[190:191], v[130:131] op_sel_hi:[1,0,1]
	ds_write_b64 v198, v[130:131] offset:120
	s_waitcnt lgkmcnt(0)
	ds_read_b64 v[100:101], v5
	ds_read_b64 v[108:109], v5 offset:264
	ds_read_b64 v[182:183], v56 offset:256
	ds_read_b64 v[116:117], v5 offset:528
	ds_read_b64 v[110:111], v56 offset:512
	ds_read_b64 v[124:125], v5 offset:792
	ds_read_b64 v[102:103], v56 offset:768
	ds_read_b64 v[178:179], v5 offset:1056
	ds_read_b64 v[184:185], v56 offset:1024
	ds_read_b64 v[176:177], v5 offset:1320
	ds_read_b64 v[186:187], v56 offset:1280
	s_waitcnt lgkmcnt(8)
; #define LAS __attribute__((address_space(3)))
; __device__ __forceinline__ f32x2 cmulc(f32x2 a, f32x2 b) { return (f32x2){a.x * b.x + a.y * b.y, a.y * b.x - a.x * b.y}; }
; template <bool INV> __device__ __forceinline__ f32x2 cmul_tw(f32x2 a, f32x2 w) { return INV ? cmulc(a, w) : cmul(a, w); }
; template <bool INV> __device__ __forceinline__ void dft16(f32x2 (&x)[16]) {
;     constexpr float C1 = 0.92387953251128674f, S1 = 0.38268343236508977f, C2 = 0.70710678118654752f;
; #pragma unroll
;     for (int b = 0; b < 4; ++b) dft4<INV>(x[b], x[4 + b], x[8 + b], x[12 + b]);
;     const f32x2 w1 = {C1, -S1}, w2 = {C2, -C2}, w3 = {S1, -C1}, w4 = {0.f, -1.f}, w6 = {-C2, -C2}, w9 = {-C1, S1};
;     x[4 * 1 + 1] = cmul_tw<INV>(x[5], w1); x[4 * 1 + 2] = cmul_tw<INV>(x[6], w2); x[4 * 1 + 3] = cmul_tw<INV>(x[7], w3);
;     x[4 * 2 + 1] = cmul_tw<INV>(x[9], w2); x[4 * 2 + 2] = cmul_tw<INV>(x[10], w4); x[4 * 2 + 3] = cmul_tw<INV>(x[11], w6);
;     x[4 * 3 + 1] = cmul_tw<INV>(x[13], w3); x[4 * 3 + 2] = cmul_tw<INV>(x[14], w6); x[4 * 3 + 3] = cmul_tw<INV>(x[15], w9);
; #pragma unroll
;     for (int c = 0; c < 4; ++c) dft4<INV>(x[4 * c], x[4 * c + 1], x[4 * c + 2], x[4 * c + 3]);
; __device__ __forceinline__ void fft_inv2(LAS f32x2* B, const LAS f32x2* TW2, int tid) {
;     asm volatile("" : "+v"(tid));
;     const int b = tid >> 5, n2 = tid & 31, base = 512 * b + n2; f32x2 x[16];
;     x[0] = B[fpad(base)];
; #pragma unroll
;     for (int k = 1; k < 16; ++k) x[k] = cmulc(B[fpad(base + 32 * k)], TW2[k * 32 + n2]);
;     dft16<true>(x);
	v_pk_mul_f32 v[188:189], v[108:109], v[182:183] op_sel:[1,1] op_sel_hi:[0,1]
	v_pk_fma_f32 v[108:109], v[108:109], v[182:183], v[188:189] op_sel_hi:[1,0,1] neg_hi:[0,0,1]
	s_waitcnt lgkmcnt(6)
	v_pk_mul_f32 v[168:169], v[116:117], v[110:111] op_sel:[1,1] op_sel_hi:[0,1]
	v_pk_fma_f32 v[116:117], v[116:117], v[110:111], v[168:169] op_sel_hi:[1,0,1] neg_hi:[0,0,1]
	s_waitcnt lgkmcnt(4)
	v_pk_mul_f32 v[180:181], v[124:125], v[102:103] op_sel:[1,1] op_sel_hi:[0,1]
	v_pk_fma_f32 v[124:125], v[124:125], v[102:103], v[180:181] op_sel_hi:[1,0,1] neg_hi:[0,0,1]
	s_waitcnt lgkmcnt(2)
	v_pk_mul_f32 v[126:127], v[178:179], v[184:185] op_sel:[1,1] op_sel_hi:[0,1]
	v_pk_fma_f32 v[178:179], v[178:179], v[184:185], v[126:127] op_sel_hi:[1,0,1] neg_hi:[0,0,1]
	s_waitcnt lgkmcnt(0)
	v_pk_mul_f32 v[118:119], v[176:177], v[186:187] op_sel:[1,1] op_sel_hi:[0,1]
	v_pk_fma_f32 v[176:177], v[176:177], v[186:187], v[118:119] op_sel_hi:[1,0,1] neg_hi:[0,0,1]
	ds_read_b64 v[166:167], v5 offset:1584
	ds_read_b64 v[188:189], v56 offset:1536
	ds_read_b64 v[174:175], v5 offset:1848
	ds_read_b64 v[168:169], v56 offset:1792
	ds_read_b64 v[104:105], v5 offset:2112
	ds_read_b64 v[180:181], v56 offset:2048
	ds_read_b64 v[112:113], v5 offset:2376
	ds_read_b64 v[126:127], v56 offset:2304
	ds_read_b64 v[120:121], v5 offset:2640
	ds_read_b64 v[118:119], v56 offset:2560
	s_waitcnt lgkmcnt(8)
	v_pk_mul_f32 v[182:183], v[166:167], v[188:189] op_sel:[1,1] op_sel_hi:[0,1]
	v_pk_fma_f32 v[166:167], v[166:167], v[188:189], v[182:183] op_sel_hi:[1,0,1] neg_hi:[0,0,1]
	s_waitcnt lgkmcnt(6)
	v_pk_mul_f32 v[110:111], v[174:175], v[168:169] op_sel:[1,1] op_sel_hi:[0,1]
	v_pk_fma_f32 v[174:175], v[174:175], v[168:169], v[110:111] op_sel_hi:[1,0,1] neg_hi:[0,0,1]
	s_waitcnt lgkmcnt(4)
	v_pk_mul_f32 v[102:103], v[104:105], v[180:181] op_sel:[1,1] op_sel_hi:[0,1]
	v_pk_fma_f32 v[104:105], v[104:105], v[180:181], v[102:103] op_sel_hi:[1,0,1] neg_hi:[0,0,1]
	s_waitcnt lgkmcnt(2)
	v_pk_mul_f32 v[184:185], v[112:113], v[126:127] op_sel:[1,1] op_sel_hi:[0,1]
	v_pk_fma_f32 v[112:113], v[112:113], v[126:127], v[184:185] op_sel_hi:[1,0,1] neg_hi:[0,0,1]
	s_waitcnt lgkmcnt(0)
	v_pk_mul_f32 v[186:187], v[120:121], v[118:119] op_sel:[1,1] op_sel_hi:[0,1]
	v_pk_fma_f32 v[120:121], v[120:121], v[118:119], v[186:187] op_sel_hi:[1,0,1] neg_hi:[0,0,1]
	ds_read_b64 v[128:129], v5 offset:2904
	ds_read_b64 v[182:183], v56 offset:2816
	ds_read_b64 v[106:107], v5 offset:3168
	ds_read_b64 v[110:111], v56 offset:3072
	ds_read_b64 v[114:115], v5 offset:3432
	ds_read_b64 v[102:103], v56 offset:3328
	ds_read_b64 v[122:123], v5 offset:3696
	ds_read_b64 v[184:185], v56 offset:3584
	ds_read_b64 v[130:131], v5 offset:3960
	ds_read_b64 v[186:187], v56 offset:3840
	s_waitcnt lgkmcnt(8)
	v_pk_mul_f32 v[188:189], v[128:129], v[182:183] op_sel:[1,1] op_sel_hi:[0,1]
	v_pk_fma_f32 v[128:129], v[128:129], v[182:183], v[188:189] op_sel_hi:[1,0,1] neg_hi:[0,0,1]
	s_waitcnt lgkmcnt(6)
	v_pk_mul_f32 v[168:169], v[106:107], v[110:111] op_sel:[1,1] op_sel_hi:[0,1]
	v_pk_fma_f32 v[106:107], v[106:107], v[110:111], v[168:169] op_sel_hi:[1,0,1] neg_hi:[0,0,1]
	s_waitcnt lgkmcnt(4)
	v_pk_mul_f32 v[180:181], v[114:115], v[102:103] op_sel:[1,1] op_sel_hi:[0,1]
	v_pk_fma_f32 v[114:115], v[114:115], v[102:103], v[180:181] op_sel_hi:[1,0,1] neg_hi:[0,0,1]
	s_waitcnt lgkmcnt(2)
	v_pk_mul_f32 v[126:127], v[122:123], v[184:185] op_sel:[1,1] op_sel_hi:[0,1]
	v_pk_fma_f32 v[122:123], v[122:123], v[184:185], v[126:127] op_sel_hi:[1,0,1] neg_hi:[0,0,1]
	s_waitcnt lgkmcnt(0)
	v_pk_mul_f32 v[118:119], v[130:131], v[186:187] op_sel:[1,1] op_sel_hi:[0,1]
	v_pk_fma_f32 v[130:131], v[130:131], v[186:187], v[118:119] op_sel_hi:[1,0,1] neg_hi:[0,0,1]
	v_pk_add_f32 v[188:189], v[100:101], v[104:105]
	v_pk_add_f32 v[168:169], v[100:101], v[104:105] neg_lo:[0,1] neg_hi:[0,1]
	v_pk_add_f32 v[180:181], v[178:179], v[106:107]
	v_pk_add_f32 v[126:127], v[178:179], v[106:107] neg_lo:[0,1] neg_hi:[0,1]
	v_pk_add_f32 v[100:101], v[188:189], v[180:181]
	v_pk_add_f32 v[104:105], v[188:189], v[180:181] neg_lo:[0,1] neg_hi:[0,1]
	v_pk_add_f32 v[178:179], v[168:169], v[126:127] op_sel:[0,1] op_sel_hi:[1,0] neg_lo:[0,1]
	v_pk_add_f32 v[106:107], v[168:169], v[126:127] op_sel:[0,1] op_sel_hi:[1,0] neg_hi:[0,1]
	v_pk_add_f32 v[118:119], v[108:109], v[112:113]
	v_pk_add_f32 v[182:183], v[108:109], v[112:113] neg_lo:[0,1] neg_hi:[0,1]
	v_pk_add_f32 v[110:111], v[176:177], v[114:115]
	v_pk_add_f32 v[102:103], v[176:177], v[114:115] neg_lo:[0,1] neg_hi:[0,1]
	v_pk_add_f32 v[108:109], v[118:119], v[110:111]
	v_pk_add_f32 v[112:113], v[118:119], v[110:111] neg_lo:[0,1] neg_hi:[0,1]
	v_pk_add_f32 v[176:177], v[182:183], v[102:103] op_sel:[0,1] op_sel_hi:[1,0] neg_lo:[0,1]
	v_pk_add_f32 v[114:115], v[182:183], v[102:103] op_sel:[0,1] op_sel_hi:[1,0] neg_hi:[0,1]
	v_pk_add_f32 v[184:185], v[116:117], v[120:121]
	v_pk_add_f32 v[186:187], v[116:117], v[120:121] neg_lo:[0,1] neg_hi:[0,1]
	v_pk_add_f32 v[188:189], v[166:167], v[122:123]
	v_pk_add_f32 v[168:169], v[166:167], v[122:123] neg_lo:[0,1] neg_hi:[0,1]
	v_pk_add_f32 v[116:117], v[184:185], v[188:189]
	v_pk_add_f32 v[120:121], v[184:185], v[188:189] neg_lo:[0,1] neg_hi:[0,1]
	v_pk_add_f32 v[166:167], v[186:187], v[168:169] op_sel:[0,1] op_sel_hi:[1,0] neg_lo:[0,1]
	v_pk_add_f32 v[122:123], v[186:187], v[168:169] op_sel:[0,1] op_sel_hi:[1,0] neg_hi:[0,1]
	v_pk_add_f32 v[180:181], v[124:125], v[128:129]
	v_pk_add_f32 v[126:127], v[124:125], v[128:129] neg_lo:[0,1] neg_hi:[0,1]
	v_pk_add_f32 v[118:119], v[174:175], v[130:131]
	v_pk_add_f32 v[182:183], v[174:175], v[130:131] neg_lo:[0,1] neg_hi:[0,1]
	v_pk_add_f32 v[124:125], v[180:181], v[118:119]
; template <bool INV> __device__ __forceinline__ f32x2 cmul_tw(f32x2 a, f32x2 w) { return INV ? cmulc(a, w) : cmul(a, w); }
; template <bool INV> __device__ __forceinline__ void dft16(f32x2 (&x)[16]) {
;     constexpr float C1 = 0.92387953251128674f, S1 = 0.38268343236508977f, C2 = 0.70710678118654752f;
; #pragma unroll
;     for (int b = 0; b < 4; ++b) dft4<INV>(x[b], x[4 + b], x[8 + b], x[12 + b]);
;     const f32x2 w1 = {C1, -S1}, w2 = {C2, -C2}, w3 = {S1, -C1}, w4 = {0.f, -1.f}, w6 = {-C2, -C2}, w9 = {-C1, S1};
;     x[4 * 1 + 1] = cmul_tw<INV>(x[5], w1); x[4 * 1 + 2] = cmul_tw<INV>(x[6], w2); x[4 * 1 + 3] = cmul_tw<INV>(x[7], w3);
;     x[4 * 2 + 1] = cmul_tw<INV>(x[9], w2); x[4 * 2 + 2] = cmul_tw<INV>(x[10], w4); x[4 * 2 + 3] = cmul_tw<INV>(x[11], w6);
;     x[4 * 3 + 1] = cmul_tw<INV>(x[13], w3); x[4 * 3 + 2] = cmul_tw<INV>(x[14], w6); x[4 * 3 + 3] = cmul_tw<INV>(x[15], w9);
; #pragma unroll
;     for (int c = 0; c < 4; ++c) dft4<INV>(x[4 * c], x[4 * c + 1], x[4 * c + 2], x[4 * c + 3]);
;     f32x2 y[16];
; #pragma unroll
;     for (int k = 0; k < 16; ++k) y[k] = x[4 * (k & 3) + (k >> 2)];
; #pragma unroll
;     for (int k = 0; k < 16; ++k) x[k] = y[k];
; __device__ __forceinline__ void fft_inv2(LAS f32x2* B, const LAS f32x2* TW2, int tid) {
;     ...
;     dft16<true>(x);
; #pragma unroll
;     for (int r = 0; r < 16; ++r) B[fpad(base + 32 * r)] = x[r];
; }
	v_pk_add_f32 v[128:129], v[180:181], v[118:119] neg_lo:[0,1] neg_hi:[0,1]
	v_pk_add_f32 v[174:175], v[126:127], v[182:183] op_sel:[0,1] op_sel_hi:[1,0] neg_lo:[0,1]
	v_pk_add_f32 v[130:131], v[126:127], v[182:183] op_sel:[0,1] op_sel_hi:[1,0] neg_hi:[0,1]
	v_pk_mul_f32 v[110:111], v[176:177], s[68:69] op_sel:[1,1] op_sel_hi:[0,1]
	v_pk_fma_f32 v[176:177], v[176:177], s[68:69], v[110:111] op_sel_hi:[1,0,1] neg_hi:[0,0,1]
	v_pk_mul_f32 v[102:103], v[166:167], s[84:85] op_sel:[1,1] op_sel_hi:[0,1]
	v_pk_fma_f32 v[166:167], v[166:167], s[84:85], v[102:103] op_sel_hi:[1,0,1] neg_hi:[0,0,1]
	v_pk_mul_f32 v[184:185], v[174:175], s[88:89] op_sel:[1,1] op_sel_hi:[0,1]
	v_pk_fma_f32 v[174:175], v[174:175], s[88:89], v[184:185] op_sel_hi:[1,0,1] neg_hi:[0,0,1]
	v_pk_mul_f32 v[186:187], v[112:113], s[84:85] op_sel:[1,1] op_sel_hi:[0,1]
	v_pk_fma_f32 v[112:113], v[112:113], s[84:85], v[186:187] op_sel_hi:[1,0,1] neg_hi:[0,0,1]
	v_pk_mul_f32 v[188:189], v[128:129], s[90:91] op_sel:[1,1] op_sel_hi:[0,1]
	v_pk_fma_f32 v[128:129], v[128:129], s[90:91], v[188:189] op_sel_hi:[1,0,1] neg_hi:[0,0,1]
	v_pk_mul_f32 v[168:169], v[114:115], s[88:89] op_sel:[1,1] op_sel_hi:[0,1]
	v_pk_fma_f32 v[114:115], v[114:115], s[88:89], v[168:169] op_sel_hi:[1,0,1] neg_hi:[0,0,1]
	v_pk_mul_f32 v[180:181], v[122:123], s[90:91] op_sel:[1,1] op_sel_hi:[0,1]
	v_pk_fma_f32 v[122:123], v[122:123], s[90:91], v[180:181] op_sel_hi:[1,0,1] neg_hi:[0,0,1]
	v_pk_mul_f32 v[126:127], v[130:131], s[98:99] op_sel:[1,1] op_sel_hi:[0,1]
	v_pk_fma_f32 v[130:131], v[130:131], s[98:99], v[126:127] op_sel_hi:[1,0,1] neg_hi:[0,0,1]
	v_pk_add_f32 v[118:119], v[100:101], v[116:117]
	v_pk_add_f32 v[182:183], v[100:101], v[116:117] neg_lo:[0,1] neg_hi:[0,1]
	v_pk_add_f32 v[110:111], v[108:109], v[124:125]
	v_pk_add_f32 v[102:103], v[108:109], v[124:125] neg_lo:[0,1] neg_hi:[0,1]
	v_pk_add_f32 v[100:101], v[118:119], v[110:111]
	v_pk_add_f32 v[116:117], v[118:119], v[110:111] neg_lo:[0,1] neg_hi:[0,1]
	v_pk_add_f32 v[108:109], v[182:183], v[102:103] op_sel:[0,1] op_sel_hi:[1,0] neg_lo:[0,1]
	v_pk_add_f32 v[124:125], v[182:183], v[102:103] op_sel:[0,1] op_sel_hi:[1,0] neg_hi:[0,1]
	v_pk_add_f32 v[184:185], v[178:179], v[166:167]
	v_pk_add_f32 v[186:187], v[178:179], v[166:167] neg_lo:[0,1] neg_hi:[0,1]
	v_pk_add_f32 v[188:189], v[176:177], v[174:175]
	v_pk_add_f32 v[168:169], v[176:177], v[174:175] neg_lo:[0,1] neg_hi:[0,1]
	v_pk_add_f32 v[178:179], v[184:185], v[188:189]
	v_pk_add_f32 v[166:167], v[184:185], v[188:189] neg_lo:[0,1] neg_hi:[0,1]
	v_pk_add_f32 v[176:177], v[186:187], v[168:169] op_sel:[0,1] op_sel_hi:[1,0] neg_lo:[0,1]
	v_pk_add_f32 v[174:175], v[186:187], v[168:169] op_sel:[0,1] op_sel_hi:[1,0] neg_hi:[0,1]
	v_pk_add_f32 v[180:181], v[104:105], v[120:121] op_sel:[0,1] op_sel_hi:[1,0] neg_lo:[0,1]
	v_pk_add_f32 v[126:127], v[104:105], v[120:121] op_sel:[0,1] op_sel_hi:[1,0] neg_hi:[0,1]
	v_pk_add_f32 v[118:119], v[112:113], v[128:129]
	v_pk_add_f32 v[182:183], v[112:113], v[128:129] neg_lo:[0,1] neg_hi:[0,1]
	v_pk_add_f32 v[104:105], v[180:181], v[118:119]
	v_pk_add_f32 v[120:121], v[180:181], v[118:119] neg_lo:[0,1] neg_hi:[0,1]
	v_pk_add_f32 v[112:113], v[126:127], v[182:183] op_sel:[0,1] op_sel_hi:[1,0] neg_lo:[0,1]
	v_pk_add_f32 v[128:129], v[126:127], v[182:183] op_sel:[0,1] op_sel_hi:[1,0] neg_hi:[0,1]
	v_pk_add_f32 v[110:111], v[106:107], v[122:123]
	v_pk_add_f32 v[102:103], v[106:107], v[122:123] neg_lo:[0,1] neg_hi:[0,1]
	v_pk_add_f32 v[184:185], v[114:115], v[130:131]
	v_pk_add_f32 v[186:187], v[114:115], v[130:131] neg_lo:[0,1] neg_hi:[0,1]
	v_pk_add_f32 v[106:107], v[110:111], v[184:185]
	v_pk_add_f32 v[122:123], v[110:111], v[184:185] neg_lo:[0,1] neg_hi:[0,1]
	v_pk_add_f32 v[114:115], v[102:103], v[186:187] op_sel:[0,1] op_sel_hi:[1,0] neg_lo:[0,1]
	v_pk_add_f32 v[130:131], v[102:103], v[186:187] op_sel:[0,1] op_sel_hi:[1,0] neg_hi:[0,1]
	ds_write_b64 v5, v[100:101]
	ds_write_b64 v5, v[178:179] offset:264
	ds_write_b64 v5, v[104:105] offset:528
	ds_write_b64 v5, v[106:107] offset:792
	ds_write_b64 v5, v[108:109] offset:1056
	ds_write_b64 v5, v[176:177] offset:1320
	ds_write_b64 v5, v[112:113] offset:1584
	ds_write_b64 v5, v[114:115] offset:1848
	ds_write_b64 v5, v[116:117] offset:2112
	ds_write_b64 v5, v[166:167] offset:2376
	ds_write_b64 v5, v[120:121] offset:2640
	ds_write_b64 v5, v[122:123] offset:2904
	ds_write_b64 v5, v[124:125] offset:3168
	ds_write_b64 v5, v[174:175] offset:3432
	ds_write_b64 v5, v[128:129] offset:3696
	ds_write_b64 v5, v[130:131] offset:3960
	s_waitcnt lgkmcnt(0)
	s_barrier
; #define LAS __attribute__((address_space(3)))
; __device__ __forceinline__ f32x2 cmulc(f32x2 a, f32x2 b) { return (f32x2){a.x * b.x + a.y * b.y, a.y * b.x - a.x * b.y}; }
; __device__ __forceinline__ void dft16_inv_lo(f32x2 (&x)[16]) {
;     constexpr float C1 = 0.92387953251128674f, S1 = 0.38268343236508977f, C2 = 0.70710678118654752f;
; #pragma unroll
;     for (int b = 0; b < 4; ++b) dft4<true>(x[b], x[4 + b], x[8 + b], x[12 + b]);
;     const f32x2 w1 = {C1, -S1}, w2 = {C2, -C2}, w3 = {S1, -C1}, w4 = {0.f, -1.f}, w6 = {-C2, -C2}, w9 = {-C1, S1};
;     x[5] = cmulc(x[5], w1); x[6] = cmulc(x[6], w2); x[7] = cmulc(x[7], w3);
;     x[9] = cmulc(x[9], w2); x[10] = cmulc(x[10], w4); x[11] = cmulc(x[11], w6);
;     x[13] = cmulc(x[13], w3); x[14] = cmulc(x[14], w6); x[15] = cmulc(x[15], w9);
; __device__ __forceinline__ void fft_inv1(f32x2 (&x)[16], const LAS f32x2* B, int n2, const f32x2 (&w)[16]) {
;     asm volatile("" : "+v"(n2));
;     x[0] = B[fpad(n2)];
; #pragma unroll
;     for (int k = 1; k < 16; ++k) x[k] = cmulc(B[fpad(512 * k + n2)], w[k]);
;     dft16_inv_lo(x);
	ds_read_b64 v[100:101], v3
	ds_read_b64 v[178:179], v3 offset:4224
	ds_read_b64 v[104:105], v3 offset:8448
	ds_read_b64 v[106:107], v3 offset:12672
	ds_read_b64 v[108:109], v3 offset:16896
	ds_read_b64 v[176:177], v3 offset:21120
	ds_read_b64 v[112:113], v3 offset:25344
	ds_read_b64 v[114:115], v3 offset:29568
	ds_read_b64 v[116:117], v3 offset:33792
	ds_read_b64 v[166:167], v3 offset:38016
	ds_read_b64 v[120:121], v3 offset:42240
	ds_read_b64 v[122:123], v3 offset:46464
	ds_read_b64 v[124:125], v3 offset:50688
	ds_read_b64 v[174:175], v3 offset:54912
	ds_read_b64 v[128:129], v3 offset:59136
	ds_read_b64 v[130:131], v3 offset:63360
	s_waitcnt lgkmcnt(14)
	v_pk_mul_f32 v[188:189], v[178:179], v[6:7] op_sel:[1,1] op_sel_hi:[0,1]
	v_pk_fma_f32 v[178:179], v[178:179], v[6:7], v[188:189] op_sel_hi:[1,0,1] neg_hi:[0,0,1]
	s_waitcnt lgkmcnt(13)
	v_pk_mul_f32 v[168:169], v[104:105], v[8:9] op_sel:[1,1] op_sel_hi:[0,1]
	v_pk_fma_f32 v[104:105], v[104:105], v[8:9], v[168:169] op_sel_hi:[1,0,1] neg_hi:[0,0,1]
	s_waitcnt lgkmcnt(12)
	v_pk_mul_f32 v[180:181], v[106:107], v[10:11] op_sel:[1,1] op_sel_hi:[0,1]
	v_pk_fma_f32 v[106:107], v[106:107], v[10:11], v[180:181] op_sel_hi:[1,0,1] neg_hi:[0,0,1]
	s_waitcnt lgkmcnt(11)
	v_pk_mul_f32 v[126:127], v[108:109], v[12:13] op_sel:[1,1] op_sel_hi:[0,1]
	v_pk_fma_f32 v[108:109], v[108:109], v[12:13], v[126:127] op_sel_hi:[1,0,1] neg_hi:[0,0,1]
	s_waitcnt lgkmcnt(10)
	v_pk_mul_f32 v[118:119], v[176:177], v[14:15] op_sel:[1,1] op_sel_hi:[0,1]
	v_pk_fma_f32 v[176:177], v[176:177], v[14:15], v[118:119] op_sel_hi:[1,0,1] neg_hi:[0,0,1]
	s_waitcnt lgkmcnt(9)
	v_pk_mul_f32 v[182:183], v[112:113], v[16:17] op_sel:[1,1] op_sel_hi:[0,1]
	v_pk_fma_f32 v[112:113], v[112:113], v[16:17], v[182:183] op_sel_hi:[1,0,1] neg_hi:[0,0,1]
	s_waitcnt lgkmcnt(8)
	v_pk_mul_f32 v[110:111], v[114:115], v[18:19] op_sel:[1,1] op_sel_hi:[0,1]
	v_pk_fma_f32 v[114:115], v[114:115], v[18:19], v[110:111] op_sel_hi:[1,0,1] neg_hi:[0,0,1]
	s_waitcnt lgkmcnt(7)
	v_pk_mul_f32 v[102:103], v[116:117], v[20:21] op_sel:[1,1] op_sel_hi:[0,1]
	v_pk_fma_f32 v[116:117], v[116:117], v[20:21], v[102:103] op_sel_hi:[1,0,1] neg_hi:[0,0,1]
	s_waitcnt lgkmcnt(6)
	v_pk_mul_f32 v[184:185], v[166:167], v[22:23] op_sel:[1,1] op_sel_hi:[0,1]
	v_pk_fma_f32 v[166:167], v[166:167], v[22:23], v[184:185] op_sel_hi:[1,0,1] neg_hi:[0,0,1]
	s_waitcnt lgkmcnt(5)
	v_pk_mul_f32 v[186:187], v[120:121], v[24:25] op_sel:[1,1] op_sel_hi:[0,1]
	v_pk_fma_f32 v[120:121], v[120:121], v[24:25], v[186:187] op_sel_hi:[1,0,1] neg_hi:[0,0,1]
	s_waitcnt lgkmcnt(4)
	v_pk_mul_f32 v[188:189], v[122:123], v[26:27] op_sel:[1,1] op_sel_hi:[0,1]
	v_pk_fma_f32 v[122:123], v[122:123], v[26:27], v[188:189] op_sel_hi:[1,0,1] neg_hi:[0,0,1]
	s_waitcnt lgkmcnt(3)
	v_pk_mul_f32 v[168:169], v[124:125], v[28:29] op_sel:[1,1] op_sel_hi:[0,1]
	v_pk_fma_f32 v[124:125], v[124:125], v[28:29], v[168:169] op_sel_hi:[1,0,1] neg_hi:[0,0,1]
	s_waitcnt lgkmcnt(2)
	v_pk_mul_f32 v[180:181], v[174:175], v[30:31] op_sel:[1,1] op_sel_hi:[0,1]
	v_pk_fma_f32 v[174:175], v[174:175], v[30:31], v[180:181] op_sel_hi:[1,0,1] neg_hi:[0,0,1]
	s_waitcnt lgkmcnt(1)
	v_pk_mul_f32 v[126:127], v[128:129], v[32:33] op_sel:[1,1] op_sel_hi:[0,1]
	v_pk_fma_f32 v[128:129], v[128:129], v[32:33], v[126:127] op_sel_hi:[1,0,1] neg_hi:[0,0,1]
	s_waitcnt lgkmcnt(0)
	v_pk_mul_f32 v[118:119], v[130:131], v[34:35] op_sel:[1,1] op_sel_hi:[0,1]
	v_pk_fma_f32 v[130:131], v[130:131], v[34:35], v[118:119] op_sel_hi:[1,0,1] neg_hi:[0,0,1]
	v_pk_add_f32 v[182:183], v[100:101], v[116:117]
	v_pk_add_f32 v[110:111], v[100:101], v[116:117] neg_lo:[0,1] neg_hi:[0,1]
	v_pk_add_f32 v[102:103], v[108:109], v[124:125]
	v_pk_add_f32 v[184:185], v[108:109], v[124:125] neg_lo:[0,1] neg_hi:[0,1]
	v_pk_add_f32 v[100:101], v[182:183], v[102:103]
	v_pk_add_f32 v[116:117], v[182:183], v[102:103] neg_lo:[0,1] neg_hi:[0,1]
	v_pk_add_f32 v[108:109], v[110:111], v[184:185] op_sel:[0,1] op_sel_hi:[1,0] neg_lo:[0,1]
	v_pk_add_f32 v[124:125], v[110:111], v[184:185] op_sel:[0,1] op_sel_hi:[1,0] neg_hi:[0,1]
	v_pk_add_f32 v[186:187], v[178:179], v[166:167]
	v_pk_add_f32 v[188:189], v[178:179], v[166:167] neg_lo:[0,1] neg_hi:[0,1]
	v_pk_add_f32 v[168:169], v[176:177], v[174:175]
	v_pk_add_f32 v[180:181], v[176:177], v[174:175] neg_lo:[0,1] neg_hi:[0,1]
	v_pk_add_f32 v[178:179], v[186:187], v[168:169]
	v_pk_add_f32 v[166:167], v[186:187], v[168:169] neg_lo:[0,1] neg_hi:[0,1]
	v_pk_add_f32 v[176:177], v[188:189], v[180:181] op_sel:[0,1] op_sel_hi:[1,0] neg_lo:[0,1]
	v_pk_add_f32 v[174:175], v[188:189], v[180:181] op_sel:[0,1] op_sel_hi:[1,0] neg_hi:[0,1]
	v_pk_add_f32 v[126:127], v[104:105], v[120:121]
	v_pk_add_f32 v[118:119], v[104:105], v[120:121] neg_lo:[0,1] neg_hi:[0,1]
	v_pk_add_f32 v[182:183], v[112:113], v[128:129]
	v_pk_add_f32 v[110:111], v[112:113], v[128:129] neg_lo:[0,1] neg_hi:[0,1]
	v_pk_add_f32 v[104:105], v[126:127], v[182:183]
	v_pk_add_f32 v[120:121], v[126:127], v[182:183] neg_lo:[0,1] neg_hi:[0,1]
	v_pk_add_f32 v[112:113], v[118:119], v[110:111] op_sel:[0,1] op_sel_hi:[1,0] neg_lo:[0,1]
	v_pk_add_f32 v[128:129], v[118:119], v[110:111] op_sel:[0,1] op_sel_hi:[1,0] neg_hi:[0,1]
	v_pk_add_f32 v[102:103], v[106:107], v[122:123]
	v_pk_add_f32 v[184:185], v[106:107], v[122:123] neg_lo:[0,1] neg_hi:[0,1]
	v_pk_add_f32 v[186:187], v[114:115], v[130:131]
	v_pk_add_f32 v[188:189], v[114:115], v[130:131] neg_lo:[0,1] neg_hi:[0,1]
	v_pk_add_f32 v[106:107], v[102:103], v[186:187]
	v_pk_add_f32 v[122:123], v[102:103], v[186:187] neg_lo:[0,1] neg_hi:[0,1]
	v_pk_add_f32 v[114:115], v[184:185], v[188:189] op_sel:[0,1] op_sel_hi:[1,0] neg_lo:[0,1]
; #define LAS __attribute__((address_space(3)))
; #define WG_SYNC() do { asm volatile("s_waitcnt lgkmcnt(0)" ::: "memory"); __builtin_amdgcn_s_barrier(); asm volatile("" ::: "memory"); } while (0)
; __device__ __forceinline__ void hy_stage(LAS float* plane, const bf16_t* PHY, int cg, int jc, int tid) {
;     asm volatile("" : "+v"(tid));
;     const u32x4* src = (const u32x4*)(PHY + (size_t)cg * MT * 4);
; #pragma unroll
;     for (int k = 0; k < 8; ++k) { const int i = tid + 512 * k; const u32x4 v = src[i];
;         const unsigned w0 = (jc & 2) ? v.y : v.x, w1 = (jc & 2) ? v.w : v.z;
;         f32x2 o; o.x = (jc & 1) ? bf_hi(w0) : bf_lo(w0); o.y = (jc & 1) ? bf_hi(w1) : bf_lo(w1);
;         *(LAS f32x2*)(plane + 2 * i) = o; }
; }
; __device__ __forceinline__ void hyena_fft(LAS unsigned char* lds, int layer, int G, const int wave_s) {
;     ...
;             WG_SYNC(); fft_inv1(x, Db, n2, w1p);
;             { const float fb0 = fbias[c];
; #pragma unroll
;               for (int r = 0; r < 8; ++r) { uz[r][0] = ux[r][0] * (x[r].x + fb0 * uz[r][0]); uz[r][1] = ux[r][1] * (x[r].y + fb0 * uz[r][1]); } }
;             WG_SYNC();
;             hy_stage(pl0, PHY, (HY / 4) + unit, jc, tid);
	v_pk_add_f32 v[130:131], v[184:185], v[188:189] op_sel:[0,1] op_sel_hi:[1,0] neg_hi:[0,1]
	v_pk_mul_f32 v[168:169], v[176:177], s[68:69] op_sel:[1,1] op_sel_hi:[0,1]
	v_pk_fma_f32 v[176:177], v[176:177], s[68:69], v[168:169] op_sel_hi:[1,0,1] neg_hi:[0,0,1]
	v_pk_mul_f32 v[180:181], v[112:113], s[84:85] op_sel:[1,1] op_sel_hi:[0,1]
	v_pk_fma_f32 v[112:113], v[112:113], s[84:85], v[180:181] op_sel_hi:[1,0,1] neg_hi:[0,0,1]
	v_pk_mul_f32 v[126:127], v[114:115], s[88:89] op_sel:[1,1] op_sel_hi:[0,1]
	v_pk_fma_f32 v[114:115], v[114:115], s[88:89], v[126:127] op_sel_hi:[1,0,1] neg_hi:[0,0,1]
	v_pk_mul_f32 v[118:119], v[166:167], s[84:85] op_sel:[1,1] op_sel_hi:[0,1]
	v_pk_fma_f32 v[166:167], v[166:167], s[84:85], v[118:119] op_sel_hi:[1,0,1] neg_hi:[0,0,1]
	v_pk_mul_f32 v[182:183], v[122:123], s[90:91] op_sel:[1,1] op_sel_hi:[0,1]
	v_pk_fma_f32 v[122:123], v[122:123], s[90:91], v[182:183] op_sel_hi:[1,0,1] neg_hi:[0,0,1]
	v_pk_mul_f32 v[110:111], v[174:175], s[88:89] op_sel:[1,1] op_sel_hi:[0,1]
	v_pk_fma_f32 v[174:175], v[174:175], s[88:89], v[110:111] op_sel_hi:[1,0,1] neg_hi:[0,0,1]
	v_pk_mul_f32 v[102:103], v[128:129], s[90:91] op_sel:[1,1] op_sel_hi:[0,1]
	v_pk_fma_f32 v[128:129], v[128:129], s[90:91], v[102:103] op_sel_hi:[1,0,1] neg_hi:[0,0,1]
	v_pk_mul_f32 v[184:185], v[130:131], s[98:99] op_sel:[1,1] op_sel_hi:[0,1]
	v_pk_fma_f32 v[130:131], v[130:131], s[98:99], v[184:185] op_sel_hi:[1,0,1] neg_hi:[0,0,1]
	v_pk_add_f32 v[186:187], v[100:101], v[104:105]
	v_pk_add_f32 v[188:189], v[100:101], v[104:105] neg_lo:[0,1] neg_hi:[0,1]
	v_pk_add_f32 v[168:169], v[178:179], v[106:107]
	v_pk_add_f32 v[180:181], v[178:179], v[106:107] neg_lo:[0,1] neg_hi:[0,1]
	v_pk_add_f32 v[100:101], v[186:187], v[168:169]
	v_pk_add_f32 v[178:179], v[188:189], v[180:181] op_sel:[0,1] op_sel_hi:[1,0] neg_lo:[0,1]
	v_pk_add_f32 v[126:127], v[108:109], v[112:113]
	v_pk_add_f32 v[118:119], v[108:109], v[112:113] neg_lo:[0,1] neg_hi:[0,1]
	v_pk_add_f32 v[182:183], v[176:177], v[114:115]
	v_pk_add_f32 v[110:111], v[176:177], v[114:115] neg_lo:[0,1] neg_hi:[0,1]
	v_pk_add_f32 v[108:109], v[126:127], v[182:183]
	v_pk_add_f32 v[176:177], v[118:119], v[110:111] op_sel:[0,1] op_sel_hi:[1,0] neg_lo:[0,1]
	v_pk_add_f32 v[102:103], v[116:117], v[120:121] op_sel:[0,1] op_sel_hi:[1,0] neg_lo:[0,1]
	v_pk_add_f32 v[184:185], v[116:117], v[120:121] op_sel:[0,1] op_sel_hi:[1,0] neg_hi:[0,1]
	v_pk_add_f32 v[186:187], v[166:167], v[122:123]
	v_pk_add_f32 v[188:189], v[166:167], v[122:123] neg_lo:[0,1] neg_hi:[0,1]
	v_pk_add_f32 v[116:117], v[102:103], v[186:187]
	v_pk_add_f32 v[166:167], v[184:185], v[188:189] op_sel:[0,1] op_sel_hi:[1,0] neg_lo:[0,1]
	v_pk_add_f32 v[168:169], v[124:125], v[128:129]
	v_pk_add_f32 v[180:181], v[124:125], v[128:129] neg_lo:[0,1] neg_hi:[0,1]
	v_pk_add_f32 v[126:127], v[174:175], v[130:131]
	v_pk_add_f32 v[118:119], v[174:175], v[130:131] neg_lo:[0,1] neg_hi:[0,1]
	v_pk_add_f32 v[124:125], v[168:169], v[126:127]
	v_pk_add_f32 v[174:175], v[180:181], v[118:119] op_sel:[0,1] op_sel_hi:[1,0] neg_lo:[0,1]
	s_load_dword s35, s[50:51], 0x0
	s_waitcnt lgkmcnt(0)
	v_mov_b32_e32 v194, s35
	v_pk_fma_f32 v[182:183], v[132:133], v[194:195], v[100:101] op_sel_hi:[1,0,1]
	v_pk_mul_f32 v[132:133], v[148:149], v[182:183]
	v_pk_fma_f32 v[110:111], v[134:135], v[194:195], v[108:109] op_sel_hi:[1,0,1]
	v_pk_mul_f32 v[134:135], v[150:151], v[110:111]
	v_pk_fma_f32 v[102:103], v[136:137], v[194:195], v[116:117] op_sel_hi:[1,0,1]
	v_pk_mul_f32 v[136:137], v[152:153], v[102:103]
	v_pk_fma_f32 v[184:185], v[138:139], v[194:195], v[124:125] op_sel_hi:[1,0,1]
	v_pk_mul_f32 v[138:139], v[154:155], v[184:185]
	v_pk_fma_f32 v[186:187], v[140:141], v[194:195], v[178:179] op_sel_hi:[1,0,1]
	v_pk_mul_f32 v[140:141], v[158:159], v[186:187]
	v_pk_fma_f32 v[188:189], v[142:143], v[194:195], v[176:177] op_sel_hi:[1,0,1]
	v_pk_mul_f32 v[142:143], v[160:161], v[188:189]
	v_pk_fma_f32 v[168:169], v[144:145], v[194:195], v[166:167] op_sel_hi:[1,0,1]
	v_pk_mul_f32 v[144:145], v[162:163], v[168:169]
	v_pk_fma_f32 v[180:181], v[146:147], v[194:195], v[174:175] op_sel_hi:[1,0,1]
	v_pk_mul_f32 v[146:147], v[164:165], v[180:181]
	s_waitcnt lgkmcnt(0)
	s_barrier
	s_waitcnt vmcnt(7)
	v_perm_b32 v126, 0, v58, s15
	v_perm_b32 v127, 0, v60, s15
	ds_write_b64 v206, v[126:127]
	s_waitcnt vmcnt(6)
	v_perm_b32 v118, 0, v62, s15
	v_perm_b32 v119, 0, v64, s15
	ds_write_b64 v206, v[118:119] offset:4096
	s_waitcnt vmcnt(5)
	v_perm_b32 v182, 0, v66, s15
	v_perm_b32 v183, 0, v68, s15
	ds_write_b64 v206, v[182:183] offset:8192
	s_waitcnt vmcnt(4)
	v_perm_b32 v110, 0, v70, s15
	v_perm_b32 v111, 0, v72, s15
	ds_write_b64 v206, v[110:111] offset:12288
	s_waitcnt vmcnt(3)
	v_perm_b32 v102, 0, v74, s15
	v_perm_b32 v103, 0, v76, s15
	ds_write_b64 v206, v[102:103] offset:16384
	s_waitcnt vmcnt(2)
	v_perm_b32 v184, 0, v78, s15
	v_perm_b32 v185, 0, v80, s15
	ds_write_b64 v206, v[184:185] offset:20480
	s_waitcnt vmcnt(1)
	v_perm_b32 v186, 0, v82, s15
	v_perm_b32 v187, 0, v84, s15
	ds_write_b64 v206, v[186:187] offset:24576
	s_waitcnt vmcnt(0)
	v_perm_b32 v188, 0, v86, s15
	v_perm_b32 v189, 0, v88, s15
	ds_write_b64 v206, v[188:189] offset:28672
	s_waitcnt lgkmcnt(0)
	s_barrier
; #define LAS __attribute__((address_space(3)))
; #define WG_SYNC() do { asm volatile("s_waitcnt lgkmcnt(0)" ::: "memory"); __builtin_amdgcn_s_barrier(); asm volatile("" ::: "memory"); } while (0)
; __device__ __forceinline__ void hy_sconv(const LAS float* plane, float w0, float w1, float w2, float cb, int n2, float (&u)[8][2]) {
;     asm volatile("" : "+v"(n2));
; #pragma unroll
;     for (int r = 0; r < 8; ++r)
; #pragma unroll
;         for (int b = 0; b < 2; ++b) { const int t = n2 + 512 * r, row = b * SEQ + t;
;             float a = cb + w1 * plane[row];
;             if (t > 0) a += w0 * plane[row - 1];
;             if (t < SEQ - 1) a += w2 * plane[row + 1];
;             u[r][b] = a; }
; }
; __device__ __forceinline__ void hyena_fft(LAS unsigned char* lds, int layer, int G, const int wave_s) {
;     ...
;             hy_stage(pl0, PHY, (HY / 4) + unit, jc, tid);
;             WG_SYNC();
;             hy_sconv(pl0, cw[HY + c], cw[3 * HY + HY + c], cw[6 * HY + HY + c], cb[HY + c], n2, ux);
;             WG_SYNC();
	v_mov_b32_e32 v168, s17
	v_mov_b32_e32 v169, s23
	v_mov_b32_e32 v180, s25
	v_mov_b32_e32 v181, s26
	ds_read_b32 v126, v208
	ds_read_b32 v118, v210
	ds_read_b32 v182, v208 offset:4
	ds_read_b32 v127, v208 offset:16384
	ds_read_b32 v119, v210 offset:16384
	ds_read_b32 v183, v208 offset:16388
	ds_read_b32 v110, v208 offset:2048
	ds_read_b32 v102, v208 offset:2044
	ds_read_b32 v184, v208 offset:2052
	ds_read_b32 v111, v208 offset:18432
	ds_read_b32 v103, v208 offset:18428
	ds_read_b32 v185, v208 offset:18436
	s_waitcnt lgkmcnt(10)
	v_cndmask_b32_e64 v118, v118, 0, s[10:11]
	s_waitcnt lgkmcnt(7)
	v_cndmask_b32_e64 v119, v119, 0, s[10:11]
	v_pk_fma_f32 v[148:149], v[168:169], v[126:127], v[180:181] op_sel:[1,0,1]
	v_pk_fma_f32 v[148:149], v[168:169], v[118:119], v[148:149] op_sel_hi:[0,1,1]
	s_waitcnt lgkmcnt(6)
	v_pk_fma_f32 v[148:149], v[180:181], v[182:183], v[148:149] op_sel_hi:[0,1,1]
	s_waitcnt lgkmcnt(2)
	v_pk_fma_f32 v[150:151], v[168:169], v[110:111], v[180:181] op_sel:[1,0,1]
	s_waitcnt lgkmcnt(1)
	v_pk_fma_f32 v[150:151], v[168:169], v[102:103], v[150:151] op_sel_hi:[0,1,1]
	s_waitcnt lgkmcnt(0)
	v_pk_fma_f32 v[150:151], v[180:181], v[184:185], v[150:151] op_sel_hi:[0,1,1]
	ds_read_b32 v186, v208 offset:4096
	ds_read_b32 v188, v208 offset:4092
	ds_read_b32 v126, v208 offset:4100
	ds_read_b32 v187, v208 offset:20480
	ds_read_b32 v189, v208 offset:20476
	ds_read_b32 v127, v208 offset:20484
	ds_read_b32 v118, v208 offset:6144
	ds_read_b32 v182, v208 offset:6140
	ds_read_b32 v110, v208 offset:6148
	ds_read_b32 v119, v208 offset:22528
	ds_read_b32 v183, v208 offset:22524
	ds_read_b32 v111, v208 offset:22532
	s_waitcnt lgkmcnt(8)
	v_pk_fma_f32 v[152:153], v[168:169], v[186:187], v[180:181] op_sel:[1,0,1]
	s_waitcnt lgkmcnt(7)
	v_pk_fma_f32 v[152:153], v[168:169], v[188:189], v[152:153] op_sel_hi:[0,1,1]
	s_waitcnt lgkmcnt(6)
	v_pk_fma_f32 v[152:153], v[180:181], v[126:127], v[152:153] op_sel_hi:[0,1,1]
	s_waitcnt lgkmcnt(2)
	v_pk_fma_f32 v[154:155], v[168:169], v[118:119], v[180:181] op_sel:[1,0,1]
	s_waitcnt lgkmcnt(1)
	v_pk_fma_f32 v[154:155], v[168:169], v[182:183], v[154:155] op_sel_hi:[0,1,1]
	s_waitcnt lgkmcnt(0)
	v_pk_fma_f32 v[154:155], v[180:181], v[110:111], v[154:155] op_sel_hi:[0,1,1]
	ds_read_b32 v102, v208 offset:8192
	ds_read_b32 v184, v208 offset:8188
	ds_read_b32 v186, v208 offset:8196
	ds_read_b32 v103, v208 offset:24576
	ds_read_b32 v185, v208 offset:24572
	ds_read_b32 v187, v208 offset:24580
	ds_read_b32 v188, v208 offset:10240
	ds_read_b32 v126, v208 offset:10236
	ds_read_b32 v118, v208 offset:10244
	ds_read_b32 v189, v208 offset:26624
	ds_read_b32 v127, v208 offset:26620
	ds_read_b32 v119, v208 offset:26628
	s_waitcnt lgkmcnt(8)
	v_pk_fma_f32 v[158:159], v[168:169], v[102:103], v[180:181] op_sel:[1,0,1]
	s_waitcnt lgkmcnt(7)
	v_pk_fma_f32 v[158:159], v[168:169], v[184:185], v[158:159] op_sel_hi:[0,1,1]
	s_waitcnt lgkmcnt(6)
	v_pk_fma_f32 v[158:159], v[180:181], v[186:187], v[158:159] op_sel_hi:[0,1,1]
	s_waitcnt lgkmcnt(2)
	v_pk_fma_f32 v[160:161], v[168:169], v[188:189], v[180:181] op_sel:[1,0,1]
	s_waitcnt lgkmcnt(1)
	v_pk_fma_f32 v[160:161], v[168:169], v[126:127], v[160:161] op_sel_hi:[0,1,1]
	s_waitcnt lgkmcnt(0)
	v_pk_fma_f32 v[160:161], v[180:181], v[118:119], v[160:161] op_sel_hi:[0,1,1]
	ds_read_b32 v182, v208 offset:12288
	ds_read_b32 v110, v208 offset:12284
	ds_read_b32 v102, v208 offset:12292
	ds_read_b32 v183, v208 offset:28672
	ds_read_b32 v111, v208 offset:28668
	ds_read_b32 v103, v208 offset:28676
	ds_read_b32 v184, v208 offset:14336
	ds_read_b32 v186, v208 offset:14332
	ds_read_b32 v188, v208 offset:14340
	ds_read_b32 v185, v208 offset:30720
	ds_read_b32 v187, v208 offset:30716
	ds_read_b32 v189, v208 offset:30724
	s_waitcnt lgkmcnt(8)
	v_pk_fma_f32 v[162:163], v[168:169], v[182:183], v[180:181] op_sel:[1,0,1]
	s_waitcnt lgkmcnt(7)
	v_pk_fma_f32 v[162:163], v[168:169], v[110:111], v[162:163] op_sel_hi:[0,1,1]
	s_waitcnt lgkmcnt(6)
	v_pk_fma_f32 v[162:163], v[180:181], v[102:103], v[162:163] op_sel_hi:[0,1,1]
	s_waitcnt lgkmcnt(3)
	v_cndmask_b32_e64 v188, v188, 0, s[28:29]
	s_waitcnt lgkmcnt(0)
	v_cndmask_b32_e64 v189, v189, 0, s[28:29]
	v_pk_fma_f32 v[164:165], v[168:169], v[184:185], v[180:181] op_sel:[1,0,1]
	v_pk_fma_f32 v[164:165], v[168:169], v[186:187], v[164:165] op_sel_hi:[0,1,1]
	v_pk_fma_f32 v[164:165], v[180:181], v[188:189], v[164:165] op_sel_hi:[0,1,1]
	s_waitcnt lgkmcnt(0)
	s_barrier
; #define LAS __attribute__((address_space(3)))
; __device__ __forceinline__ f32x2 cmul(f32x2 a, f32x2 b) { return (f32x2){a.x * b.x - a.y * b.y, a.x * b.y + a.y * b.x}; }
; __device__ __forceinline__ void dft16_fwd_lo(f32x2 (&x)[16]) {
;     constexpr float C1 = 0.92387953251128674f, S1 = 0.38268343236508977f, C2 = 0.70710678118654752f;
; #pragma unroll
;     for (int b = 0; b < 4; ++b) { const f32x2 x0 = x[b], x1 = x[4 + b]; const f32x2 j1 = {x1.y, -x1.x};
;         x[b] = x0 + x1; x[4 + b] = x0 + j1; x[8 + b] = x0 - x1; x[12 + b] = x0 - j1; }
;     const f32x2 w1 = {C1, -S1}, w2 = {C2, -C2}, w3 = {S1, -C1}, w4 = {0.f, -1.f}, w6 = {-C2, -C2}, w9 = {-C1, S1};
;     x[5] = cmul(x[5], w1); x[6] = cmul(x[6], w2); x[7] = cmul(x[7], w3);
;     x[9] = cmul(x[9], w2); x[10] = cmul(x[10], w4); x[11] = cmul(x[11], w6);
;     x[13] = cmul(x[13], w3); x[14] = cmul(x[14], w6); x[15] = cmul(x[15], w9);
; #pragma unroll
;     for (int c = 0; c < 4; ++c) dft4<false>(x[4 * c], x[4 * c + 1], x[4 * c + 2], x[4 * c + 3]);
;     f32x2 y[16];
; #pragma unroll
;     for (int k = 0; k < 16; ++k) y[k] = x[4 * (k & 3) + (k >> 2)];
; #pragma unroll
;     for (int k = 0; k < 16; ++k) x[k] = y[k];
; }
; template <bool LO> __device__ __forceinline__ void fft_fwd1(f32x2 (&x)[16], LAS f32x2* B, int n2, const f32x2 (&w)[16]) {
;     asm volatile("" : "+v"(n2));
;     if (LO) dft16_fwd_lo(x); else dft16<false>(x);
;     B[fpad(n2)] = x[0];
; #pragma unroll
;     for (int k = 1; k < 16; ++k) B[fpad(512 * k + n2)] = cmul(x[k], w[k]);
	v_pk_add_f32 v[104:105], v[132:133], v[140:141] neg_lo:[0,1] neg_hi:[0,1]
	v_pk_add_f32 v[106:107], v[132:133], v[140:141] op_sel:[0,1] op_sel_hi:[1,0] neg_lo:[0,1]
	v_pk_add_f32 v[126:127], v[132:133], v[140:141] op_sel:[0,1] op_sel_hi:[1,0] neg_hi:[0,1]
	v_pk_add_f32 v[100:101], v[132:133], v[140:141]
	v_pk_add_f32 v[112:113], v[134:135], v[142:143] neg_lo:[0,1] neg_hi:[0,1]
	v_pk_add_f32 v[114:115], v[134:135], v[142:143] op_sel:[0,1] op_sel_hi:[1,0] neg_lo:[0,1]
	v_pk_add_f32 v[118:119], v[134:135], v[142:143] op_sel:[0,1] op_sel_hi:[1,0] neg_hi:[0,1]
	v_pk_add_f32 v[108:109], v[134:135], v[142:143]
	v_pk_add_f32 v[120:121], v[136:137], v[144:145] neg_lo:[0,1] neg_hi:[0,1]
	v_pk_add_f32 v[122:123], v[136:137], v[144:145] op_sel:[0,1] op_sel_hi:[1,0] neg_lo:[0,1]
	v_pk_add_f32 v[182:183], v[136:137], v[144:145] op_sel:[0,1] op_sel_hi:[1,0] neg_hi:[0,1]
	v_pk_add_f32 v[116:117], v[136:137], v[144:145]
	v_pk_add_f32 v[128:129], v[138:139], v[146:147] neg_lo:[0,1] neg_hi:[0,1]
	v_pk_add_f32 v[130:131], v[138:139], v[146:147] op_sel:[0,1] op_sel_hi:[1,0] neg_lo:[0,1]
	v_pk_add_f32 v[110:111], v[138:139], v[146:147] op_sel:[0,1] op_sel_hi:[1,0] neg_hi:[0,1]
	v_pk_add_f32 v[124:125], v[138:139], v[146:147]
	v_pk_mul_f32 v[102:103], v[118:119], s[68:69] op_sel:[1,1] op_sel_hi:[0,1]
	v_pk_fma_f32 v[118:119], v[118:119], s[68:69], v[102:103] op_sel_hi:[1,0,1] neg_lo:[0,0,1]
	v_pk_mul_f32 v[184:185], v[182:183], s[84:85] op_sel:[1,1] op_sel_hi:[0,1]
	v_pk_fma_f32 v[182:183], v[182:183], s[84:85], v[184:185] op_sel_hi:[1,0,1] neg_lo:[0,0,1]
	v_pk_mul_f32 v[186:187], v[110:111], s[88:89] op_sel:[1,1] op_sel_hi:[0,1]
	v_pk_fma_f32 v[110:111], v[110:111], s[88:89], v[186:187] op_sel_hi:[1,0,1] neg_lo:[0,0,1]
	v_pk_mul_f32 v[188:189], v[112:113], s[84:85] op_sel:[1,1] op_sel_hi:[0,1]
	v_pk_fma_f32 v[112:113], v[112:113], s[84:85], v[188:189] op_sel_hi:[1,0,1] neg_lo:[0,0,1]
	v_pk_mul_f32 v[168:169], v[128:129], s[90:91] op_sel:[1,1] op_sel_hi:[0,1]
	v_pk_fma_f32 v[128:129], v[128:129], s[90:91], v[168:169] op_sel_hi:[1,0,1] neg_lo:[0,0,1]
	v_pk_mul_f32 v[180:181], v[114:115], s[88:89] op_sel:[1,1] op_sel_hi:[0,1]
	v_pk_fma_f32 v[114:115], v[114:115], s[88:89], v[180:181] op_sel_hi:[1,0,1] neg_lo:[0,0,1]
	v_pk_mul_f32 v[178:179], v[122:123], s[90:91] op_sel:[1,1] op_sel_hi:[0,1]
	v_pk_fma_f32 v[122:123], v[122:123], s[90:91], v[178:179] op_sel_hi:[1,0,1] neg_lo:[0,0,1]
	v_pk_mul_f32 v[176:177], v[130:131], s[98:99] op_sel:[1,1] op_sel_hi:[0,1]
	v_pk_fma_f32 v[130:131], v[130:131], s[98:99], v[176:177] op_sel_hi:[1,0,1] neg_lo:[0,0,1]
	v_pk_add_f32 v[166:167], v[100:101], v[116:117]
	v_pk_add_f32 v[174:175], v[100:101], v[116:117] neg_lo:[0,1] neg_hi:[0,1]
	v_pk_add_f32 v[102:103], v[108:109], v[124:125]
	v_pk_add_f32 v[184:185], v[108:109], v[124:125] neg_lo:[0,1] neg_hi:[0,1]
	v_pk_add_f32 v[100:101], v[166:167], v[102:103]
	v_pk_add_f32 v[116:117], v[166:167], v[102:103] neg_lo:[0,1] neg_hi:[0,1]
	v_pk_add_f32 v[108:109], v[174:175], v[184:185] op_sel:[0,1] op_sel_hi:[1,0] neg_hi:[0,1]
	v_pk_add_f32 v[124:125], v[174:175], v[184:185] op_sel:[0,1] op_sel_hi:[1,0] neg_lo:[0,1]
	v_pk_add_f32 v[186:187], v[126:127], v[182:183]
	v_pk_add_f32 v[188:189], v[126:127], v[182:183] neg_lo:[0,1] neg_hi:[0,1]
	v_pk_add_f32 v[168:169], v[118:119], v[110:111]
	v_pk_add_f32 v[180:181], v[118:119], v[110:111] neg_lo:[0,1] neg_hi:[0,1]
	v_pk_add_f32 v[126:127], v[186:187], v[168:169]
	v_pk_add_f32 v[182:183], v[186:187], v[168:169] neg_lo:[0,1] neg_hi:[0,1]
	v_pk_add_f32 v[118:119], v[188:189], v[180:181] op_sel:[0,1] op_sel_hi:[1,0] neg_hi:[0,1]
	v_pk_add_f32 v[110:111], v[188:189], v[180:181] op_sel:[0,1] op_sel_hi:[1,0] neg_lo:[0,1]
	v_pk_add_f32 v[178:179], v[104:105], v[120:121] op_sel:[0,1] op_sel_hi:[1,0] neg_hi:[0,1]
	v_pk_add_f32 v[176:177], v[104:105], v[120:121] op_sel:[0,1] op_sel_hi:[1,0] neg_lo:[0,1]
	v_pk_add_f32 v[166:167], v[112:113], v[128:129]
	v_pk_add_f32 v[174:175], v[112:113], v[128:129] neg_lo:[0,1] neg_hi:[0,1]
	v_pk_add_f32 v[104:105], v[178:179], v[166:167]
	v_pk_add_f32 v[120:121], v[178:179], v[166:167] neg_lo:[0,1] neg_hi:[0,1]
	v_pk_add_f32 v[112:113], v[176:177], v[174:175] op_sel:[0,1] op_sel_hi:[1,0] neg_hi:[0,1]
	v_pk_add_f32 v[128:129], v[176:177], v[174:175] op_sel:[0,1] op_sel_hi:[1,0] neg_lo:[0,1]
	v_pk_add_f32 v[102:103], v[106:107], v[122:123]
	v_pk_add_f32 v[184:185], v[106:107], v[122:123] neg_lo:[0,1] neg_hi:[0,1]
	v_pk_add_f32 v[186:187], v[114:115], v[130:131]
	v_pk_add_f32 v[188:189], v[114:115], v[130:131] neg_lo:[0,1] neg_hi:[0,1]
	v_pk_add_f32 v[106:107], v[102:103], v[186:187]
	v_pk_add_f32 v[122:123], v[102:103], v[186:187] neg_lo:[0,1] neg_hi:[0,1]
	v_pk_add_f32 v[114:115], v[184:185], v[188:189] op_sel:[0,1] op_sel_hi:[1,0] neg_hi:[0,1]
	v_pk_add_f32 v[130:131], v[184:185], v[188:189] op_sel:[0,1] op_sel_hi:[1,0] neg_lo:[0,1]
	ds_write_b64 v3, v[100:101]
	v_pk_mul_f32 v[180:181], v[126:127], v[6:7] op_sel:[1,1] op_sel_hi:[0,1]
	v_pk_fma_f32 v[168:169], v[126:127], v[6:7], v[180:181] op_sel_hi:[1,0,1] neg_lo:[0,0,1]
	ds_write_b64 v3, v[168:169] offset:4224
	v_pk_mul_f32 v[176:177], v[104:105], v[8:9] op_sel:[1,1] op_sel_hi:[0,1]
	v_pk_fma_f32 v[178:179], v[104:105], v[8:9], v[176:177] op_sel_hi:[1,0,1] neg_lo:[0,0,1]
	ds_write_b64 v3, v[178:179] offset:8448
	v_pk_mul_f32 v[174:175], v[106:107], v[10:11] op_sel:[1,1] op_sel_hi:[0,1]
	v_pk_fma_f32 v[166:167], v[106:107], v[10:11], v[174:175] op_sel_hi:[1,0,1] neg_lo:[0,0,1]
	ds_write_b64 v3, v[166:167] offset:12672
	v_pk_mul_f32 v[184:185], v[108:109], v[12:13] op_sel:[1,1] op_sel_hi:[0,1]
	v_pk_fma_f32 v[102:103], v[108:109], v[12:13], v[184:185] op_sel_hi:[1,0,1] neg_lo:[0,0,1]
; #define LAS __attribute__((address_space(3)))
; __device__ __forceinline__ f32x2 cmul(f32x2 a, f32x2 b) { return (f32x2){a.x * b.x - a.y * b.y, a.x * b.y + a.y * b.x}; }
; template <bool LO> __device__ __forceinline__ void fft_fwd1(f32x2 (&x)[16], LAS f32x2* B, int n2, const f32x2 (&w)[16]) {
;     asm volatile("" : "+v"(n2));
;     if (LO) dft16_fwd_lo(x); else dft16<false>(x);
;     B[fpad(n2)] = x[0];
; #pragma unroll
;     for (int k = 1; k < 16; ++k) B[fpad(512 * k + n2)] = cmul(x[k], w[k]);
; }
; __device__ __forceinline__ void fft_fwd2(LAS f32x2* B, const LAS f32x2* TW2, int tid) {
;     asm volatile("" : "+v"(tid));
;     const int b = tid >> 5, n2 = tid & 31, base = 512 * b + n2; f32x2 x[16];
; #pragma unroll
;     for (int r = 0; r < 16; ++r) x[r] = B[fpad(base + 32 * r)];
;     dft16<false>(x);
	ds_write_b64 v3, v[102:103] offset:16896
	v_pk_mul_f32 v[188:189], v[118:119], v[14:15] op_sel:[1,1] op_sel_hi:[0,1]
	v_pk_fma_f32 v[186:187], v[118:119], v[14:15], v[188:189] op_sel_hi:[1,0,1] neg_lo:[0,0,1]
	ds_write_b64 v3, v[186:187] offset:21120
	v_pk_mul_f32 v[168:169], v[112:113], v[16:17] op_sel:[1,1] op_sel_hi:[0,1]
	v_pk_fma_f32 v[180:181], v[112:113], v[16:17], v[168:169] op_sel_hi:[1,0,1] neg_lo:[0,0,1]
	ds_write_b64 v3, v[180:181] offset:25344
	v_pk_mul_f32 v[178:179], v[114:115], v[18:19] op_sel:[1,1] op_sel_hi:[0,1]
	v_pk_fma_f32 v[176:177], v[114:115], v[18:19], v[178:179] op_sel_hi:[1,0,1] neg_lo:[0,0,1]
	ds_write_b64 v3, v[176:177] offset:29568
	v_pk_mul_f32 v[166:167], v[116:117], v[20:21] op_sel:[1,1] op_sel_hi:[0,1]
	v_pk_fma_f32 v[174:175], v[116:117], v[20:21], v[166:167] op_sel_hi:[1,0,1] neg_lo:[0,0,1]
	ds_write_b64 v3, v[174:175] offset:33792
	v_pk_mul_f32 v[102:103], v[182:183], v[22:23] op_sel:[1,1] op_sel_hi:[0,1]
	v_pk_fma_f32 v[184:185], v[182:183], v[22:23], v[102:103] op_sel_hi:[1,0,1] neg_lo:[0,0,1]
	ds_write_b64 v3, v[184:185] offset:38016
	v_pk_mul_f32 v[186:187], v[120:121], v[24:25] op_sel:[1,1] op_sel_hi:[0,1]
	v_pk_fma_f32 v[188:189], v[120:121], v[24:25], v[186:187] op_sel_hi:[1,0,1] neg_lo:[0,0,1]
	ds_write_b64 v3, v[188:189] offset:42240
	v_pk_mul_f32 v[180:181], v[122:123], v[26:27] op_sel:[1,1] op_sel_hi:[0,1]
	v_pk_fma_f32 v[168:169], v[122:123], v[26:27], v[180:181] op_sel_hi:[1,0,1] neg_lo:[0,0,1]
	ds_write_b64 v3, v[168:169] offset:46464
	v_pk_mul_f32 v[176:177], v[124:125], v[28:29] op_sel:[1,1] op_sel_hi:[0,1]
	v_pk_fma_f32 v[178:179], v[124:125], v[28:29], v[176:177] op_sel_hi:[1,0,1] neg_lo:[0,0,1]
	ds_write_b64 v3, v[178:179] offset:50688
	v_pk_mul_f32 v[174:175], v[110:111], v[30:31] op_sel:[1,1] op_sel_hi:[0,1]
	v_pk_fma_f32 v[166:167], v[110:111], v[30:31], v[174:175] op_sel_hi:[1,0,1] neg_lo:[0,0,1]
	ds_write_b64 v3, v[166:167] offset:54912
	v_pk_mul_f32 v[184:185], v[128:129], v[32:33] op_sel:[1,1] op_sel_hi:[0,1]
	v_pk_fma_f32 v[102:103], v[128:129], v[32:33], v[184:185] op_sel_hi:[1,0,1] neg_lo:[0,0,1]
	ds_write_b64 v3, v[102:103] offset:59136
	v_pk_mul_f32 v[188:189], v[130:131], v[34:35] op_sel:[1,1] op_sel_hi:[0,1]
	v_pk_fma_f32 v[186:187], v[130:131], v[34:35], v[188:189] op_sel_hi:[1,0,1] neg_lo:[0,0,1]
	ds_write_b64 v3, v[186:187] offset:63360
	s_waitcnt lgkmcnt(0)
	s_barrier
	ds_read_b64 v[100:101], v5
	ds_read_b64 v[126:127], v5 offset:264
	ds_read_b64 v[104:105], v5 offset:528
	ds_read_b64 v[106:107], v5 offset:792
	ds_read_b64 v[108:109], v5 offset:1056
	ds_read_b64 v[118:119], v5 offset:1320
	ds_read_b64 v[112:113], v5 offset:1584
	ds_read_b64 v[114:115], v5 offset:1848
	ds_read_b64 v[116:117], v5 offset:2112
	ds_read_b64 v[182:183], v5 offset:2376
	ds_read_b64 v[120:121], v5 offset:2640
	ds_read_b64 v[122:123], v5 offset:2904
	s_waitcnt lgkmcnt(8)
	ds_read_b64 v[124:125], v5 offset:3168
	ds_read_b64 v[110:111], v5 offset:3432
	ds_read_b64 v[128:129], v5 offset:3696
	ds_read_b64 v[130:131], v5 offset:3960
	s_waitcnt lgkmcnt(7)
	v_pk_add_f32 v[180:181], v[100:101], v[116:117]
	v_pk_add_f32 v[168:169], v[100:101], v[116:117] neg_lo:[0,1] neg_hi:[0,1]
	s_waitcnt lgkmcnt(3)
	v_pk_add_f32 v[176:177], v[108:109], v[124:125]
	v_pk_add_f32 v[178:179], v[108:109], v[124:125] neg_lo:[0,1] neg_hi:[0,1]
	v_pk_add_f32 v[100:101], v[180:181], v[176:177]
	v_pk_add_f32 v[116:117], v[180:181], v[176:177] neg_lo:[0,1] neg_hi:[0,1]
	v_pk_add_f32 v[108:109], v[168:169], v[178:179] op_sel:[0,1] op_sel_hi:[1,0] neg_hi:[0,1]
	v_pk_add_f32 v[124:125], v[168:169], v[178:179] op_sel:[0,1] op_sel_hi:[1,0] neg_lo:[0,1]
	v_pk_add_f32 v[174:175], v[126:127], v[182:183]
	v_pk_add_f32 v[166:167], v[126:127], v[182:183] neg_lo:[0,1] neg_hi:[0,1]
	s_waitcnt lgkmcnt(2)
	v_pk_add_f32 v[184:185], v[118:119], v[110:111]
	v_pk_add_f32 v[102:103], v[118:119], v[110:111] neg_lo:[0,1] neg_hi:[0,1]
	v_pk_add_f32 v[126:127], v[174:175], v[184:185]
	v_pk_add_f32 v[182:183], v[174:175], v[184:185] neg_lo:[0,1] neg_hi:[0,1]
	v_pk_add_f32 v[118:119], v[166:167], v[102:103] op_sel:[0,1] op_sel_hi:[1,0] neg_hi:[0,1]
	v_pk_add_f32 v[110:111], v[166:167], v[102:103] op_sel:[0,1] op_sel_hi:[1,0] neg_lo:[0,1]
	v_pk_add_f32 v[188:189], v[104:105], v[120:121]
	v_pk_add_f32 v[186:187], v[104:105], v[120:121] neg_lo:[0,1] neg_hi:[0,1]
	s_waitcnt lgkmcnt(1)
	v_pk_add_f32 v[180:181], v[112:113], v[128:129]
	v_pk_add_f32 v[168:169], v[112:113], v[128:129] neg_lo:[0,1] neg_hi:[0,1]
	v_pk_add_f32 v[104:105], v[188:189], v[180:181]
	v_pk_add_f32 v[120:121], v[188:189], v[180:181] neg_lo:[0,1] neg_hi:[0,1]
	v_pk_add_f32 v[112:113], v[186:187], v[168:169] op_sel:[0,1] op_sel_hi:[1,0] neg_hi:[0,1]
	v_pk_add_f32 v[128:129], v[186:187], v[168:169] op_sel:[0,1] op_sel_hi:[1,0] neg_lo:[0,1]
	v_pk_add_f32 v[176:177], v[106:107], v[122:123]
	v_pk_add_f32 v[178:179], v[106:107], v[122:123] neg_lo:[0,1] neg_hi:[0,1]
	s_waitcnt lgkmcnt(0)
; #define LAS __attribute__((address_space(3)))
; __device__ __forceinline__ f32x2 cmul(f32x2 a, f32x2 b) { return (f32x2){a.x * b.x - a.y * b.y, a.x * b.y + a.y * b.x}; }
; template <bool INV> __device__ __forceinline__ f32x2 cmul_tw(f32x2 a, f32x2 w) { return INV ? cmulc(a, w) : cmul(a, w); }
; template <bool INV> __device__ __forceinline__ void dft16(f32x2 (&x)[16]) {
;     constexpr float C1 = 0.92387953251128674f, S1 = 0.38268343236508977f, C2 = 0.70710678118654752f;
; #pragma unroll
;     for (int b = 0; b < 4; ++b) dft4<INV>(x[b], x[4 + b], x[8 + b], x[12 + b]);
;     const f32x2 w1 = {C1, -S1}, w2 = {C2, -C2}, w3 = {S1, -C1}, w4 = {0.f, -1.f}, w6 = {-C2, -C2}, w9 = {-C1, S1};
;     x[4 * 1 + 1] = cmul_tw<INV>(x[5], w1); x[4 * 1 + 2] = cmul_tw<INV>(x[6], w2); x[4 * 1 + 3] = cmul_tw<INV>(x[7], w3);
;     x[4 * 2 + 1] = cmul_tw<INV>(x[9], w2); x[4 * 2 + 2] = cmul_tw<INV>(x[10], w4); x[4 * 2 + 3] = cmul_tw<INV>(x[11], w6);
;     x[4 * 3 + 1] = cmul_tw<INV>(x[13], w3); x[4 * 3 + 2] = cmul_tw<INV>(x[14], w6); x[4 * 3 + 3] = cmul_tw<INV>(x[15], w9);
; #pragma unroll
;     for (int c = 0; c < 4; ++c) dft4<INV>(x[4 * c], x[4 * c + 1], x[4 * c + 2], x[4 * c + 3]);
;     f32x2 y[16];
; #pragma unroll
;     for (int k = 0; k < 16; ++k) y[k] = x[4 * (k & 3) + (k >> 2)];
; #pragma unroll
;     for (int k = 0; k < 16; ++k) x[k] = y[k];
; __device__ __forceinline__ void fft_fwd2(LAS f32x2* B, const LAS f32x2* TW2, int tid) {
;     asm volatile("" : "+v"(tid));
;     const int b = tid >> 5, n2 = tid & 31, base = 512 * b + n2; f32x2 x[16];
; #pragma unroll
;     for (int r = 0; r < 16; ++r) x[r] = B[fpad(base + 32 * r)];
;     dft16<false>(x);
;     B[fpad(base)] = x[0];
; #pragma unroll
;     for (int k = 1; k < 16; ++k) B[fpad(base + 32 * k)] = cmul(x[k], TW2[k * 32 + n2]);
; }
	v_pk_add_f32 v[174:175], v[114:115], v[130:131]
	v_pk_add_f32 v[166:167], v[114:115], v[130:131] neg_lo:[0,1] neg_hi:[0,1]
	v_pk_add_f32 v[106:107], v[176:177], v[174:175]
	v_pk_add_f32 v[122:123], v[176:177], v[174:175] neg_lo:[0,1] neg_hi:[0,1]
	v_pk_add_f32 v[114:115], v[178:179], v[166:167] op_sel:[0,1] op_sel_hi:[1,0] neg_hi:[0,1]
	v_pk_add_f32 v[130:131], v[178:179], v[166:167] op_sel:[0,1] op_sel_hi:[1,0] neg_lo:[0,1]
	v_pk_mul_f32 v[184:185], v[118:119], s[68:69] op_sel:[1,1] op_sel_hi:[0,1]
	v_pk_fma_f32 v[118:119], v[118:119], s[68:69], v[184:185] op_sel_hi:[1,0,1] neg_lo:[0,0,1]
	v_pk_mul_f32 v[102:103], v[112:113], s[84:85] op_sel:[1,1] op_sel_hi:[0,1]
	v_pk_fma_f32 v[112:113], v[112:113], s[84:85], v[102:103] op_sel_hi:[1,0,1] neg_lo:[0,0,1]
	v_pk_mul_f32 v[188:189], v[114:115], s[88:89] op_sel:[1,1] op_sel_hi:[0,1]
	v_pk_fma_f32 v[114:115], v[114:115], s[88:89], v[188:189] op_sel_hi:[1,0,1] neg_lo:[0,0,1]
	v_pk_mul_f32 v[186:187], v[182:183], s[84:85] op_sel:[1,1] op_sel_hi:[0,1]
	v_pk_fma_f32 v[182:183], v[182:183], s[84:85], v[186:187] op_sel_hi:[1,0,1] neg_lo:[0,0,1]
	v_pk_mul_f32 v[180:181], v[122:123], s[90:91] op_sel:[1,1] op_sel_hi:[0,1]
	v_pk_fma_f32 v[122:123], v[122:123], s[90:91], v[180:181] op_sel_hi:[1,0,1] neg_lo:[0,0,1]
	v_pk_mul_f32 v[168:169], v[110:111], s[88:89] op_sel:[1,1] op_sel_hi:[0,1]
	v_pk_fma_f32 v[110:111], v[110:111], s[88:89], v[168:169] op_sel_hi:[1,0,1] neg_lo:[0,0,1]
	v_pk_mul_f32 v[176:177], v[128:129], s[90:91] op_sel:[1,1] op_sel_hi:[0,1]
	v_pk_fma_f32 v[128:129], v[128:129], s[90:91], v[176:177] op_sel_hi:[1,0,1] neg_lo:[0,0,1]
	v_pk_mul_f32 v[178:179], v[130:131], s[98:99] op_sel:[1,1] op_sel_hi:[0,1]
	v_pk_fma_f32 v[130:131], v[130:131], s[98:99], v[178:179] op_sel_hi:[1,0,1] neg_lo:[0,0,1]
	v_pk_add_f32 v[174:175], v[100:101], v[104:105]
	v_pk_add_f32 v[166:167], v[100:101], v[104:105] neg_lo:[0,1] neg_hi:[0,1]
	v_pk_add_f32 v[184:185], v[126:127], v[106:107]
	v_pk_add_f32 v[102:103], v[126:127], v[106:107] neg_lo:[0,1] neg_hi:[0,1]
	v_pk_add_f32 v[100:101], v[174:175], v[184:185]
	v_pk_add_f32 v[104:105], v[174:175], v[184:185] neg_lo:[0,1] neg_hi:[0,1]
	v_pk_add_f32 v[126:127], v[166:167], v[102:103] op_sel:[0,1] op_sel_hi:[1,0] neg_hi:[0,1]
	v_pk_add_f32 v[106:107], v[166:167], v[102:103] op_sel:[0,1] op_sel_hi:[1,0] neg_lo:[0,1]
	v_pk_add_f32 v[188:189], v[108:109], v[112:113]
	v_pk_add_f32 v[186:187], v[108:109], v[112:113] neg_lo:[0,1] neg_hi:[0,1]
	v_pk_add_f32 v[180:181], v[118:119], v[114:115]
	v_pk_add_f32 v[168:169], v[118:119], v[114:115] neg_lo:[0,1] neg_hi:[0,1]
	v_pk_add_f32 v[108:109], v[188:189], v[180:181]
	v_pk_add_f32 v[112:113], v[188:189], v[180:181] neg_lo:[0,1] neg_hi:[0,1]
	v_pk_add_f32 v[118:119], v[186:187], v[168:169] op_sel:[0,1] op_sel_hi:[1,0] neg_hi:[0,1]
	v_pk_add_f32 v[114:115], v[186:187], v[168:169] op_sel:[0,1] op_sel_hi:[1,0] neg_lo:[0,1]
	v_pk_add_f32 v[176:177], v[116:117], v[120:121] op_sel:[0,1] op_sel_hi:[1,0] neg_hi:[0,1]
	v_pk_add_f32 v[178:179], v[116:117], v[120:121] op_sel:[0,1] op_sel_hi:[1,0] neg_lo:[0,1]
	v_pk_add_f32 v[174:175], v[182:183], v[122:123]
	v_pk_add_f32 v[166:167], v[182:183], v[122:123] neg_lo:[0,1] neg_hi:[0,1]
	v_pk_add_f32 v[116:117], v[176:177], v[174:175]
	v_pk_add_f32 v[120:121], v[176:177], v[174:175] neg_lo:[0,1] neg_hi:[0,1]
	v_pk_add_f32 v[182:183], v[178:179], v[166:167] op_sel:[0,1] op_sel_hi:[1,0] neg_hi:[0,1]
	v_pk_add_f32 v[122:123], v[178:179], v[166:167] op_sel:[0,1] op_sel_hi:[1,0] neg_lo:[0,1]
	v_pk_add_f32 v[184:185], v[124:125], v[128:129]
	v_pk_add_f32 v[102:103], v[124:125], v[128:129] neg_lo:[0,1] neg_hi:[0,1]
	v_pk_add_f32 v[188:189], v[110:111], v[130:131]
	v_pk_add_f32 v[186:187], v[110:111], v[130:131] neg_lo:[0,1] neg_hi:[0,1]
	v_pk_add_f32 v[124:125], v[184:185], v[188:189]
	v_pk_add_f32 v[128:129], v[184:185], v[188:189] neg_lo:[0,1] neg_hi:[0,1]
	v_pk_add_f32 v[110:111], v[102:103], v[186:187] op_sel:[0,1] op_sel_hi:[1,0] neg_hi:[0,1]
	v_pk_add_f32 v[130:131], v[102:103], v[186:187] op_sel:[0,1] op_sel_hi:[1,0] neg_lo:[0,1]
	ds_write_b64 v5, v[100:101]
	ds_read_b64 v[180:181], v56 offset:256
	ds_read_b64 v[168:169], v56 offset:512
	ds_read_b64 v[176:177], v56 offset:768
	ds_read_b64 v[178:179], v56 offset:1024
	s_waitcnt lgkmcnt(3)
	v_pk_mul_f32 v[174:175], v[108:109], v[180:181] op_sel:[1,1] op_sel_hi:[0,1]
	v_pk_fma_f32 v[108:109], v[108:109], v[180:181], v[174:175] op_sel_hi:[1,0,1] neg_lo:[0,0,1]
	ds_write_b64 v5, v[108:109] offset:264
	s_waitcnt lgkmcnt(3)
	v_pk_mul_f32 v[166:167], v[116:117], v[168:169] op_sel:[1,1] op_sel_hi:[0,1]
	v_pk_fma_f32 v[116:117], v[116:117], v[168:169], v[166:167] op_sel_hi:[1,0,1] neg_lo:[0,0,1]
	ds_write_b64 v5, v[116:117] offset:528
	s_waitcnt lgkmcnt(3)
	v_pk_mul_f32 v[184:185], v[124:125], v[176:177] op_sel:[1,1] op_sel_hi:[0,1]
	v_pk_fma_f32 v[124:125], v[124:125], v[176:177], v[184:185] op_sel_hi:[1,0,1] neg_lo:[0,0,1]
	ds_write_b64 v5, v[124:125] offset:792
	s_waitcnt lgkmcnt(3)
	v_pk_mul_f32 v[102:103], v[126:127], v[178:179] op_sel:[1,1] op_sel_hi:[0,1]
	v_pk_fma_f32 v[126:127], v[126:127], v[178:179], v[102:103] op_sel_hi:[1,0,1] neg_lo:[0,0,1]
	ds_write_b64 v5, v[126:127] offset:1056
	ds_read_b64 v[188:189], v56 offset:1280
	ds_read_b64 v[186:187], v56 offset:1536
	ds_read_b64 v[174:175], v56 offset:1792
	ds_read_b64 v[166:167], v56 offset:2048
	s_waitcnt lgkmcnt(3)
	v_pk_mul_f32 v[184:185], v[118:119], v[188:189] op_sel:[1,1] op_sel_hi:[0,1]
	v_pk_fma_f32 v[118:119], v[118:119], v[188:189], v[184:185] op_sel_hi:[1,0,1] neg_lo:[0,0,1]
	ds_write_b64 v5, v[118:119] offset:1320
	s_waitcnt lgkmcnt(3)
; #define LAS __attribute__((address_space(3)))
; __device__ __forceinline__ f32x2 cmul(f32x2 a, f32x2 b) { return (f32x2){a.x * b.x - a.y * b.y, a.x * b.y + a.y * b.x}; }
; __device__ __forceinline__ void fft_fwd2(LAS f32x2* B, const LAS f32x2* TW2, int tid) {
;     ...
;     B[fpad(base)] = x[0];
; #pragma unroll
;     for (int k = 1; k < 16; ++k) B[fpad(base + 32 * k)] = cmul(x[k], TW2[k * 32 + n2]);
; }
; template <int MODE> __device__ __forceinline__ void fft_pair32(LAS f32x2* B, const LAS f32x2* F, int wave, int lane) {
;     asm volatile("" : "+v"(lane));
;     constexpr float CS[16] = {1.f, 0.98078528040323043f, 0.92387953251128674f, 0.83146961230254524f, 0.70710678118654752f, 0.55557023301960218f, 0.38268343236508977f, 0.19509032201612825f,
;                               0.f, -0.19509032201612825f, -0.38268343236508977f, -0.55557023301960218f, -0.70710678118654752f, -0.83146961230254524f, -0.92387953251128674f, -0.98078528040323043f};
;     constexpr float SN[16] = {0.f, 0.19509032201612825f, 0.38268343236508977f, 0.55557023301960218f, 0.70710678118654752f, 0.83146961230254524f, 0.92387953251128674f, 0.98078528040323043f,
;                               1.f, 0.98078528040323043f, 0.92387953251128674f, 0.83146961230254524f, 0.70710678118654752f, 0.55557023301960218f, 0.38268343236508977f, 0.19509032201612825f};
;     const int hi = lane >> 5, blk = 32 * wave + (lane & 31); const float sg = hi ? -1.f : 1.f;
;     LAS f32x2* p = B + 33 * blk; f32x2 v[16];
; #pragma unroll
;     for (int j = 0; j < 16; ++j) { const f32x2 d = p[j] + p[j + 16] * sg;
;         const f32x2 w = {hi ? CS[j] : 1.f, hi ? -SN[j] : 0.f}; v[j] = j == 0 ? d : cmul(d, w); }
	v_pk_mul_f32 v[102:103], v[182:183], v[186:187] op_sel:[1,1] op_sel_hi:[0,1]
	v_pk_fma_f32 v[182:183], v[182:183], v[186:187], v[102:103] op_sel_hi:[1,0,1] neg_lo:[0,0,1]
	ds_write_b64 v5, v[182:183] offset:1584
	s_waitcnt lgkmcnt(3)
	v_pk_mul_f32 v[180:181], v[110:111], v[174:175] op_sel:[1,1] op_sel_hi:[0,1]
	v_pk_fma_f32 v[110:111], v[110:111], v[174:175], v[180:181] op_sel_hi:[1,0,1] neg_lo:[0,0,1]
	ds_write_b64 v5, v[110:111] offset:1848
	s_waitcnt lgkmcnt(3)
	v_pk_mul_f32 v[168:169], v[104:105], v[166:167] op_sel:[1,1] op_sel_hi:[0,1]
	v_pk_fma_f32 v[104:105], v[104:105], v[166:167], v[168:169] op_sel_hi:[1,0,1] neg_lo:[0,0,1]
	ds_write_b64 v5, v[104:105] offset:2112
	ds_read_b64 v[176:177], v56 offset:2304
	ds_read_b64 v[178:179], v56 offset:2560
	ds_read_b64 v[184:185], v56 offset:2816
	ds_read_b64 v[102:103], v56 offset:3072
	s_waitcnt lgkmcnt(3)
	v_pk_mul_f32 v[180:181], v[112:113], v[176:177] op_sel:[1,1] op_sel_hi:[0,1]
	v_pk_fma_f32 v[112:113], v[112:113], v[176:177], v[180:181] op_sel_hi:[1,0,1] neg_lo:[0,0,1]
	ds_write_b64 v5, v[112:113] offset:2376
	s_waitcnt lgkmcnt(3)
	v_pk_mul_f32 v[168:169], v[120:121], v[178:179] op_sel:[1,1] op_sel_hi:[0,1]
	v_pk_fma_f32 v[120:121], v[120:121], v[178:179], v[168:169] op_sel_hi:[1,0,1] neg_lo:[0,0,1]
	ds_write_b64 v5, v[120:121] offset:2640
	s_waitcnt lgkmcnt(3)
	v_pk_mul_f32 v[188:189], v[128:129], v[184:185] op_sel:[1,1] op_sel_hi:[0,1]
	v_pk_fma_f32 v[128:129], v[128:129], v[184:185], v[188:189] op_sel_hi:[1,0,1] neg_lo:[0,0,1]
	ds_write_b64 v5, v[128:129] offset:2904
	s_waitcnt lgkmcnt(3)
	v_pk_mul_f32 v[186:187], v[106:107], v[102:103] op_sel:[1,1] op_sel_hi:[0,1]
	v_pk_fma_f32 v[106:107], v[106:107], v[102:103], v[186:187] op_sel_hi:[1,0,1] neg_lo:[0,0,1]
	ds_write_b64 v5, v[106:107] offset:3168
	ds_read_b64 v[174:175], v56 offset:3328
	ds_read_b64 v[166:167], v56 offset:3584
	ds_read_b64 v[180:181], v56 offset:3840
	s_waitcnt lgkmcnt(2)
	v_pk_mul_f32 v[168:169], v[114:115], v[174:175] op_sel:[1,1] op_sel_hi:[0,1]
	v_pk_fma_f32 v[114:115], v[114:115], v[174:175], v[168:169] op_sel_hi:[1,0,1] neg_lo:[0,0,1]
	ds_write_b64 v5, v[114:115] offset:3432
	s_waitcnt lgkmcnt(2)
	v_pk_mul_f32 v[188:189], v[122:123], v[166:167] op_sel:[1,1] op_sel_hi:[0,1]
	v_pk_fma_f32 v[122:123], v[122:123], v[166:167], v[188:189] op_sel_hi:[1,0,1] neg_lo:[0,0,1]
	ds_write_b64 v5, v[122:123] offset:3696
	s_waitcnt lgkmcnt(2)
	v_pk_mul_f32 v[186:187], v[130:131], v[180:181] op_sel:[1,1] op_sel_hi:[0,1]
	v_pk_fma_f32 v[130:131], v[130:131], v[180:181], v[186:187] op_sel_hi:[1,0,1] neg_lo:[0,0,1]
	ds_write_b64 v5, v[130:131] offset:3960
	s_waitcnt lgkmcnt(0)
	ds_read_b64 v[100:101], v156
	ds_read_b64 v[176:177], v156 offset:128
	ds_read_b64 v[108:109], v156 offset:8
	ds_read_b64 v[178:179], v156 offset:136
	ds_read_b64 v[116:117], v156 offset:16
	ds_read_b64 v[184:185], v156 offset:144
	ds_read_b64 v[124:125], v156 offset:24
	ds_read_b64 v[102:103], v156 offset:152
	s_waitcnt lgkmcnt(6)
	v_pk_fma_f32 v[100:101], v[176:177], v[190:191], v[100:101] op_sel_hi:[1,0,1]
	s_waitcnt lgkmcnt(4)
	v_pk_fma_f32 v[108:109], v[178:179], v[190:191], v[108:109] op_sel_hi:[1,0,1]
	v_pk_mul_f32 v[168:169], v[108:109], v[36:37] op_sel:[1,1] op_sel_hi:[0,1]
	v_pk_fma_f32 v[108:109], v[108:109], v[36:37], v[168:169] op_sel_hi:[1,0,1] neg_lo:[0,0,1]
	s_waitcnt lgkmcnt(2)
	v_pk_fma_f32 v[116:117], v[184:185], v[190:191], v[116:117] op_sel_hi:[1,0,1]
	v_pk_mul_f32 v[188:189], v[116:117], v[38:39] op_sel:[1,1] op_sel_hi:[0,1]
	v_pk_fma_f32 v[116:117], v[116:117], v[38:39], v[188:189] op_sel_hi:[1,0,1] neg_lo:[0,0,1]
	s_waitcnt lgkmcnt(0)
	v_pk_fma_f32 v[124:125], v[102:103], v[190:191], v[124:125] op_sel_hi:[1,0,1]
	v_pk_mul_f32 v[186:187], v[124:125], v[40:41] op_sel:[1,1] op_sel_hi:[0,1]
	v_pk_fma_f32 v[124:125], v[124:125], v[40:41], v[186:187] op_sel_hi:[1,0,1] neg_lo:[0,0,1]
	ds_read_b64 v[126:127], v156 offset:32
	ds_read_b64 v[174:175], v156 offset:160
	ds_read_b64 v[118:119], v156 offset:40
	ds_read_b64 v[166:167], v156 offset:168
	ds_read_b64 v[182:183], v156 offset:48
	ds_read_b64 v[180:181], v156 offset:176
	ds_read_b64 v[110:111], v156 offset:56
	ds_read_b64 v[168:169], v156 offset:184
	s_waitcnt lgkmcnt(6)
	v_pk_fma_f32 v[126:127], v[174:175], v[190:191], v[126:127] op_sel_hi:[1,0,1]
	v_pk_mul_f32 v[188:189], v[126:127], v[42:43] op_sel:[1,1] op_sel_hi:[0,1]
	v_pk_fma_f32 v[126:127], v[126:127], v[42:43], v[188:189] op_sel_hi:[1,0,1] neg_lo:[0,0,1]
	s_waitcnt lgkmcnt(4)
	v_pk_fma_f32 v[118:119], v[166:167], v[190:191], v[118:119] op_sel_hi:[1,0,1]
	v_pk_mul_f32 v[186:187], v[118:119], v[44:45] op_sel:[1,1] op_sel_hi:[0,1]
	v_pk_fma_f32 v[118:119], v[118:119], v[44:45], v[186:187] op_sel_hi:[1,0,1] neg_lo:[0,0,1]
	s_waitcnt lgkmcnt(2)
	v_pk_fma_f32 v[182:183], v[180:181], v[190:191], v[182:183] op_sel_hi:[1,0,1]
	v_pk_mul_f32 v[176:177], v[182:183], v[46:47] op_sel:[1,1] op_sel_hi:[0,1]
	v_pk_fma_f32 v[182:183], v[182:183], v[46:47], v[176:177] op_sel_hi:[1,0,1] neg_lo:[0,0,1]
	s_waitcnt lgkmcnt(0)
	v_pk_fma_f32 v[110:111], v[168:169], v[190:191], v[110:111] op_sel_hi:[1,0,1]
	v_pk_mul_f32 v[178:179], v[110:111], v[48:49] op_sel:[1,1] op_sel_hi:[0,1]
	v_pk_fma_f32 v[110:111], v[110:111], v[48:49], v[178:179] op_sel_hi:[1,0,1] neg_lo:[0,0,1]
	ds_read_b64 v[104:105], v156 offset:64
	ds_read_b64 v[184:185], v156 offset:192
	ds_read_b64 v[112:113], v156 offset:72
	ds_read_b64 v[102:103], v156 offset:200
	ds_read_b64 v[120:121], v156 offset:80
	ds_read_b64 v[188:189], v156 offset:208
	ds_read_b64 v[128:129], v156 offset:88
	ds_read_b64 v[186:187], v156 offset:216
	s_waitcnt lgkmcnt(6)
; #define LAS __attribute__((address_space(3)))
; __device__ __forceinline__ f32x2 cmul(f32x2 a, f32x2 b) { return (f32x2){a.x * b.x - a.y * b.y, a.x * b.y + a.y * b.x}; }
; template <bool INV> __device__ __forceinline__ f32x2 cmul_tw(f32x2 a, f32x2 w) { return INV ? cmulc(a, w) : cmul(a, w); }
; template <bool INV> __device__ __forceinline__ void dft16(f32x2 (&x)[16]) {
;     constexpr float C1 = 0.92387953251128674f, S1 = 0.38268343236508977f, C2 = 0.70710678118654752f;
; #pragma unroll
;     for (int b = 0; b < 4; ++b) dft4<INV>(x[b], x[4 + b], x[8 + b], x[12 + b]);
;     const f32x2 w1 = {C1, -S1}, w2 = {C2, -C2}, w3 = {S1, -C1}, w4 = {0.f, -1.f}, w6 = {-C2, -C2}, w9 = {-C1, S1};
;     x[4 * 1 + 1] = cmul_tw<INV>(x[5], w1); x[4 * 1 + 2] = cmul_tw<INV>(x[6], w2); x[4 * 1 + 3] = cmul_tw<INV>(x[7], w3);
;     x[4 * 2 + 1] = cmul_tw<INV>(x[9], w2); x[4 * 2 + 2] = cmul_tw<INV>(x[10], w4); x[4 * 2 + 3] = cmul_tw<INV>(x[11], w6);
;     x[4 * 3 + 1] = cmul_tw<INV>(x[13], w3); x[4 * 3 + 2] = cmul_tw<INV>(x[14], w6); x[4 * 3 + 3] = cmul_tw<INV>(x[15], w9);
; template <int MODE> __device__ __forceinline__ void fft_pair32(LAS f32x2* B, const LAS f32x2* F, int wave, int lane) {
;     asm volatile("" : "+v"(lane));
;     constexpr float CS[16] = {1.f, 0.98078528040323043f, 0.92387953251128674f, 0.83146961230254524f, 0.70710678118654752f, 0.55557023301960218f, 0.38268343236508977f, 0.19509032201612825f,
;                               0.f, -0.19509032201612825f, -0.38268343236508977f, -0.55557023301960218f, -0.70710678118654752f, -0.83146961230254524f, -0.92387953251128674f, -0.98078528040323043f};
;     constexpr float SN[16] = {0.f, 0.19509032201612825f, 0.38268343236508977f, 0.55557023301960218f, 0.70710678118654752f, 0.83146961230254524f, 0.92387953251128674f, 0.98078528040323043f,
;                               1.f, 0.98078528040323043f, 0.92387953251128674f, 0.83146961230254524f, 0.70710678118654752f, 0.55557023301960218f, 0.38268343236508977f, 0.19509032201612825f};
;     const int hi = lane >> 5, blk = 32 * wave + (lane & 31); const float sg = hi ? -1.f : 1.f;
;     LAS f32x2* p = B + 33 * blk; f32x2 v[16];
; #pragma unroll
;     for (int j = 0; j < 16; ++j) { const f32x2 d = p[j] + p[j + 16] * sg;
;         const f32x2 w = {hi ? CS[j] : 1.f, hi ? -SN[j] : 0.f}; v[j] = j == 0 ? d : cmul(d, w); }
;     dft16<false>(v);
	v_pk_fma_f32 v[104:105], v[184:185], v[190:191], v[104:105] op_sel_hi:[1,0,1]
	v_pk_mul_f32 v[176:177], v[104:105], v[50:51] op_sel:[1,1] op_sel_hi:[0,1]
	v_pk_fma_f32 v[104:105], v[104:105], v[50:51], v[176:177] op_sel_hi:[1,0,1] neg_lo:[0,0,1]
	s_waitcnt lgkmcnt(4)
	v_pk_fma_f32 v[112:113], v[102:103], v[190:191], v[112:113] op_sel_hi:[1,0,1]
	v_pk_mul_f32 v[178:179], v[112:113], v[52:53] op_sel:[1,1] op_sel_hi:[0,1]
	v_pk_fma_f32 v[112:113], v[112:113], v[52:53], v[178:179] op_sel_hi:[1,0,1] neg_lo:[0,0,1]
	s_waitcnt lgkmcnt(2)
	v_pk_fma_f32 v[120:121], v[188:189], v[190:191], v[120:121] op_sel_hi:[1,0,1]
	v_pk_mul_f32 v[174:175], v[120:121], v[54:55] op_sel:[1,1] op_sel_hi:[0,1]
	v_pk_fma_f32 v[120:121], v[120:121], v[54:55], v[174:175] op_sel_hi:[1,0,1] neg_lo:[0,0,1]
	s_waitcnt lgkmcnt(0)
	v_pk_fma_f32 v[128:129], v[186:187], v[190:191], v[128:129] op_sel_hi:[1,0,1]
	v_pk_mul_f32 v[166:167], v[128:129], v[90:91] op_sel:[1,1] op_sel_hi:[0,1]
	v_pk_fma_f32 v[128:129], v[128:129], v[90:91], v[166:167] op_sel_hi:[1,0,1] neg_lo:[0,0,1]
	ds_read_b64 v[106:107], v156 offset:96
	ds_read_b64 v[180:181], v156 offset:224
	ds_read_b64 v[114:115], v156 offset:104
	ds_read_b64 v[168:169], v156 offset:232
	ds_read_b64 v[122:123], v156 offset:112
	ds_read_b64 v[176:177], v156 offset:240
	ds_read_b64 v[130:131], v156 offset:120
	ds_read_b64 v[178:179], v156 offset:248
	s_waitcnt lgkmcnt(6)
	v_pk_fma_f32 v[106:107], v[180:181], v[190:191], v[106:107] op_sel_hi:[1,0,1]
	v_pk_mul_f32 v[174:175], v[106:107], v[92:93] op_sel:[1,1] op_sel_hi:[0,1]
	v_pk_fma_f32 v[106:107], v[106:107], v[92:93], v[174:175] op_sel_hi:[1,0,1] neg_lo:[0,0,1]
	s_waitcnt lgkmcnt(4)
	v_pk_fma_f32 v[114:115], v[168:169], v[190:191], v[114:115] op_sel_hi:[1,0,1]
	v_pk_mul_f32 v[166:167], v[114:115], v[94:95] op_sel:[1,1] op_sel_hi:[0,1]
	v_pk_fma_f32 v[114:115], v[114:115], v[94:95], v[166:167] op_sel_hi:[1,0,1] neg_lo:[0,0,1]
	s_waitcnt lgkmcnt(2)
	v_pk_fma_f32 v[122:123], v[176:177], v[190:191], v[122:123] op_sel_hi:[1,0,1]
	v_pk_mul_f32 v[184:185], v[122:123], v[96:97] op_sel:[1,1] op_sel_hi:[0,1]
	v_pk_fma_f32 v[122:123], v[122:123], v[96:97], v[184:185] op_sel_hi:[1,0,1] neg_lo:[0,0,1]
	s_waitcnt lgkmcnt(0)
	v_pk_fma_f32 v[130:131], v[178:179], v[190:191], v[130:131] op_sel_hi:[1,0,1]
	v_pk_mul_f32 v[102:103], v[130:131], v[98:99] op_sel:[1,1] op_sel_hi:[0,1]
	v_pk_fma_f32 v[130:131], v[130:131], v[98:99], v[102:103] op_sel_hi:[1,0,1] neg_lo:[0,0,1]
	v_pk_add_f32 v[188:189], v[100:101], v[104:105]
	v_pk_add_f32 v[186:187], v[100:101], v[104:105] neg_lo:[0,1] neg_hi:[0,1]
	v_pk_add_f32 v[174:175], v[126:127], v[106:107]
	v_pk_add_f32 v[166:167], v[126:127], v[106:107] neg_lo:[0,1] neg_hi:[0,1]
	v_pk_add_f32 v[100:101], v[188:189], v[174:175]
	v_pk_add_f32 v[104:105], v[188:189], v[174:175] neg_lo:[0,1] neg_hi:[0,1]
	v_pk_add_f32 v[126:127], v[186:187], v[166:167] op_sel:[0,1] op_sel_hi:[1,0] neg_hi:[0,1]
	v_pk_add_f32 v[106:107], v[186:187], v[166:167] op_sel:[0,1] op_sel_hi:[1,0] neg_lo:[0,1]
	v_pk_add_f32 v[184:185], v[108:109], v[112:113]
	v_pk_add_f32 v[102:103], v[108:109], v[112:113] neg_lo:[0,1] neg_hi:[0,1]
	v_pk_add_f32 v[180:181], v[118:119], v[114:115]
	v_pk_add_f32 v[168:169], v[118:119], v[114:115] neg_lo:[0,1] neg_hi:[0,1]
	v_pk_add_f32 v[108:109], v[184:185], v[180:181]
	v_pk_add_f32 v[112:113], v[184:185], v[180:181] neg_lo:[0,1] neg_hi:[0,1]
	v_pk_add_f32 v[118:119], v[102:103], v[168:169] op_sel:[0,1] op_sel_hi:[1,0] neg_hi:[0,1]
	v_pk_add_f32 v[114:115], v[102:103], v[168:169] op_sel:[0,1] op_sel_hi:[1,0] neg_lo:[0,1]
	v_pk_add_f32 v[176:177], v[116:117], v[120:121]
	v_pk_add_f32 v[178:179], v[116:117], v[120:121] neg_lo:[0,1] neg_hi:[0,1]
	v_pk_add_f32 v[188:189], v[182:183], v[122:123]
	v_pk_add_f32 v[186:187], v[182:183], v[122:123] neg_lo:[0,1] neg_hi:[0,1]
	v_pk_add_f32 v[116:117], v[176:177], v[188:189]
	v_pk_add_f32 v[120:121], v[176:177], v[188:189] neg_lo:[0,1] neg_hi:[0,1]
	v_pk_add_f32 v[182:183], v[178:179], v[186:187] op_sel:[0,1] op_sel_hi:[1,0] neg_hi:[0,1]
	v_pk_add_f32 v[122:123], v[178:179], v[186:187] op_sel:[0,1] op_sel_hi:[1,0] neg_lo:[0,1]
	v_pk_add_f32 v[174:175], v[124:125], v[128:129]
	v_pk_add_f32 v[166:167], v[124:125], v[128:129] neg_lo:[0,1] neg_hi:[0,1]
	v_pk_add_f32 v[184:185], v[110:111], v[130:131]
	v_pk_add_f32 v[102:103], v[110:111], v[130:131] neg_lo:[0,1] neg_hi:[0,1]
	v_pk_add_f32 v[124:125], v[174:175], v[184:185]
	v_pk_add_f32 v[128:129], v[174:175], v[184:185] neg_lo:[0,1] neg_hi:[0,1]
	v_pk_add_f32 v[110:111], v[166:167], v[102:103] op_sel:[0,1] op_sel_hi:[1,0] neg_hi:[0,1]
	v_pk_add_f32 v[130:131], v[166:167], v[102:103] op_sel:[0,1] op_sel_hi:[1,0] neg_lo:[0,1]
	v_pk_mul_f32 v[180:181], v[118:119], s[68:69] op_sel:[1,1] op_sel_hi:[0,1]
	v_pk_fma_f32 v[118:119], v[118:119], s[68:69], v[180:181] op_sel_hi:[1,0,1] neg_lo:[0,0,1]
	v_pk_mul_f32 v[168:169], v[182:183], s[84:85] op_sel:[1,1] op_sel_hi:[0,1]
	v_pk_fma_f32 v[182:183], v[182:183], s[84:85], v[168:169] op_sel_hi:[1,0,1] neg_lo:[0,0,1]
	v_pk_mul_f32 v[176:177], v[110:111], s[88:89] op_sel:[1,1] op_sel_hi:[0,1]
	v_pk_fma_f32 v[110:111], v[110:111], s[88:89], v[176:177] op_sel_hi:[1,0,1] neg_lo:[0,0,1]
	v_pk_mul_f32 v[178:179], v[112:113], s[84:85] op_sel:[1,1] op_sel_hi:[0,1]
	v_pk_fma_f32 v[112:113], v[112:113], s[84:85], v[178:179] op_sel_hi:[1,0,1] neg_lo:[0,0,1]
	v_pk_mul_f32 v[188:189], v[128:129], s[90:91] op_sel:[1,1] op_sel_hi:[0,1]
	v_pk_fma_f32 v[128:129], v[128:129], s[90:91], v[188:189] op_sel_hi:[1,0,1] neg_lo:[0,0,1]
	v_pk_mul_f32 v[186:187], v[114:115], s[88:89] op_sel:[1,1] op_sel_hi:[0,1]
	v_pk_fma_f32 v[114:115], v[114:115], s[88:89], v[186:187] op_sel_hi:[1,0,1] neg_lo:[0,0,1]
; #define LAS __attribute__((address_space(3)))
; __device__ __forceinline__ f32x2 cmul(f32x2 a, f32x2 b) { return (f32x2){a.x * b.x - a.y * b.y, a.x * b.y + a.y * b.x}; }
; template <bool INV> __device__ __forceinline__ f32x2 cmul_tw(f32x2 a, f32x2 w) { return INV ? cmulc(a, w) : cmul(a, w); }
; template <bool INV> __device__ __forceinline__ void dft16(f32x2 (&x)[16]) {
;     constexpr float C1 = 0.92387953251128674f, S1 = 0.38268343236508977f, C2 = 0.70710678118654752f;
; #pragma unroll
;     for (int b = 0; b < 4; ++b) dft4<INV>(x[b], x[4 + b], x[8 + b], x[12 + b]);
;     const f32x2 w1 = {C1, -S1}, w2 = {C2, -C2}, w3 = {S1, -C1}, w4 = {0.f, -1.f}, w6 = {-C2, -C2}, w9 = {-C1, S1};
;     x[4 * 1 + 1] = cmul_tw<INV>(x[5], w1); x[4 * 1 + 2] = cmul_tw<INV>(x[6], w2); x[4 * 1 + 3] = cmul_tw<INV>(x[7], w3);
;     x[4 * 2 + 1] = cmul_tw<INV>(x[9], w2); x[4 * 2 + 2] = cmul_tw<INV>(x[10], w4); x[4 * 2 + 3] = cmul_tw<INV>(x[11], w6);
;     x[4 * 3 + 1] = cmul_tw<INV>(x[13], w3); x[4 * 3 + 2] = cmul_tw<INV>(x[14], w6); x[4 * 3 + 3] = cmul_tw<INV>(x[15], w9);
; #pragma unroll
;     for (int c = 0; c < 4; ++c) dft4<INV>(x[4 * c], x[4 * c + 1], x[4 * c + 2], x[4 * c + 3]);
;     f32x2 y[16];
; #pragma unroll
;     for (int k = 0; k < 16; ++k) y[k] = x[4 * (k & 3) + (k >> 2)];
; #pragma unroll
;     for (int k = 0; k < 16; ++k) x[k] = y[k];
; }
; template <int MODE> __device__ __forceinline__ void fft_pair32(LAS f32x2* B, const LAS f32x2* F, int wave, int lane) {
;     ...
;     const int k1 = blk >> 4, k2 = blk & 15, kb1 = (16 - k1) & 15, b1 = k1 != 0 ? 1 : 0, kb2 = (16 - k2 - b1) & 15, b2 = (k2 != 0 || b1) ? 1 : 0;
;     const LAS f32x2* fa = F + 33 * blk; const LAS f32x2* fb = F + 33 * (16 * kb1 + kb2);
;     const LAS f32x2* fah = fa + hi; const LAS f32x2* fbh = fb + (1 - b2) - hi;
;     constexpr float SC = 1.0f / (2.0f * (float)FN);
; #pragma unroll
;     for (int k = 0; k < 16; ++k) { const f32x2 A = fah[2 * k]; f32x2 Bm = fbh[31 - 2 * k];
;         if (k == 0) { const f32x2 m0 = b2 ? fb[31] : fa[0]; Bm = hi ? Bm : m0; }
;         const f32x2 H = MODE == 0 ? (f32x2){(A.x + Bm.x) * SC, (A.y - Bm.y) * SC} : (f32x2){(A.y + Bm.y) * SC, (Bm.x - A.x) * SC};
;         v[k] = cmul(v[k], H); }
;     dft16<true>(v);
	v_pk_mul_f32 v[174:175], v[122:123], s[90:91] op_sel:[1,1] op_sel_hi:[0,1]
	v_pk_fma_f32 v[122:123], v[122:123], s[90:91], v[174:175] op_sel_hi:[1,0,1] neg_lo:[0,0,1]
	v_pk_mul_f32 v[166:167], v[130:131], s[98:99] op_sel:[1,1] op_sel_hi:[0,1]
	v_pk_fma_f32 v[130:131], v[130:131], s[98:99], v[166:167] op_sel_hi:[1,0,1] neg_lo:[0,0,1]
	v_pk_add_f32 v[184:185], v[100:101], v[116:117]
	v_pk_add_f32 v[102:103], v[100:101], v[116:117] neg_lo:[0,1] neg_hi:[0,1]
	v_pk_add_f32 v[180:181], v[108:109], v[124:125]
	v_pk_add_f32 v[168:169], v[108:109], v[124:125] neg_lo:[0,1] neg_hi:[0,1]
	v_pk_add_f32 v[100:101], v[184:185], v[180:181]
	v_pk_add_f32 v[116:117], v[184:185], v[180:181] neg_lo:[0,1] neg_hi:[0,1]
	v_pk_add_f32 v[108:109], v[102:103], v[168:169] op_sel:[0,1] op_sel_hi:[1,0] neg_hi:[0,1]
	v_pk_add_f32 v[124:125], v[102:103], v[168:169] op_sel:[0,1] op_sel_hi:[1,0] neg_lo:[0,1]
	v_pk_add_f32 v[176:177], v[126:127], v[182:183]
	v_pk_add_f32 v[178:179], v[126:127], v[182:183] neg_lo:[0,1] neg_hi:[0,1]
	v_pk_add_f32 v[188:189], v[118:119], v[110:111]
	v_pk_add_f32 v[186:187], v[118:119], v[110:111] neg_lo:[0,1] neg_hi:[0,1]
	v_pk_add_f32 v[126:127], v[176:177], v[188:189]
	v_pk_add_f32 v[182:183], v[176:177], v[188:189] neg_lo:[0,1] neg_hi:[0,1]
	v_pk_add_f32 v[118:119], v[178:179], v[186:187] op_sel:[0,1] op_sel_hi:[1,0] neg_hi:[0,1]
	v_pk_add_f32 v[110:111], v[178:179], v[186:187] op_sel:[0,1] op_sel_hi:[1,0] neg_lo:[0,1]
	v_pk_add_f32 v[174:175], v[104:105], v[120:121] op_sel:[0,1] op_sel_hi:[1,0] neg_hi:[0,1]
	v_pk_add_f32 v[166:167], v[104:105], v[120:121] op_sel:[0,1] op_sel_hi:[1,0] neg_lo:[0,1]
	v_pk_add_f32 v[184:185], v[112:113], v[128:129]
	v_pk_add_f32 v[102:103], v[112:113], v[128:129] neg_lo:[0,1] neg_hi:[0,1]
	v_pk_add_f32 v[104:105], v[174:175], v[184:185]
	v_pk_add_f32 v[120:121], v[174:175], v[184:185] neg_lo:[0,1] neg_hi:[0,1]
	v_pk_add_f32 v[112:113], v[166:167], v[102:103] op_sel:[0,1] op_sel_hi:[1,0] neg_hi:[0,1]
	v_pk_add_f32 v[128:129], v[166:167], v[102:103] op_sel:[0,1] op_sel_hi:[1,0] neg_lo:[0,1]
	v_pk_add_f32 v[180:181], v[106:107], v[122:123]
	v_pk_add_f32 v[168:169], v[106:107], v[122:123] neg_lo:[0,1] neg_hi:[0,1]
	v_pk_add_f32 v[176:177], v[114:115], v[130:131]
	v_pk_add_f32 v[178:179], v[114:115], v[130:131] neg_lo:[0,1] neg_hi:[0,1]
	v_pk_add_f32 v[106:107], v[180:181], v[176:177]
	v_pk_add_f32 v[122:123], v[180:181], v[176:177] neg_lo:[0,1] neg_hi:[0,1]
	v_pk_add_f32 v[114:115], v[168:169], v[178:179] op_sel:[0,1] op_sel_hi:[1,0] neg_hi:[0,1]
	v_pk_add_f32 v[130:131], v[168:169], v[178:179] op_sel:[0,1] op_sel_hi:[1,0] neg_lo:[0,1]
	ds_read_b64 v[188:189], v200
	ds_read_b64 v[184:185], v204
	ds_read_b64 v[186:187], v200 offset:16
	ds_read_b64 v[102:103], v202 offset:232
	ds_read_b64 v[174:175], v200 offset:32
	ds_read_b64 v[180:181], v202 offset:216
	ds_read_b64 v[166:167], v200 offset:48
	ds_read_b64 v[168:169], v202 offset:200
	s_waitcnt lgkmcnt(6)
	v_pk_add_f32 v[188:189], v[188:189], v[184:185] op_sel:[1,1] op_sel_hi:[0,0] neg_hi:[1,0]
	v_pk_mul_f32 v[176:177], v[100:101], v[188:189] op_sel:[1,1] op_sel_hi:[0,1]
	v_pk_fma_f32 v[100:101], v[100:101], v[188:189], v[176:177] op_sel_hi:[1,0,1] neg_lo:[0,0,1]
	s_waitcnt lgkmcnt(4)
	v_pk_add_f32 v[186:187], v[186:187], v[102:103] op_sel:[1,1] op_sel_hi:[0,0] neg_hi:[1,0]
	v_pk_mul_f32 v[178:179], v[126:127], v[186:187] op_sel:[1,1] op_sel_hi:[0,1]
	v_pk_fma_f32 v[126:127], v[126:127], v[186:187], v[178:179] op_sel_hi:[1,0,1] neg_lo:[0,0,1]
	s_waitcnt lgkmcnt(2)
	v_pk_add_f32 v[174:175], v[174:175], v[180:181] op_sel:[1,1] op_sel_hi:[0,0] neg_hi:[1,0]
	v_pk_mul_f32 v[176:177], v[104:105], v[174:175] op_sel:[1,1] op_sel_hi:[0,1]
	v_pk_fma_f32 v[104:105], v[104:105], v[174:175], v[176:177] op_sel_hi:[1,0,1] neg_lo:[0,0,1]
	s_waitcnt lgkmcnt(0)
	v_pk_add_f32 v[166:167], v[166:167], v[168:169] op_sel:[1,1] op_sel_hi:[0,0] neg_hi:[1,0]
	v_pk_mul_f32 v[178:179], v[106:107], v[166:167] op_sel:[1,1] op_sel_hi:[0,1]
	v_pk_fma_f32 v[106:107], v[106:107], v[166:167], v[178:179] op_sel_hi:[1,0,1] neg_lo:[0,0,1]
	ds_read_b64 v[176:177], v200 offset:64
	ds_read_b64 v[174:175], v202 offset:184
	ds_read_b64 v[178:179], v200 offset:80
	ds_read_b64 v[166:167], v202 offset:168
	ds_read_b64 v[188:189], v200 offset:96
	ds_read_b64 v[184:185], v202 offset:152
	ds_read_b64 v[186:187], v200 offset:112
	ds_read_b64 v[102:103], v202 offset:136
	s_waitcnt lgkmcnt(6)
	v_pk_add_f32 v[176:177], v[176:177], v[174:175] op_sel:[1,1] op_sel_hi:[0,0] neg_hi:[1,0]
	v_pk_mul_f32 v[180:181], v[108:109], v[176:177] op_sel:[1,1] op_sel_hi:[0,1]
	v_pk_fma_f32 v[108:109], v[108:109], v[176:177], v[180:181] op_sel_hi:[1,0,1] neg_lo:[0,0,1]
	s_waitcnt lgkmcnt(4)
	v_pk_add_f32 v[178:179], v[178:179], v[166:167] op_sel:[1,1] op_sel_hi:[0,0] neg_hi:[1,0]
	v_pk_mul_f32 v[168:169], v[118:119], v[178:179] op_sel:[1,1] op_sel_hi:[0,1]
	v_pk_fma_f32 v[118:119], v[118:119], v[178:179], v[168:169] op_sel_hi:[1,0,1] neg_lo:[0,0,1]
	s_waitcnt lgkmcnt(2)
	v_pk_add_f32 v[188:189], v[188:189], v[184:185] op_sel:[1,1] op_sel_hi:[0,0] neg_hi:[1,0]
	v_pk_mul_f32 v[180:181], v[112:113], v[188:189] op_sel:[1,1] op_sel_hi:[0,1]
	v_pk_fma_f32 v[112:113], v[112:113], v[188:189], v[180:181] op_sel_hi:[1,0,1] neg_lo:[0,0,1]
	s_waitcnt lgkmcnt(0)
	v_pk_add_f32 v[186:187], v[186:187], v[102:103] op_sel:[1,1] op_sel_hi:[0,0] neg_hi:[1,0]
	v_pk_mul_f32 v[168:169], v[114:115], v[186:187] op_sel:[1,1] op_sel_hi:[0,1]
	v_pk_fma_f32 v[114:115], v[114:115], v[186:187], v[168:169] op_sel_hi:[1,0,1] neg_lo:[0,0,1]
	ds_read_b64 v[180:181], v200 offset:128
	ds_read_b64 v[188:189], v202 offset:120
	ds_read_b64 v[168:169], v200 offset:144
	ds_read_b64 v[186:187], v202 offset:104
	ds_read_b64 v[176:177], v200 offset:160
	ds_read_b64 v[174:175], v202 offset:88
	ds_read_b64 v[178:179], v200 offset:176
	ds_read_b64 v[166:167], v202 offset:72
	s_waitcnt lgkmcnt(6)
; __device__ __forceinline__ f32x2 cmul(f32x2 a, f32x2 b) { return (f32x2){a.x * b.x - a.y * b.y, a.x * b.y + a.y * b.x}; }
; template <bool INV> __device__ __forceinline__ f32x2 cmul_tw(f32x2 a, f32x2 w) { return INV ? cmulc(a, w) : cmul(a, w); }
; template <bool INV> __device__ __forceinline__ void dft16(f32x2 (&x)[16]) {
;     constexpr float C1 = 0.92387953251128674f, S1 = 0.38268343236508977f, C2 = 0.70710678118654752f;
; #pragma unroll
;     for (int b = 0; b < 4; ++b) dft4<INV>(x[b], x[4 + b], x[8 + b], x[12 + b]);
;     const f32x2 w1 = {C1, -S1}, w2 = {C2, -C2}, w3 = {S1, -C1}, w4 = {0.f, -1.f}, w6 = {-C2, -C2}, w9 = {-C1, S1};
;     x[4 * 1 + 1] = cmul_tw<INV>(x[5], w1); x[4 * 1 + 2] = cmul_tw<INV>(x[6], w2); x[4 * 1 + 3] = cmul_tw<INV>(x[7], w3);
;     x[4 * 2 + 1] = cmul_tw<INV>(x[9], w2); x[4 * 2 + 2] = cmul_tw<INV>(x[10], w4); x[4 * 2 + 3] = cmul_tw<INV>(x[11], w6);
;     x[4 * 3 + 1] = cmul_tw<INV>(x[13], w3); x[4 * 3 + 2] = cmul_tw<INV>(x[14], w6); x[4 * 3 + 3] = cmul_tw<INV>(x[15], w9);
; #pragma unroll
;     for (int c = 0; c < 4; ++c) dft4<INV>(x[4 * c], x[4 * c + 1], x[4 * c + 2], x[4 * c + 3]);
;     f32x2 y[16];
; #pragma unroll
;     for (int k = 0; k < 16; ++k) y[k] = x[4 * (k & 3) + (k >> 2)];
; #pragma unroll
;     for (int k = 0; k < 16; ++k) x[k] = y[k];
; }
; template <int MODE> __device__ __forceinline__ void fft_pair32(LAS f32x2* B, const LAS f32x2* F, int wave, int lane) {
;     ...
;     for (int k = 0; k < 16; ++k) { const f32x2 A = fah[2 * k]; f32x2 Bm = fbh[31 - 2 * k];
;         if (k == 0) { const f32x2 m0 = b2 ? fb[31] : fa[0]; Bm = hi ? Bm : m0; }
;         const f32x2 H = MODE == 0 ? (f32x2){(A.x + Bm.x) * SC, (A.y - Bm.y) * SC} : (f32x2){(A.y + Bm.y) * SC, (Bm.x - A.x) * SC};
;         v[k] = cmul(v[k], H); }
;     dft16<true>(v);
	v_pk_add_f32 v[180:181], v[180:181], v[188:189] op_sel:[1,1] op_sel_hi:[0,0] neg_hi:[1,0]
	v_pk_mul_f32 v[184:185], v[116:117], v[180:181] op_sel:[1,1] op_sel_hi:[0,1]
	v_pk_fma_f32 v[116:117], v[116:117], v[180:181], v[184:185] op_sel_hi:[1,0,1] neg_lo:[0,0,1]
	s_waitcnt lgkmcnt(4)
	v_pk_add_f32 v[168:169], v[168:169], v[186:187] op_sel:[1,1] op_sel_hi:[0,0] neg_hi:[1,0]
	v_pk_mul_f32 v[102:103], v[182:183], v[168:169] op_sel:[1,1] op_sel_hi:[0,1]
	v_pk_fma_f32 v[182:183], v[182:183], v[168:169], v[102:103] op_sel_hi:[1,0,1] neg_lo:[0,0,1]
	s_waitcnt lgkmcnt(2)
	v_pk_add_f32 v[176:177], v[176:177], v[174:175] op_sel:[1,1] op_sel_hi:[0,0] neg_hi:[1,0]
	v_pk_mul_f32 v[184:185], v[120:121], v[176:177] op_sel:[1,1] op_sel_hi:[0,1]
	v_pk_fma_f32 v[120:121], v[120:121], v[176:177], v[184:185] op_sel_hi:[1,0,1] neg_lo:[0,0,1]
	s_waitcnt lgkmcnt(0)
	v_pk_add_f32 v[178:179], v[178:179], v[166:167] op_sel:[1,1] op_sel_hi:[0,0] neg_hi:[1,0]
	v_pk_mul_f32 v[102:103], v[122:123], v[178:179] op_sel:[1,1] op_sel_hi:[0,1]
	v_pk_fma_f32 v[122:123], v[122:123], v[178:179], v[102:103] op_sel_hi:[1,0,1] neg_lo:[0,0,1]
	ds_read_b64 v[184:185], v200 offset:192
	ds_read_b64 v[176:177], v202 offset:56
	ds_read_b64 v[102:103], v200 offset:208
	ds_read_b64 v[178:179], v202 offset:40
	ds_read_b64 v[180:181], v200 offset:224
	ds_read_b64 v[188:189], v202 offset:24
	ds_read_b64 v[168:169], v200 offset:240
	ds_read_b64 v[186:187], v202 offset:8
	s_waitcnt lgkmcnt(6)
	v_pk_add_f32 v[184:185], v[184:185], v[176:177] op_sel:[1,1] op_sel_hi:[0,0] neg_hi:[1,0]
	v_pk_mul_f32 v[174:175], v[124:125], v[184:185] op_sel:[1,1] op_sel_hi:[0,1]
	v_pk_fma_f32 v[124:125], v[124:125], v[184:185], v[174:175] op_sel_hi:[1,0,1] neg_lo:[0,0,1]
	s_waitcnt lgkmcnt(4)
	v_pk_add_f32 v[102:103], v[102:103], v[178:179] op_sel:[1,1] op_sel_hi:[0,0] neg_hi:[1,0]
	v_pk_mul_f32 v[166:167], v[110:111], v[102:103] op_sel:[1,1] op_sel_hi:[0,1]
	v_pk_fma_f32 v[110:111], v[110:111], v[102:103], v[166:167] op_sel_hi:[1,0,1] neg_lo:[0,0,1]
	s_waitcnt lgkmcnt(2)
	v_pk_add_f32 v[180:181], v[180:181], v[188:189] op_sel:[1,1] op_sel_hi:[0,0] neg_hi:[1,0]
	v_pk_mul_f32 v[174:175], v[128:129], v[180:181] op_sel:[1,1] op_sel_hi:[0,1]
	v_pk_fma_f32 v[128:129], v[128:129], v[180:181], v[174:175] op_sel_hi:[1,0,1] neg_lo:[0,0,1]
	s_waitcnt lgkmcnt(0)
	v_pk_add_f32 v[168:169], v[168:169], v[186:187] op_sel:[1,1] op_sel_hi:[0,0] neg_hi:[1,0]
	v_pk_mul_f32 v[166:167], v[130:131], v[168:169] op_sel:[1,1] op_sel_hi:[0,1]
	v_pk_fma_f32 v[130:131], v[130:131], v[168:169], v[166:167] op_sel_hi:[1,0,1] neg_lo:[0,0,1]
	v_pk_add_f32 v[174:175], v[100:101], v[116:117]
	v_pk_add_f32 v[166:167], v[100:101], v[116:117] neg_lo:[0,1] neg_hi:[0,1]
	v_pk_add_f32 v[184:185], v[108:109], v[124:125]
	v_pk_add_f32 v[102:103], v[108:109], v[124:125] neg_lo:[0,1] neg_hi:[0,1]
	v_pk_add_f32 v[100:101], v[174:175], v[184:185]
	v_pk_add_f32 v[116:117], v[174:175], v[184:185] neg_lo:[0,1] neg_hi:[0,1]
	v_pk_add_f32 v[108:109], v[166:167], v[102:103] op_sel:[0,1] op_sel_hi:[1,0] neg_lo:[0,1]
	v_pk_add_f32 v[124:125], v[166:167], v[102:103] op_sel:[0,1] op_sel_hi:[1,0] neg_hi:[0,1]
	v_pk_add_f32 v[180:181], v[126:127], v[182:183]
	v_pk_add_f32 v[168:169], v[126:127], v[182:183] neg_lo:[0,1] neg_hi:[0,1]
	v_pk_add_f32 v[176:177], v[118:119], v[110:111]
	v_pk_add_f32 v[178:179], v[118:119], v[110:111] neg_lo:[0,1] neg_hi:[0,1]
	v_pk_add_f32 v[126:127], v[180:181], v[176:177]
	v_pk_add_f32 v[182:183], v[180:181], v[176:177] neg_lo:[0,1] neg_hi:[0,1]
	v_pk_add_f32 v[118:119], v[168:169], v[178:179] op_sel:[0,1] op_sel_hi:[1,0] neg_lo:[0,1]
	v_pk_add_f32 v[110:111], v[168:169], v[178:179] op_sel:[0,1] op_sel_hi:[1,0] neg_hi:[0,1]
	v_pk_add_f32 v[188:189], v[104:105], v[120:121]
	v_pk_add_f32 v[186:187], v[104:105], v[120:121] neg_lo:[0,1] neg_hi:[0,1]
	v_pk_add_f32 v[174:175], v[112:113], v[128:129]
	v_pk_add_f32 v[166:167], v[112:113], v[128:129] neg_lo:[0,1] neg_hi:[0,1]
	v_pk_add_f32 v[104:105], v[188:189], v[174:175]
	v_pk_add_f32 v[120:121], v[188:189], v[174:175] neg_lo:[0,1] neg_hi:[0,1]
	v_pk_add_f32 v[112:113], v[186:187], v[166:167] op_sel:[0,1] op_sel_hi:[1,0] neg_lo:[0,1]
	v_pk_add_f32 v[128:129], v[186:187], v[166:167] op_sel:[0,1] op_sel_hi:[1,0] neg_hi:[0,1]
	v_pk_add_f32 v[184:185], v[106:107], v[122:123]
	v_pk_add_f32 v[102:103], v[106:107], v[122:123] neg_lo:[0,1] neg_hi:[0,1]
	v_pk_add_f32 v[180:181], v[114:115], v[130:131]
	v_pk_add_f32 v[168:169], v[114:115], v[130:131] neg_lo:[0,1] neg_hi:[0,1]
	v_pk_add_f32 v[106:107], v[184:185], v[180:181]
	v_pk_add_f32 v[122:123], v[184:185], v[180:181] neg_lo:[0,1] neg_hi:[0,1]
	v_pk_add_f32 v[114:115], v[102:103], v[168:169] op_sel:[0,1] op_sel_hi:[1,0] neg_lo:[0,1]
	v_pk_add_f32 v[130:131], v[102:103], v[168:169] op_sel:[0,1] op_sel_hi:[1,0] neg_hi:[0,1]
	v_pk_mul_f32 v[176:177], v[118:119], s[68:69] op_sel:[1,1] op_sel_hi:[0,1]
	v_pk_fma_f32 v[118:119], v[118:119], s[68:69], v[176:177] op_sel_hi:[1,0,1] neg_hi:[0,0,1]
	v_pk_mul_f32 v[178:179], v[112:113], s[84:85] op_sel:[1,1] op_sel_hi:[0,1]
	v_pk_fma_f32 v[112:113], v[112:113], s[84:85], v[178:179] op_sel_hi:[1,0,1] neg_hi:[0,0,1]
	v_pk_mul_f32 v[188:189], v[114:115], s[88:89] op_sel:[1,1] op_sel_hi:[0,1]
	v_pk_fma_f32 v[114:115], v[114:115], s[88:89], v[188:189] op_sel_hi:[1,0,1] neg_hi:[0,0,1]
	v_pk_mul_f32 v[186:187], v[182:183], s[84:85] op_sel:[1,1] op_sel_hi:[0,1]
	v_pk_fma_f32 v[182:183], v[182:183], s[84:85], v[186:187] op_sel_hi:[1,0,1] neg_hi:[0,0,1]
	v_pk_mul_f32 v[174:175], v[122:123], s[90:91] op_sel:[1,1] op_sel_hi:[0,1]
	v_pk_fma_f32 v[122:123], v[122:123], s[90:91], v[174:175] op_sel_hi:[1,0,1] neg_hi:[0,0,1]
; __device__ __forceinline__ f32x2 cmulc(f32x2 a, f32x2 b) { return (f32x2){a.x * b.x + a.y * b.y, a.y * b.x - a.x * b.y}; }
; template <bool INV> __device__ __forceinline__ f32x2 cmul_tw(f32x2 a, f32x2 w) { return INV ? cmulc(a, w) : cmul(a, w); }
; template <bool INV> __device__ __forceinline__ void dft16(f32x2 (&x)[16]) {
;     constexpr float C1 = 0.92387953251128674f, S1 = 0.38268343236508977f, C2 = 0.70710678118654752f;
; #pragma unroll
;     for (int b = 0; b < 4; ++b) dft4<INV>(x[b], x[4 + b], x[8 + b], x[12 + b]);
;     const f32x2 w1 = {C1, -S1}, w2 = {C2, -C2}, w3 = {S1, -C1}, w4 = {0.f, -1.f}, w6 = {-C2, -C2}, w9 = {-C1, S1};
;     x[4 * 1 + 1] = cmul_tw<INV>(x[5], w1); x[4 * 1 + 2] = cmul_tw<INV>(x[6], w2); x[4 * 1 + 3] = cmul_tw<INV>(x[7], w3);
;     x[4 * 2 + 1] = cmul_tw<INV>(x[9], w2); x[4 * 2 + 2] = cmul_tw<INV>(x[10], w4); x[4 * 2 + 3] = cmul_tw<INV>(x[11], w6);
;     x[4 * 3 + 1] = cmul_tw<INV>(x[13], w3); x[4 * 3 + 2] = cmul_tw<INV>(x[14], w6); x[4 * 3 + 3] = cmul_tw<INV>(x[15], w9);
; #pragma unroll
;     for (int c = 0; c < 4; ++c) dft4<INV>(x[4 * c], x[4 * c + 1], x[4 * c + 2], x[4 * c + 3]);
;     f32x2 y[16];
; #pragma unroll
;     for (int k = 0; k < 16; ++k) y[k] = x[4 * (k & 3) + (k >> 2)];
; #pragma unroll
;     for (int k = 0; k < 16; ++k) x[k] = y[k];
; }
; template <int MODE> __device__ __forceinline__ void fft_pair32(LAS f32x2* B, const LAS f32x2* F, int wave, int lane) {
;     ...
;     dft16<true>(v);
; #pragma unroll
;     for (int j = 0; j < 16; ++j) { const f32x2 w = {hi ? CS[j] : 1.f, hi ? -SN[j] : 0.f}; const f32x2 u = j == 0 ? v[j] : cmulc(v[j], w);
;         const auto rx = __builtin_amdgcn_permlane32_swap(__float_as_uint(u.x), __float_as_uint(u.x), false, false);
;         const auto ry = __builtin_amdgcn_permlane32_swap(__float_as_uint(u.y), __float_as_uint(u.y), false, false);
;         const f32x2 a = {__uint_as_float(rx[0]), __uint_as_float(ry[0])}, b = {__uint_as_float(rx[1]), __uint_as_float(ry[1])};
;         p[16 * hi + j] = a + b * sg; }
; }
	v_pk_mul_f32 v[166:167], v[110:111], s[88:89] op_sel:[1,1] op_sel_hi:[0,1]
	v_pk_fma_f32 v[110:111], v[110:111], s[88:89], v[166:167] op_sel_hi:[1,0,1] neg_hi:[0,0,1]
	v_pk_mul_f32 v[184:185], v[128:129], s[90:91] op_sel:[1,1] op_sel_hi:[0,1]
	v_pk_fma_f32 v[128:129], v[128:129], s[90:91], v[184:185] op_sel_hi:[1,0,1] neg_hi:[0,0,1]
	v_pk_mul_f32 v[102:103], v[130:131], s[98:99] op_sel:[1,1] op_sel_hi:[0,1]
	v_pk_fma_f32 v[130:131], v[130:131], s[98:99], v[102:103] op_sel_hi:[1,0,1] neg_hi:[0,0,1]
	v_pk_add_f32 v[180:181], v[100:101], v[104:105]
	v_pk_add_f32 v[168:169], v[100:101], v[104:105] neg_lo:[0,1] neg_hi:[0,1]
	v_pk_add_f32 v[176:177], v[126:127], v[106:107]
	v_pk_add_f32 v[178:179], v[126:127], v[106:107] neg_lo:[0,1] neg_hi:[0,1]
	v_pk_add_f32 v[100:101], v[180:181], v[176:177]
	v_pk_add_f32 v[104:105], v[180:181], v[176:177] neg_lo:[0,1] neg_hi:[0,1]
	v_pk_add_f32 v[126:127], v[168:169], v[178:179] op_sel:[0,1] op_sel_hi:[1,0] neg_lo:[0,1]
	v_pk_add_f32 v[106:107], v[168:169], v[178:179] op_sel:[0,1] op_sel_hi:[1,0] neg_hi:[0,1]
	v_pk_add_f32 v[188:189], v[108:109], v[112:113]
	v_pk_add_f32 v[186:187], v[108:109], v[112:113] neg_lo:[0,1] neg_hi:[0,1]
	v_pk_add_f32 v[174:175], v[118:119], v[114:115]
	v_pk_add_f32 v[166:167], v[118:119], v[114:115] neg_lo:[0,1] neg_hi:[0,1]
	v_pk_add_f32 v[108:109], v[188:189], v[174:175]
	v_pk_add_f32 v[112:113], v[188:189], v[174:175] neg_lo:[0,1] neg_hi:[0,1]
	v_pk_add_f32 v[118:119], v[186:187], v[166:167] op_sel:[0,1] op_sel_hi:[1,0] neg_lo:[0,1]
	v_pk_add_f32 v[114:115], v[186:187], v[166:167] op_sel:[0,1] op_sel_hi:[1,0] neg_hi:[0,1]
	v_pk_add_f32 v[184:185], v[116:117], v[120:121] op_sel:[0,1] op_sel_hi:[1,0] neg_lo:[0,1]
	v_pk_add_f32 v[102:103], v[116:117], v[120:121] op_sel:[0,1] op_sel_hi:[1,0] neg_hi:[0,1]
	v_pk_add_f32 v[180:181], v[182:183], v[122:123]
	v_pk_add_f32 v[168:169], v[182:183], v[122:123] neg_lo:[0,1] neg_hi:[0,1]
	v_pk_add_f32 v[116:117], v[184:185], v[180:181]
	v_pk_add_f32 v[120:121], v[184:185], v[180:181] neg_lo:[0,1] neg_hi:[0,1]
	v_pk_add_f32 v[182:183], v[102:103], v[168:169] op_sel:[0,1] op_sel_hi:[1,0] neg_lo:[0,1]
	v_pk_add_f32 v[122:123], v[102:103], v[168:169] op_sel:[0,1] op_sel_hi:[1,0] neg_hi:[0,1]
	v_pk_add_f32 v[176:177], v[124:125], v[128:129]
	v_pk_add_f32 v[178:179], v[124:125], v[128:129] neg_lo:[0,1] neg_hi:[0,1]
	v_pk_add_f32 v[188:189], v[110:111], v[130:131]
	v_pk_add_f32 v[186:187], v[110:111], v[130:131] neg_lo:[0,1] neg_hi:[0,1]
	v_pk_add_f32 v[124:125], v[176:177], v[188:189]
	v_pk_add_f32 v[128:129], v[176:177], v[188:189] neg_lo:[0,1] neg_hi:[0,1]
	v_pk_add_f32 v[110:111], v[178:179], v[186:187] op_sel:[0,1] op_sel_hi:[1,0] neg_lo:[0,1]
	v_pk_add_f32 v[130:131], v[178:179], v[186:187] op_sel:[0,1] op_sel_hi:[1,0] neg_hi:[0,1]
	v_mov_b32_e32 v174, v100
	v_mov_b32_e32 v175, v101
	v_pk_mul_f32 v[180:181], v[108:109], v[36:37] op_sel:[1,1] op_sel_hi:[0,1]
	v_pk_fma_f32 v[166:167], v[108:109], v[36:37], v[180:181] op_sel_hi:[1,0,1] neg_hi:[0,0,1]
	v_pk_fma_f32 v[108:109], v[108:109], v[36:37], v[180:181] op_sel_hi:[1,0,1] neg_hi:[0,0,1]
	v_pk_mul_f32 v[168:169], v[116:117], v[38:39] op_sel:[1,1] op_sel_hi:[0,1]
	v_pk_fma_f32 v[184:185], v[116:117], v[38:39], v[168:169] op_sel_hi:[1,0,1] neg_hi:[0,0,1]
	v_pk_fma_f32 v[116:117], v[116:117], v[38:39], v[168:169] op_sel_hi:[1,0,1] neg_hi:[0,0,1]
	v_pk_mul_f32 v[176:177], v[124:125], v[40:41] op_sel:[1,1] op_sel_hi:[0,1]
	v_pk_fma_f32 v[102:103], v[124:125], v[40:41], v[176:177] op_sel_hi:[1,0,1] neg_hi:[0,0,1]
	v_pk_fma_f32 v[124:125], v[124:125], v[40:41], v[176:177] op_sel_hi:[1,0,1] neg_hi:[0,0,1]
	s_nop 1
	v_permlane32_swap_b32_e32 v100, v174
	v_permlane32_swap_b32_e32 v101, v175
	v_permlane32_swap_b32_e32 v108, v166
	v_permlane32_swap_b32_e32 v109, v167
	v_permlane32_swap_b32_e32 v116, v184
	v_permlane32_swap_b32_e32 v117, v185
	v_permlane32_swap_b32_e32 v124, v102
	v_permlane32_swap_b32_e32 v125, v103
	v_pk_fma_f32 v[100:101], v[174:175], v[190:191], v[100:101] op_sel_hi:[1,0,1]
	ds_write_b64 v198, v[100:101]
	v_pk_fma_f32 v[108:109], v[166:167], v[190:191], v[108:109] op_sel_hi:[1,0,1]
	ds_write_b64 v198, v[108:109] offset:8
	v_pk_fma_f32 v[116:117], v[184:185], v[190:191], v[116:117] op_sel_hi:[1,0,1]
	ds_write_b64 v198, v[116:117] offset:16
	v_pk_fma_f32 v[124:125], v[102:103], v[190:191], v[124:125] op_sel_hi:[1,0,1]
	ds_write_b64 v198, v[124:125] offset:24
	v_pk_mul_f32 v[168:169], v[126:127], v[42:43] op_sel:[1,1] op_sel_hi:[0,1]
	v_pk_fma_f32 v[178:179], v[126:127], v[42:43], v[168:169] op_sel_hi:[1,0,1] neg_hi:[0,0,1]
	v_pk_fma_f32 v[126:127], v[126:127], v[42:43], v[168:169] op_sel_hi:[1,0,1] neg_hi:[0,0,1]
	v_pk_mul_f32 v[176:177], v[118:119], v[44:45] op_sel:[1,1] op_sel_hi:[0,1]
	v_pk_fma_f32 v[188:189], v[118:119], v[44:45], v[176:177] op_sel_hi:[1,0,1] neg_hi:[0,0,1]
	v_pk_fma_f32 v[118:119], v[118:119], v[44:45], v[176:177] op_sel_hi:[1,0,1] neg_hi:[0,0,1]
	v_pk_mul_f32 v[174:175], v[182:183], v[46:47] op_sel:[1,1] op_sel_hi:[0,1]
	v_pk_fma_f32 v[186:187], v[182:183], v[46:47], v[174:175] op_sel_hi:[1,0,1] neg_hi:[0,0,1]
	v_pk_fma_f32 v[182:183], v[182:183], v[46:47], v[174:175] op_sel_hi:[1,0,1] neg_hi:[0,0,1]
	v_pk_mul_f32 v[166:167], v[110:111], v[48:49] op_sel:[1,1] op_sel_hi:[0,1]
	v_pk_fma_f32 v[180:181], v[110:111], v[48:49], v[166:167] op_sel_hi:[1,0,1] neg_hi:[0,0,1]
	v_pk_fma_f32 v[110:111], v[110:111], v[48:49], v[166:167] op_sel_hi:[1,0,1] neg_hi:[0,0,1]
	s_nop 1
	v_permlane32_swap_b32_e32 v126, v178
	v_permlane32_swap_b32_e32 v127, v179
	v_permlane32_swap_b32_e32 v118, v188
	v_permlane32_swap_b32_e32 v119, v189
	v_permlane32_swap_b32_e32 v182, v186
; #define LAS __attribute__((address_space(3)))
; __device__ __forceinline__ f32x2 cmulc(f32x2 a, f32x2 b) { return (f32x2){a.x * b.x + a.y * b.y, a.y * b.x - a.x * b.y}; }
; __device__ __forceinline__ void fft_inv2(LAS f32x2* B, const LAS f32x2* TW2, int tid) {
;     asm volatile("" : "+v"(tid));
;     const int b = tid >> 5, n2 = tid & 31, base = 512 * b + n2; f32x2 x[16];
;     x[0] = B[fpad(base)];
; #pragma unroll
;     for (int k = 1; k < 16; ++k) x[k] = cmulc(B[fpad(base + 32 * k)], TW2[k * 32 + n2]);
;     dft16<true>(x);
; #pragma unroll
;     for (int r = 0; r < 16; ++r) B[fpad(base + 32 * r)] = x[r];
; }
; template <int MODE> __device__ __forceinline__ void fft_pair32(LAS f32x2* B, const LAS f32x2* F, int wave, int lane) {
;     ...
; #pragma unroll
;     for (int j = 0; j < 16; ++j) { const f32x2 w = {hi ? CS[j] : 1.f, hi ? -SN[j] : 0.f}; const f32x2 u = j == 0 ? v[j] : cmulc(v[j], w);
;         const auto rx = __builtin_amdgcn_permlane32_swap(__float_as_uint(u.x), __float_as_uint(u.x), false, false);
;         const auto ry = __builtin_amdgcn_permlane32_swap(__float_as_uint(u.y), __float_as_uint(u.y), false, false);
;         const f32x2 a = {__uint_as_float(rx[0]), __uint_as_float(ry[0])}, b = {__uint_as_float(rx[1]), __uint_as_float(ry[1])};
;         p[16 * hi + j] = a + b * sg; }
; }
	v_permlane32_swap_b32_e32 v183, v187
	v_permlane32_swap_b32_e32 v110, v180
	v_permlane32_swap_b32_e32 v111, v181
	v_pk_fma_f32 v[126:127], v[178:179], v[190:191], v[126:127] op_sel_hi:[1,0,1]
	ds_write_b64 v198, v[126:127] offset:32
	v_pk_fma_f32 v[118:119], v[188:189], v[190:191], v[118:119] op_sel_hi:[1,0,1]
	ds_write_b64 v198, v[118:119] offset:40
	v_pk_fma_f32 v[182:183], v[186:187], v[190:191], v[182:183] op_sel_hi:[1,0,1]
	ds_write_b64 v198, v[182:183] offset:48
	v_pk_fma_f32 v[110:111], v[180:181], v[190:191], v[110:111] op_sel_hi:[1,0,1]
	ds_write_b64 v198, v[110:111] offset:56
	v_pk_mul_f32 v[174:175], v[104:105], v[50:51] op_sel:[1,1] op_sel_hi:[0,1]
	v_pk_fma_f32 v[184:185], v[104:105], v[50:51], v[174:175] op_sel_hi:[1,0,1] neg_hi:[0,0,1]
	v_pk_fma_f32 v[104:105], v[104:105], v[50:51], v[174:175] op_sel_hi:[1,0,1] neg_hi:[0,0,1]
	v_pk_mul_f32 v[166:167], v[112:113], v[52:53] op_sel:[1,1] op_sel_hi:[0,1]
	v_pk_fma_f32 v[102:103], v[112:113], v[52:53], v[166:167] op_sel_hi:[1,0,1] neg_hi:[0,0,1]
	v_pk_fma_f32 v[112:113], v[112:113], v[52:53], v[166:167] op_sel_hi:[1,0,1] neg_hi:[0,0,1]
	v_pk_mul_f32 v[178:179], v[120:121], v[54:55] op_sel:[1,1] op_sel_hi:[0,1]
	v_pk_fma_f32 v[168:169], v[120:121], v[54:55], v[178:179] op_sel_hi:[1,0,1] neg_hi:[0,0,1]
	v_pk_fma_f32 v[120:121], v[120:121], v[54:55], v[178:179] op_sel_hi:[1,0,1] neg_hi:[0,0,1]
	v_pk_mul_f32 v[188:189], v[128:129], v[90:91] op_sel:[1,1] op_sel_hi:[0,1]
	v_pk_fma_f32 v[176:177], v[128:129], v[90:91], v[188:189] op_sel_hi:[1,0,1] neg_hi:[0,0,1]
	v_pk_fma_f32 v[128:129], v[128:129], v[90:91], v[188:189] op_sel_hi:[1,0,1] neg_hi:[0,0,1]
	s_nop 1
	v_permlane32_swap_b32_e32 v104, v184
	v_permlane32_swap_b32_e32 v105, v185
	v_permlane32_swap_b32_e32 v112, v102
	v_permlane32_swap_b32_e32 v113, v103
	v_permlane32_swap_b32_e32 v120, v168
	v_permlane32_swap_b32_e32 v121, v169
	v_permlane32_swap_b32_e32 v128, v176
	v_permlane32_swap_b32_e32 v129, v177
	v_pk_fma_f32 v[104:105], v[184:185], v[190:191], v[104:105] op_sel_hi:[1,0,1]
	ds_write_b64 v198, v[104:105] offset:64
	v_pk_fma_f32 v[112:113], v[102:103], v[190:191], v[112:113] op_sel_hi:[1,0,1]
	ds_write_b64 v198, v[112:113] offset:72
	v_pk_fma_f32 v[120:121], v[168:169], v[190:191], v[120:121] op_sel_hi:[1,0,1]
	ds_write_b64 v198, v[120:121] offset:80
	v_pk_fma_f32 v[128:129], v[176:177], v[190:191], v[128:129] op_sel_hi:[1,0,1]
	ds_write_b64 v198, v[128:129] offset:88
	v_pk_mul_f32 v[178:179], v[106:107], v[92:93] op_sel:[1,1] op_sel_hi:[0,1]
	v_pk_fma_f32 v[186:187], v[106:107], v[92:93], v[178:179] op_sel_hi:[1,0,1] neg_hi:[0,0,1]
	v_pk_fma_f32 v[106:107], v[106:107], v[92:93], v[178:179] op_sel_hi:[1,0,1] neg_hi:[0,0,1]
	v_pk_mul_f32 v[188:189], v[114:115], v[94:95] op_sel:[1,1] op_sel_hi:[0,1]
	v_pk_fma_f32 v[180:181], v[114:115], v[94:95], v[188:189] op_sel_hi:[1,0,1] neg_hi:[0,0,1]
	v_pk_fma_f32 v[114:115], v[114:115], v[94:95], v[188:189] op_sel_hi:[1,0,1] neg_hi:[0,0,1]
	v_pk_mul_f32 v[184:185], v[122:123], v[96:97] op_sel:[1,1] op_sel_hi:[0,1]
	v_pk_fma_f32 v[174:175], v[122:123], v[96:97], v[184:185] op_sel_hi:[1,0,1] neg_hi:[0,0,1]
	v_pk_fma_f32 v[122:123], v[122:123], v[96:97], v[184:185] op_sel_hi:[1,0,1] neg_hi:[0,0,1]
	v_pk_mul_f32 v[102:103], v[130:131], v[98:99] op_sel:[1,1] op_sel_hi:[0,1]
	v_pk_fma_f32 v[166:167], v[130:131], v[98:99], v[102:103] op_sel_hi:[1,0,1] neg_hi:[0,0,1]
	v_pk_fma_f32 v[130:131], v[130:131], v[98:99], v[102:103] op_sel_hi:[1,0,1] neg_hi:[0,0,1]
	s_nop 1
	v_permlane32_swap_b32_e32 v106, v186
	v_permlane32_swap_b32_e32 v107, v187
	v_permlane32_swap_b32_e32 v114, v180
	v_permlane32_swap_b32_e32 v115, v181
	v_permlane32_swap_b32_e32 v122, v174
	v_permlane32_swap_b32_e32 v123, v175
	v_permlane32_swap_b32_e32 v130, v166
	v_permlane32_swap_b32_e32 v131, v167
	v_pk_fma_f32 v[106:107], v[186:187], v[190:191], v[106:107] op_sel_hi:[1,0,1]
	ds_write_b64 v198, v[106:107] offset:96
	v_pk_fma_f32 v[114:115], v[180:181], v[190:191], v[114:115] op_sel_hi:[1,0,1]
	ds_write_b64 v198, v[114:115] offset:104
	v_pk_fma_f32 v[122:123], v[174:175], v[190:191], v[122:123] op_sel_hi:[1,0,1]
	ds_write_b64 v198, v[122:123] offset:112
	v_pk_fma_f32 v[130:131], v[166:167], v[190:191], v[130:131] op_sel_hi:[1,0,1]
	ds_write_b64 v198, v[130:131] offset:120
	s_waitcnt lgkmcnt(0)
	ds_read_b64 v[100:101], v5
	ds_read_b64 v[108:109], v5 offset:264
	ds_read_b64 v[168:169], v56 offset:256
	ds_read_b64 v[116:117], v5 offset:528
	ds_read_b64 v[176:177], v56 offset:512
	ds_read_b64 v[124:125], v5 offset:792
	ds_read_b64 v[178:179], v56 offset:768
	ds_read_b64 v[126:127], v5 offset:1056
	ds_read_b64 v[188:189], v56 offset:1024
	ds_read_b64 v[118:119], v5 offset:1320
	ds_read_b64 v[184:185], v56 offset:1280
	s_waitcnt lgkmcnt(8)
	v_pk_mul_f32 v[102:103], v[108:109], v[168:169] op_sel:[1,1] op_sel_hi:[0,1]
	v_pk_fma_f32 v[108:109], v[108:109], v[168:169], v[102:103] op_sel_hi:[1,0,1] neg_hi:[0,0,1]
	s_waitcnt lgkmcnt(6)
	v_pk_mul_f32 v[186:187], v[116:117], v[176:177] op_sel:[1,1] op_sel_hi:[0,1]
	v_pk_fma_f32 v[116:117], v[116:117], v[176:177], v[186:187] op_sel_hi:[1,0,1] neg_hi:[0,0,1]
	s_waitcnt lgkmcnt(4)
	v_pk_mul_f32 v[180:181], v[124:125], v[178:179] op_sel:[1,1] op_sel_hi:[0,1]
	v_pk_fma_f32 v[124:125], v[124:125], v[178:179], v[180:181] op_sel_hi:[1,0,1] neg_hi:[0,0,1]
	s_waitcnt lgkmcnt(2)
	v_pk_mul_f32 v[174:175], v[126:127], v[188:189] op_sel:[1,1] op_sel_hi:[0,1]
	v_pk_fma_f32 v[126:127], v[126:127], v[188:189], v[174:175] op_sel_hi:[1,0,1] neg_hi:[0,0,1]
	s_waitcnt lgkmcnt(0)
; #define LAS __attribute__((address_space(3)))
; __device__ __forceinline__ f32x2 cmulc(f32x2 a, f32x2 b) { return (f32x2){a.x * b.x + a.y * b.y, a.y * b.x - a.x * b.y}; }
; template <bool INV> __device__ __forceinline__ f32x2 cmul_tw(f32x2 a, f32x2 w) { return INV ? cmulc(a, w) : cmul(a, w); }
; template <bool INV> __device__ __forceinline__ void dft16(f32x2 (&x)[16]) {
;     constexpr float C1 = 0.92387953251128674f, S1 = 0.38268343236508977f, C2 = 0.70710678118654752f;
; #pragma unroll
;     for (int b = 0; b < 4; ++b) dft4<INV>(x[b], x[4 + b], x[8 + b], x[12 + b]);
;     const f32x2 w1 = {C1, -S1}, w2 = {C2, -C2}, w3 = {S1, -C1}, w4 = {0.f, -1.f}, w6 = {-C2, -C2}, w9 = {-C1, S1};
;     x[4 * 1 + 1] = cmul_tw<INV>(x[5], w1); x[4 * 1 + 2] = cmul_tw<INV>(x[6], w2); x[4 * 1 + 3] = cmul_tw<INV>(x[7], w3);
;     x[4 * 2 + 1] = cmul_tw<INV>(x[9], w2); x[4 * 2 + 2] = cmul_tw<INV>(x[10], w4); x[4 * 2 + 3] = cmul_tw<INV>(x[11], w6);
;     x[4 * 3 + 1] = cmul_tw<INV>(x[13], w3); x[4 * 3 + 2] = cmul_tw<INV>(x[14], w6); x[4 * 3 + 3] = cmul_tw<INV>(x[15], w9);
; #pragma unroll
;     for (int c = 0; c < 4; ++c) dft4<INV>(x[4 * c], x[4 * c + 1], x[4 * c + 2], x[4 * c + 3]);
;     f32x2 y[16];
; #pragma unroll
;     for (int k = 0; k < 16; ++k) y[k] = x[4 * (k & 3) + (k >> 2)];
; #pragma unroll
;     for (int k = 0; k < 16; ++k) x[k] = y[k];
; }
; __device__ __forceinline__ void fft_inv2(LAS f32x2* B, const LAS f32x2* TW2, int tid) {
;     asm volatile("" : "+v"(tid));
;     const int b = tid >> 5, n2 = tid & 31, base = 512 * b + n2; f32x2 x[16];
;     x[0] = B[fpad(base)];
; #pragma unroll
;     for (int k = 1; k < 16; ++k) x[k] = cmulc(B[fpad(base + 32 * k)], TW2[k * 32 + n2]);
;     dft16<true>(x);
; #pragma unroll
;     for (int r = 0; r < 16; ++r) B[fpad(base + 32 * r)] = x[r];
; }
	v_pk_mul_f32 v[166:167], v[118:119], v[184:185] op_sel:[1,1] op_sel_hi:[0,1]
	v_pk_fma_f32 v[118:119], v[118:119], v[184:185], v[166:167] op_sel_hi:[1,0,1] neg_hi:[0,0,1]
	ds_read_b64 v[182:183], v5 offset:1584
	ds_read_b64 v[102:103], v56 offset:1536
	ds_read_b64 v[110:111], v5 offset:1848
	ds_read_b64 v[186:187], v56 offset:1792
	ds_read_b64 v[104:105], v5 offset:2112
	ds_read_b64 v[180:181], v56 offset:2048
	ds_read_b64 v[112:113], v5 offset:2376
	ds_read_b64 v[174:175], v56 offset:2304
	ds_read_b64 v[120:121], v5 offset:2640
	ds_read_b64 v[166:167], v56 offset:2560
	s_waitcnt lgkmcnt(8)
	v_pk_mul_f32 v[168:169], v[182:183], v[102:103] op_sel:[1,1] op_sel_hi:[0,1]
	v_pk_fma_f32 v[182:183], v[182:183], v[102:103], v[168:169] op_sel_hi:[1,0,1] neg_hi:[0,0,1]
	s_waitcnt lgkmcnt(6)
	v_pk_mul_f32 v[176:177], v[110:111], v[186:187] op_sel:[1,1] op_sel_hi:[0,1]
	v_pk_fma_f32 v[110:111], v[110:111], v[186:187], v[176:177] op_sel_hi:[1,0,1] neg_hi:[0,0,1]
	s_waitcnt lgkmcnt(4)
	v_pk_mul_f32 v[178:179], v[104:105], v[180:181] op_sel:[1,1] op_sel_hi:[0,1]
	v_pk_fma_f32 v[104:105], v[104:105], v[180:181], v[178:179] op_sel_hi:[1,0,1] neg_hi:[0,0,1]
	s_waitcnt lgkmcnt(2)
	v_pk_mul_f32 v[188:189], v[112:113], v[174:175] op_sel:[1,1] op_sel_hi:[0,1]
	v_pk_fma_f32 v[112:113], v[112:113], v[174:175], v[188:189] op_sel_hi:[1,0,1] neg_hi:[0,0,1]
	s_waitcnt lgkmcnt(0)
	v_pk_mul_f32 v[184:185], v[120:121], v[166:167] op_sel:[1,1] op_sel_hi:[0,1]
	v_pk_fma_f32 v[120:121], v[120:121], v[166:167], v[184:185] op_sel_hi:[1,0,1] neg_hi:[0,0,1]
	ds_read_b64 v[128:129], v5 offset:2904
	ds_read_b64 v[168:169], v56 offset:2816
	ds_read_b64 v[106:107], v5 offset:3168
	ds_read_b64 v[176:177], v56 offset:3072
	ds_read_b64 v[114:115], v5 offset:3432
	ds_read_b64 v[178:179], v56 offset:3328
	ds_read_b64 v[122:123], v5 offset:3696
	ds_read_b64 v[188:189], v56 offset:3584
	ds_read_b64 v[130:131], v5 offset:3960
	ds_read_b64 v[184:185], v56 offset:3840
	s_waitcnt lgkmcnt(8)
	v_pk_mul_f32 v[102:103], v[128:129], v[168:169] op_sel:[1,1] op_sel_hi:[0,1]
	v_pk_fma_f32 v[128:129], v[128:129], v[168:169], v[102:103] op_sel_hi:[1,0,1] neg_hi:[0,0,1]
	s_waitcnt lgkmcnt(6)
	v_pk_mul_f32 v[186:187], v[106:107], v[176:177] op_sel:[1,1] op_sel_hi:[0,1]
	v_pk_fma_f32 v[106:107], v[106:107], v[176:177], v[186:187] op_sel_hi:[1,0,1] neg_hi:[0,0,1]
	s_waitcnt lgkmcnt(4)
	v_pk_mul_f32 v[180:181], v[114:115], v[178:179] op_sel:[1,1] op_sel_hi:[0,1]
	v_pk_fma_f32 v[114:115], v[114:115], v[178:179], v[180:181] op_sel_hi:[1,0,1] neg_hi:[0,0,1]
	s_waitcnt lgkmcnt(2)
	v_pk_mul_f32 v[174:175], v[122:123], v[188:189] op_sel:[1,1] op_sel_hi:[0,1]
	v_pk_fma_f32 v[122:123], v[122:123], v[188:189], v[174:175] op_sel_hi:[1,0,1] neg_hi:[0,0,1]
	s_waitcnt lgkmcnt(0)
	v_pk_mul_f32 v[166:167], v[130:131], v[184:185] op_sel:[1,1] op_sel_hi:[0,1]
	v_pk_fma_f32 v[130:131], v[130:131], v[184:185], v[166:167] op_sel_hi:[1,0,1] neg_hi:[0,0,1]
	v_pk_add_f32 v[102:103], v[100:101], v[104:105]
	v_pk_add_f32 v[186:187], v[100:101], v[104:105] neg_lo:[0,1] neg_hi:[0,1]
	v_pk_add_f32 v[180:181], v[126:127], v[106:107]
	v_pk_add_f32 v[174:175], v[126:127], v[106:107] neg_lo:[0,1] neg_hi:[0,1]
	v_pk_add_f32 v[100:101], v[102:103], v[180:181]
	v_pk_add_f32 v[104:105], v[102:103], v[180:181] neg_lo:[0,1] neg_hi:[0,1]
	v_pk_add_f32 v[126:127], v[186:187], v[174:175] op_sel:[0,1] op_sel_hi:[1,0] neg_lo:[0,1]
	v_pk_add_f32 v[106:107], v[186:187], v[174:175] op_sel:[0,1] op_sel_hi:[1,0] neg_hi:[0,1]
	v_pk_add_f32 v[166:167], v[108:109], v[112:113]
	v_pk_add_f32 v[168:169], v[108:109], v[112:113] neg_lo:[0,1] neg_hi:[0,1]
	v_pk_add_f32 v[176:177], v[118:119], v[114:115]
	v_pk_add_f32 v[178:179], v[118:119], v[114:115] neg_lo:[0,1] neg_hi:[0,1]
	v_pk_add_f32 v[108:109], v[166:167], v[176:177]
	v_pk_add_f32 v[112:113], v[166:167], v[176:177] neg_lo:[0,1] neg_hi:[0,1]
	v_pk_add_f32 v[118:119], v[168:169], v[178:179] op_sel:[0,1] op_sel_hi:[1,0] neg_lo:[0,1]
	v_pk_add_f32 v[114:115], v[168:169], v[178:179] op_sel:[0,1] op_sel_hi:[1,0] neg_hi:[0,1]
	v_pk_add_f32 v[188:189], v[116:117], v[120:121]
	v_pk_add_f32 v[184:185], v[116:117], v[120:121] neg_lo:[0,1] neg_hi:[0,1]
	v_pk_add_f32 v[102:103], v[182:183], v[122:123]
	v_pk_add_f32 v[186:187], v[182:183], v[122:123] neg_lo:[0,1] neg_hi:[0,1]
	v_pk_add_f32 v[116:117], v[188:189], v[102:103]
	v_pk_add_f32 v[120:121], v[188:189], v[102:103] neg_lo:[0,1] neg_hi:[0,1]
	v_pk_add_f32 v[182:183], v[184:185], v[186:187] op_sel:[0,1] op_sel_hi:[1,0] neg_lo:[0,1]
	v_pk_add_f32 v[122:123], v[184:185], v[186:187] op_sel:[0,1] op_sel_hi:[1,0] neg_hi:[0,1]
	v_pk_add_f32 v[180:181], v[124:125], v[128:129]
	v_pk_add_f32 v[174:175], v[124:125], v[128:129] neg_lo:[0,1] neg_hi:[0,1]
	v_pk_add_f32 v[166:167], v[110:111], v[130:131]
	v_pk_add_f32 v[168:169], v[110:111], v[130:131] neg_lo:[0,1] neg_hi:[0,1]
	v_pk_add_f32 v[124:125], v[180:181], v[166:167]
	v_pk_add_f32 v[128:129], v[180:181], v[166:167] neg_lo:[0,1] neg_hi:[0,1]
	v_pk_add_f32 v[110:111], v[174:175], v[168:169] op_sel:[0,1] op_sel_hi:[1,0] neg_lo:[0,1]
	v_pk_add_f32 v[130:131], v[174:175], v[168:169] op_sel:[0,1] op_sel_hi:[1,0] neg_hi:[0,1]
	v_pk_mul_f32 v[176:177], v[118:119], s[68:69] op_sel:[1,1] op_sel_hi:[0,1]
	v_pk_fma_f32 v[118:119], v[118:119], s[68:69], v[176:177] op_sel_hi:[1,0,1] neg_hi:[0,0,1]
	v_pk_mul_f32 v[178:179], v[182:183], s[84:85] op_sel:[1,1] op_sel_hi:[0,1]
	v_pk_fma_f32 v[182:183], v[182:183], s[84:85], v[178:179] op_sel_hi:[1,0,1] neg_hi:[0,0,1]
	v_pk_mul_f32 v[188:189], v[110:111], s[88:89] op_sel:[1,1] op_sel_hi:[0,1]
	v_pk_fma_f32 v[110:111], v[110:111], s[88:89], v[188:189] op_sel_hi:[1,0,1] neg_hi:[0,0,1]
; #define LAS __attribute__((address_space(3)))
; __device__ __forceinline__ f32x2 cmulc(f32x2 a, f32x2 b) { return (f32x2){a.x * b.x + a.y * b.y, a.y * b.x - a.x * b.y}; }
; __device__ __forceinline__ void fft_inv2(LAS f32x2* B, const LAS f32x2* TW2, int tid) {
;     asm volatile("" : "+v"(tid));
;     const int b = tid >> 5, n2 = tid & 31, base = 512 * b + n2; f32x2 x[16];
;     x[0] = B[fpad(base)];
; #pragma unroll
;     for (int k = 1; k < 16; ++k) x[k] = cmulc(B[fpad(base + 32 * k)], TW2[k * 32 + n2]);
;     dft16<true>(x);
; #pragma unroll
;     for (int r = 0; r < 16; ++r) B[fpad(base + 32 * r)] = x[r];
; }
; __device__ __forceinline__ void fft_inv1(f32x2 (&x)[16], const LAS f32x2* B, int n2, const f32x2 (&w)[16]) {
;     asm volatile("" : "+v"(n2));
;     x[0] = B[fpad(n2)];
; #pragma unroll
;     for (int k = 1; k < 16; ++k) x[k] = cmulc(B[fpad(512 * k + n2)], w[k]);
;     dft16_inv_lo(x);
; }
	v_pk_mul_f32 v[184:185], v[112:113], s[84:85] op_sel:[1,1] op_sel_hi:[0,1]
	v_pk_fma_f32 v[112:113], v[112:113], s[84:85], v[184:185] op_sel_hi:[1,0,1] neg_hi:[0,0,1]
	v_pk_mul_f32 v[102:103], v[128:129], s[90:91] op_sel:[1,1] op_sel_hi:[0,1]
	v_pk_fma_f32 v[128:129], v[128:129], s[90:91], v[102:103] op_sel_hi:[1,0,1] neg_hi:[0,0,1]
	v_pk_mul_f32 v[186:187], v[114:115], s[88:89] op_sel:[1,1] op_sel_hi:[0,1]
	v_pk_fma_f32 v[114:115], v[114:115], s[88:89], v[186:187] op_sel_hi:[1,0,1] neg_hi:[0,0,1]
	v_pk_mul_f32 v[180:181], v[122:123], s[90:91] op_sel:[1,1] op_sel_hi:[0,1]
	v_pk_fma_f32 v[122:123], v[122:123], s[90:91], v[180:181] op_sel_hi:[1,0,1] neg_hi:[0,0,1]
	v_pk_mul_f32 v[174:175], v[130:131], s[98:99] op_sel:[1,1] op_sel_hi:[0,1]
	v_pk_fma_f32 v[130:131], v[130:131], s[98:99], v[174:175] op_sel_hi:[1,0,1] neg_hi:[0,0,1]
	v_pk_add_f32 v[166:167], v[100:101], v[116:117]
	v_pk_add_f32 v[168:169], v[100:101], v[116:117] neg_lo:[0,1] neg_hi:[0,1]
	v_pk_add_f32 v[176:177], v[108:109], v[124:125]
	v_pk_add_f32 v[178:179], v[108:109], v[124:125] neg_lo:[0,1] neg_hi:[0,1]
	v_pk_add_f32 v[100:101], v[166:167], v[176:177]
	v_pk_add_f32 v[116:117], v[166:167], v[176:177] neg_lo:[0,1] neg_hi:[0,1]
	v_pk_add_f32 v[108:109], v[168:169], v[178:179] op_sel:[0,1] op_sel_hi:[1,0] neg_lo:[0,1]
	v_pk_add_f32 v[124:125], v[168:169], v[178:179] op_sel:[0,1] op_sel_hi:[1,0] neg_hi:[0,1]
	v_pk_add_f32 v[188:189], v[126:127], v[182:183]
	v_pk_add_f32 v[184:185], v[126:127], v[182:183] neg_lo:[0,1] neg_hi:[0,1]
	v_pk_add_f32 v[102:103], v[118:119], v[110:111]
	v_pk_add_f32 v[186:187], v[118:119], v[110:111] neg_lo:[0,1] neg_hi:[0,1]
	v_pk_add_f32 v[126:127], v[188:189], v[102:103]
	v_pk_add_f32 v[182:183], v[188:189], v[102:103] neg_lo:[0,1] neg_hi:[0,1]
	v_pk_add_f32 v[118:119], v[184:185], v[186:187] op_sel:[0,1] op_sel_hi:[1,0] neg_lo:[0,1]
	v_pk_add_f32 v[110:111], v[184:185], v[186:187] op_sel:[0,1] op_sel_hi:[1,0] neg_hi:[0,1]
	v_pk_add_f32 v[180:181], v[104:105], v[120:121] op_sel:[0,1] op_sel_hi:[1,0] neg_lo:[0,1]
	v_pk_add_f32 v[174:175], v[104:105], v[120:121] op_sel:[0,1] op_sel_hi:[1,0] neg_hi:[0,1]
	v_pk_add_f32 v[166:167], v[112:113], v[128:129]
	v_pk_add_f32 v[168:169], v[112:113], v[128:129] neg_lo:[0,1] neg_hi:[0,1]
	v_pk_add_f32 v[104:105], v[180:181], v[166:167]
	v_pk_add_f32 v[120:121], v[180:181], v[166:167] neg_lo:[0,1] neg_hi:[0,1]
	v_pk_add_f32 v[112:113], v[174:175], v[168:169] op_sel:[0,1] op_sel_hi:[1,0] neg_lo:[0,1]
	v_pk_add_f32 v[128:129], v[174:175], v[168:169] op_sel:[0,1] op_sel_hi:[1,0] neg_hi:[0,1]
	v_pk_add_f32 v[176:177], v[106:107], v[122:123]
	v_pk_add_f32 v[178:179], v[106:107], v[122:123] neg_lo:[0,1] neg_hi:[0,1]
	v_pk_add_f32 v[188:189], v[114:115], v[130:131]
	v_pk_add_f32 v[184:185], v[114:115], v[130:131] neg_lo:[0,1] neg_hi:[0,1]
	v_pk_add_f32 v[106:107], v[176:177], v[188:189]
	v_pk_add_f32 v[122:123], v[176:177], v[188:189] neg_lo:[0,1] neg_hi:[0,1]
	v_pk_add_f32 v[114:115], v[178:179], v[184:185] op_sel:[0,1] op_sel_hi:[1,0] neg_lo:[0,1]
	v_pk_add_f32 v[130:131], v[178:179], v[184:185] op_sel:[0,1] op_sel_hi:[1,0] neg_hi:[0,1]
	ds_write_b64 v5, v[100:101]
	ds_write_b64 v5, v[126:127] offset:264
	ds_write_b64 v5, v[104:105] offset:528
	ds_write_b64 v5, v[106:107] offset:792
	ds_write_b64 v5, v[108:109] offset:1056
	ds_write_b64 v5, v[118:119] offset:1320
	ds_write_b64 v5, v[112:113] offset:1584
	ds_write_b64 v5, v[114:115] offset:1848
	ds_write_b64 v5, v[116:117] offset:2112
	ds_write_b64 v5, v[182:183] offset:2376
	ds_write_b64 v5, v[120:121] offset:2640
	ds_write_b64 v5, v[122:123] offset:2904
	ds_write_b64 v5, v[124:125] offset:3168
	ds_write_b64 v5, v[110:111] offset:3432
	ds_write_b64 v5, v[128:129] offset:3696
	ds_write_b64 v5, v[130:131] offset:3960
	s_waitcnt lgkmcnt(0)
	s_barrier
	ds_read_b64 v[100:101], v3
	ds_read_b64 v[126:127], v3 offset:4224
	ds_read_b64 v[104:105], v3 offset:8448
	ds_read_b64 v[106:107], v3 offset:12672
	ds_read_b64 v[108:109], v3 offset:16896
	ds_read_b64 v[118:119], v3 offset:21120
	ds_read_b64 v[112:113], v3 offset:25344
	ds_read_b64 v[114:115], v3 offset:29568
	ds_read_b64 v[116:117], v3 offset:33792
	ds_read_b64 v[182:183], v3 offset:38016
	ds_read_b64 v[120:121], v3 offset:42240
	ds_read_b64 v[122:123], v3 offset:46464
	ds_read_b64 v[124:125], v3 offset:50688
	ds_read_b64 v[110:111], v3 offset:54912
	ds_read_b64 v[128:129], v3 offset:59136
	ds_read_b64 v[130:131], v3 offset:63360
	s_waitcnt lgkmcnt(14)
	v_pk_mul_f32 v[102:103], v[126:127], v[6:7] op_sel:[1,1] op_sel_hi:[0,1]
	v_pk_fma_f32 v[126:127], v[126:127], v[6:7], v[102:103] op_sel_hi:[1,0,1] neg_hi:[0,0,1]
	s_waitcnt lgkmcnt(13)
	v_pk_mul_f32 v[186:187], v[104:105], v[8:9] op_sel:[1,1] op_sel_hi:[0,1]
	v_pk_fma_f32 v[104:105], v[104:105], v[8:9], v[186:187] op_sel_hi:[1,0,1] neg_hi:[0,0,1]
	s_waitcnt lgkmcnt(12)
	v_pk_mul_f32 v[180:181], v[106:107], v[10:11] op_sel:[1,1] op_sel_hi:[0,1]
	v_pk_fma_f32 v[106:107], v[106:107], v[10:11], v[180:181] op_sel_hi:[1,0,1] neg_hi:[0,0,1]
	s_waitcnt lgkmcnt(11)
	v_pk_mul_f32 v[174:175], v[108:109], v[12:13] op_sel:[1,1] op_sel_hi:[0,1]
	v_pk_fma_f32 v[108:109], v[108:109], v[12:13], v[174:175] op_sel_hi:[1,0,1] neg_hi:[0,0,1]
	s_waitcnt lgkmcnt(10)
	v_pk_mul_f32 v[166:167], v[118:119], v[14:15] op_sel:[1,1] op_sel_hi:[0,1]
	v_pk_fma_f32 v[118:119], v[118:119], v[14:15], v[166:167] op_sel_hi:[1,0,1] neg_hi:[0,0,1]
	s_waitcnt lgkmcnt(9)
	v_pk_mul_f32 v[168:169], v[112:113], v[16:17] op_sel:[1,1] op_sel_hi:[0,1]
	v_pk_fma_f32 v[112:113], v[112:113], v[16:17], v[168:169] op_sel_hi:[1,0,1] neg_hi:[0,0,1]
	s_waitcnt lgkmcnt(8)
; #define LAS __attribute__((address_space(3)))
; __device__ __forceinline__ f32x2 cmulc(f32x2 a, f32x2 b) { return (f32x2){a.x * b.x + a.y * b.y, a.y * b.x - a.x * b.y}; }
; __device__ __forceinline__ void dft16_inv_lo(f32x2 (&x)[16]) {
;     constexpr float C1 = 0.92387953251128674f, S1 = 0.38268343236508977f, C2 = 0.70710678118654752f;
; #pragma unroll
;     for (int b = 0; b < 4; ++b) dft4<true>(x[b], x[4 + b], x[8 + b], x[12 + b]);
;     const f32x2 w1 = {C1, -S1}, w2 = {C2, -C2}, w3 = {S1, -C1}, w4 = {0.f, -1.f}, w6 = {-C2, -C2}, w9 = {-C1, S1};
;     x[5] = cmulc(x[5], w1); x[6] = cmulc(x[6], w2); x[7] = cmulc(x[7], w3);
;     x[9] = cmulc(x[9], w2); x[10] = cmulc(x[10], w4); x[11] = cmulc(x[11], w6);
;     x[13] = cmulc(x[13], w3); x[14] = cmulc(x[14], w6); x[15] = cmulc(x[15], w9);
;     f32x2 y[8];
; #pragma unroll
;     for (int c = 0; c < 4; ++c) { const f32x2 t0 = x[4 * c] + x[4 * c + 2], t1 = x[4 * c] - x[4 * c + 2], t2 = x[4 * c + 1] + x[4 * c + 3], t3 = x[4 * c + 1] - x[4 * c + 3];
;         y[c] = t0 + t2; y[4 + c] = t1 + (f32x2){-t3.y, t3.x}; }
; #pragma unroll
;     for (int k = 0; k < 8; ++k) x[k] = y[k];
; }
; __device__ __forceinline__ void fft_inv1(f32x2 (&x)[16], const LAS f32x2* B, int n2, const f32x2 (&w)[16]) {
;     asm volatile("" : "+v"(n2));
;     x[0] = B[fpad(n2)];
; #pragma unroll
;     for (int k = 1; k < 16; ++k) x[k] = cmulc(B[fpad(512 * k + n2)], w[k]);
;     dft16_inv_lo(x);
; }
	v_pk_mul_f32 v[176:177], v[114:115], v[18:19] op_sel:[1,1] op_sel_hi:[0,1]
	v_pk_fma_f32 v[114:115], v[114:115], v[18:19], v[176:177] op_sel_hi:[1,0,1] neg_hi:[0,0,1]
	s_waitcnt lgkmcnt(7)
	v_pk_mul_f32 v[178:179], v[116:117], v[20:21] op_sel:[1,1] op_sel_hi:[0,1]
	v_pk_fma_f32 v[116:117], v[116:117], v[20:21], v[178:179] op_sel_hi:[1,0,1] neg_hi:[0,0,1]
	s_waitcnt lgkmcnt(6)
	v_pk_mul_f32 v[188:189], v[182:183], v[22:23] op_sel:[1,1] op_sel_hi:[0,1]
	v_pk_fma_f32 v[182:183], v[182:183], v[22:23], v[188:189] op_sel_hi:[1,0,1] neg_hi:[0,0,1]
	s_waitcnt lgkmcnt(5)
	v_pk_mul_f32 v[184:185], v[120:121], v[24:25] op_sel:[1,1] op_sel_hi:[0,1]
	v_pk_fma_f32 v[120:121], v[120:121], v[24:25], v[184:185] op_sel_hi:[1,0,1] neg_hi:[0,0,1]
	s_waitcnt lgkmcnt(4)
	v_pk_mul_f32 v[102:103], v[122:123], v[26:27] op_sel:[1,1] op_sel_hi:[0,1]
	v_pk_fma_f32 v[122:123], v[122:123], v[26:27], v[102:103] op_sel_hi:[1,0,1] neg_hi:[0,0,1]
	s_waitcnt lgkmcnt(3)
	v_pk_mul_f32 v[186:187], v[124:125], v[28:29] op_sel:[1,1] op_sel_hi:[0,1]
	v_pk_fma_f32 v[124:125], v[124:125], v[28:29], v[186:187] op_sel_hi:[1,0,1] neg_hi:[0,0,1]
	s_waitcnt lgkmcnt(2)
	v_pk_mul_f32 v[180:181], v[110:111], v[30:31] op_sel:[1,1] op_sel_hi:[0,1]
	v_pk_fma_f32 v[110:111], v[110:111], v[30:31], v[180:181] op_sel_hi:[1,0,1] neg_hi:[0,0,1]
	s_waitcnt lgkmcnt(1)
	v_pk_mul_f32 v[174:175], v[128:129], v[32:33] op_sel:[1,1] op_sel_hi:[0,1]
	v_pk_fma_f32 v[128:129], v[128:129], v[32:33], v[174:175] op_sel_hi:[1,0,1] neg_hi:[0,0,1]
	s_waitcnt lgkmcnt(0)
	v_pk_mul_f32 v[166:167], v[130:131], v[34:35] op_sel:[1,1] op_sel_hi:[0,1]
	v_pk_fma_f32 v[130:131], v[130:131], v[34:35], v[166:167] op_sel_hi:[1,0,1] neg_hi:[0,0,1]
	v_pk_add_f32 v[168:169], v[100:101], v[116:117]
	v_pk_add_f32 v[176:177], v[100:101], v[116:117] neg_lo:[0,1] neg_hi:[0,1]
	v_pk_add_f32 v[178:179], v[108:109], v[124:125]
	v_pk_add_f32 v[188:189], v[108:109], v[124:125] neg_lo:[0,1] neg_hi:[0,1]
	v_pk_add_f32 v[100:101], v[168:169], v[178:179]
	v_pk_add_f32 v[116:117], v[168:169], v[178:179] neg_lo:[0,1] neg_hi:[0,1]
	v_pk_add_f32 v[108:109], v[176:177], v[188:189] op_sel:[0,1] op_sel_hi:[1,0] neg_lo:[0,1]
	v_pk_add_f32 v[124:125], v[176:177], v[188:189] op_sel:[0,1] op_sel_hi:[1,0] neg_hi:[0,1]
	v_pk_add_f32 v[184:185], v[126:127], v[182:183]
	v_pk_add_f32 v[102:103], v[126:127], v[182:183] neg_lo:[0,1] neg_hi:[0,1]
	v_pk_add_f32 v[186:187], v[118:119], v[110:111]
	v_pk_add_f32 v[180:181], v[118:119], v[110:111] neg_lo:[0,1] neg_hi:[0,1]
	v_pk_add_f32 v[126:127], v[184:185], v[186:187]
	v_pk_add_f32 v[182:183], v[184:185], v[186:187] neg_lo:[0,1] neg_hi:[0,1]
	v_pk_add_f32 v[118:119], v[102:103], v[180:181] op_sel:[0,1] op_sel_hi:[1,0] neg_lo:[0,1]
	v_pk_add_f32 v[110:111], v[102:103], v[180:181] op_sel:[0,1] op_sel_hi:[1,0] neg_hi:[0,1]
	v_pk_add_f32 v[174:175], v[104:105], v[120:121]
	v_pk_add_f32 v[166:167], v[104:105], v[120:121] neg_lo:[0,1] neg_hi:[0,1]
	v_pk_add_f32 v[168:169], v[112:113], v[128:129]
	v_pk_add_f32 v[176:177], v[112:113], v[128:129] neg_lo:[0,1] neg_hi:[0,1]
	v_pk_add_f32 v[104:105], v[174:175], v[168:169]
	v_pk_add_f32 v[120:121], v[174:175], v[168:169] neg_lo:[0,1] neg_hi:[0,1]
	v_pk_add_f32 v[112:113], v[166:167], v[176:177] op_sel:[0,1] op_sel_hi:[1,0] neg_lo:[0,1]
	v_pk_add_f32 v[128:129], v[166:167], v[176:177] op_sel:[0,1] op_sel_hi:[1,0] neg_hi:[0,1]
	v_pk_add_f32 v[178:179], v[106:107], v[122:123]
	v_pk_add_f32 v[188:189], v[106:107], v[122:123] neg_lo:[0,1] neg_hi:[0,1]
	v_pk_add_f32 v[184:185], v[114:115], v[130:131]
	v_pk_add_f32 v[102:103], v[114:115], v[130:131] neg_lo:[0,1] neg_hi:[0,1]
	v_pk_add_f32 v[106:107], v[178:179], v[184:185]
	v_pk_add_f32 v[122:123], v[178:179], v[184:185] neg_lo:[0,1] neg_hi:[0,1]
	v_pk_add_f32 v[114:115], v[188:189], v[102:103] op_sel:[0,1] op_sel_hi:[1,0] neg_lo:[0,1]
	v_pk_add_f32 v[130:131], v[188:189], v[102:103] op_sel:[0,1] op_sel_hi:[1,0] neg_hi:[0,1]
	v_pk_mul_f32 v[186:187], v[118:119], s[68:69] op_sel:[1,1] op_sel_hi:[0,1]
	v_pk_fma_f32 v[118:119], v[118:119], s[68:69], v[186:187] op_sel_hi:[1,0,1] neg_hi:[0,0,1]
	v_pk_mul_f32 v[180:181], v[112:113], s[84:85] op_sel:[1,1] op_sel_hi:[0,1]
	v_pk_fma_f32 v[112:113], v[112:113], s[84:85], v[180:181] op_sel_hi:[1,0,1] neg_hi:[0,0,1]
	v_pk_mul_f32 v[174:175], v[114:115], s[88:89] op_sel:[1,1] op_sel_hi:[0,1]
	v_pk_fma_f32 v[114:115], v[114:115], s[88:89], v[174:175] op_sel_hi:[1,0,1] neg_hi:[0,0,1]
	v_pk_mul_f32 v[166:167], v[182:183], s[84:85] op_sel:[1,1] op_sel_hi:[0,1]
	v_pk_fma_f32 v[182:183], v[182:183], s[84:85], v[166:167] op_sel_hi:[1,0,1] neg_hi:[0,0,1]
	v_pk_mul_f32 v[168:169], v[122:123], s[90:91] op_sel:[1,1] op_sel_hi:[0,1]
	v_pk_fma_f32 v[122:123], v[122:123], s[90:91], v[168:169] op_sel_hi:[1,0,1] neg_hi:[0,0,1]
	v_pk_mul_f32 v[176:177], v[110:111], s[88:89] op_sel:[1,1] op_sel_hi:[0,1]
	v_pk_fma_f32 v[110:111], v[110:111], s[88:89], v[176:177] op_sel_hi:[1,0,1] neg_hi:[0,0,1]
	v_pk_mul_f32 v[178:179], v[128:129], s[90:91] op_sel:[1,1] op_sel_hi:[0,1]
	v_pk_fma_f32 v[128:129], v[128:129], s[90:91], v[178:179] op_sel_hi:[1,0,1] neg_hi:[0,0,1]
	v_pk_mul_f32 v[188:189], v[130:131], s[98:99] op_sel:[1,1] op_sel_hi:[0,1]
	v_pk_fma_f32 v[130:131], v[130:131], s[98:99], v[188:189] op_sel_hi:[1,0,1] neg_hi:[0,0,1]
	v_pk_add_f32 v[184:185], v[100:101], v[104:105]
	v_pk_add_f32 v[102:103], v[100:101], v[104:105] neg_lo:[0,1] neg_hi:[0,1]
	v_pk_add_f32 v[186:187], v[126:127], v[106:107]
	v_pk_add_f32 v[180:181], v[126:127], v[106:107] neg_lo:[0,1] neg_hi:[0,1]
	v_pk_add_f32 v[100:101], v[184:185], v[186:187]
	v_pk_add_f32 v[126:127], v[102:103], v[180:181] op_sel:[0,1] op_sel_hi:[1,0] neg_lo:[0,1]
	v_pk_add_f32 v[174:175], v[108:109], v[112:113]
	v_pk_add_f32 v[166:167], v[108:109], v[112:113] neg_lo:[0,1] neg_hi:[0,1]
	v_pk_add_f32 v[168:169], v[118:119], v[114:115]
	v_pk_add_f32 v[176:177], v[118:119], v[114:115] neg_lo:[0,1] neg_hi:[0,1]
	v_pk_add_f32 v[108:109], v[174:175], v[168:169]
	v_pk_add_f32 v[118:119], v[166:167], v[176:177] op_sel:[0,1] op_sel_hi:[1,0] neg_lo:[0,1]
	v_pk_add_f32 v[178:179], v[116:117], v[120:121] op_sel:[0,1] op_sel_hi:[1,0] neg_lo:[0,1]
	v_pk_add_f32 v[188:189], v[116:117], v[120:121] op_sel:[0,1] op_sel_hi:[1,0] neg_hi:[0,1]
	v_pk_add_f32 v[184:185], v[182:183], v[122:123]
	v_pk_add_f32 v[102:103], v[182:183], v[122:123] neg_lo:[0,1] neg_hi:[0,1]
	v_pk_add_f32 v[116:117], v[178:179], v[184:185]
	v_pk_add_f32 v[182:183], v[188:189], v[102:103] op_sel:[0,1] op_sel_hi:[1,0] neg_lo:[0,1]
	v_pk_add_f32 v[186:187], v[124:125], v[128:129]
	v_pk_add_f32 v[180:181], v[124:125], v[128:129] neg_lo:[0,1] neg_hi:[0,1]
	v_pk_add_f32 v[174:175], v[110:111], v[130:131]
	v_pk_add_f32 v[166:167], v[110:111], v[130:131] neg_lo:[0,1] neg_hi:[0,1]
	v_pk_add_f32 v[124:125], v[186:187], v[174:175]
	v_pk_add_f32 v[110:111], v[180:181], v[166:167] op_sel:[0,1] op_sel_hi:[1,0] neg_lo:[0,1]
	s_load_dword s35, s[50:51], 0x1000
	s_mul_i32 s43, s80, 0x8800
	s_add_u32 s46, s40, s43
	s_addc_u32 s47, s41, 0
	s_waitcnt lgkmcnt(0)
; __device__ __forceinline__ void hyena_fft(LAS unsigned char* lds, int layer, int G, const int wave_s) {
;     ...
;             { const float fb1 = fbias[HY + c]; float* zo = ZT + (size_t)c * MT;
; #pragma unroll
;               for (int r = 0; r < 8; ++r) { const int t = n2 + 512 * r;
;                   zo[t] = ux[r][0] * (x[r].x + fb1 * uz[r][0]); zo[SEQ + t] = ux[r][1] * (x[r].y + fb1 * uz[r][1]); } }
;         }
	v_mov_b32_e32 v194, s35
	v_pk_fma_f32 v[168:169], v[132:133], v[194:195], v[100:101] op_sel_hi:[1,0,1]
	v_pk_mul_f32 v[168:169], v[148:149], v[168:169]
	s_add_u32 s60, s46, 0
	s_addc_u32 s61, s47, 0
	s_add_u32 s62, s60, 0x4000
	s_addc_u32 s63, s61, 0
	global_store_dword v212, v168, s[60:61]
	global_store_dword v212, v169, s[62:63]
	v_pk_fma_f32 v[176:177], v[134:135], v[194:195], v[108:109] op_sel_hi:[1,0,1]
	v_pk_mul_f32 v[176:177], v[150:151], v[176:177]
	global_store_dword v212, v176, s[60:61] offset:2048
	global_store_dword v212, v177, s[62:63] offset:2048
	v_pk_fma_f32 v[178:179], v[136:137], v[194:195], v[116:117] op_sel_hi:[1,0,1]
	v_pk_mul_f32 v[178:179], v[152:153], v[178:179]
	s_add_u32 s60, s46, 0x1000
	s_addc_u32 s61, s47, 0
	s_add_u32 s62, s60, 0x4000
	s_addc_u32 s63, s61, 0
	global_store_dword v212, v178, s[60:61]
	global_store_dword v212, v179, s[62:63]
	v_pk_fma_f32 v[188:189], v[138:139], v[194:195], v[124:125] op_sel_hi:[1,0,1]
	v_pk_mul_f32 v[188:189], v[154:155], v[188:189]
	global_store_dword v212, v188, s[60:61] offset:2048
	global_store_dword v212, v189, s[62:63] offset:2048
	v_pk_fma_f32 v[184:185], v[140:141], v[194:195], v[126:127] op_sel_hi:[1,0,1]
	v_pk_mul_f32 v[184:185], v[158:159], v[184:185]
	s_add_u32 s60, s46, 0x2000
	s_addc_u32 s61, s47, 0
	s_add_u32 s62, s60, 0x4000
	s_addc_u32 s63, s61, 0
	global_store_dword v212, v184, s[60:61]
	global_store_dword v212, v185, s[62:63]
	v_pk_fma_f32 v[102:103], v[142:143], v[194:195], v[118:119] op_sel_hi:[1,0,1]
	v_pk_mul_f32 v[102:103], v[160:161], v[102:103]
	global_store_dword v212, v102, s[60:61] offset:2048
	global_store_dword v212, v103, s[62:63] offset:2048
	v_pk_fma_f32 v[186:187], v[144:145], v[194:195], v[182:183] op_sel_hi:[1,0,1]
	v_pk_mul_f32 v[186:187], v[162:163], v[186:187]
	s_add_u32 s60, s46, 0x3000
	s_addc_u32 s61, s47, 0
	s_add_u32 s62, s60, 0x4000
	s_addc_u32 s63, s61, 0
	global_store_dword v212, v186, s[60:61]
	global_store_dword v212, v187, s[62:63]
	v_pk_fma_f32 v[180:181], v[146:147], v[194:195], v[110:111] op_sel_hi:[1,0,1]
	v_pk_mul_f32 v[180:181], v[164:165], v[180:181]
	global_store_dword v212, v180, s[60:61] offset:2048
	global_store_dword v212, v181, s[62:63] offset:2048
	s_add_u32 s80, s80, 1
	s_cmp_lt_i32 s80, s93
	s_cbranch_scc1 .Lhfft_loop
	s_waitcnt vmcnt(0) lgkmcnt(0)
